# v26 + redundant s_waitcnt lgkmcnt(0) after the pre-MMA barrier removed (already waited before the barrier) in all 8 K-loops
# speedup vs baseline: 1.0055x; 1.0055x over previous
; #define PG8_STAGE(bufoff, gbase, voff) do { _Pragma("unroll") for (int _i = 0; _i < 2; ++_i) \
;         __builtin_amdgcn_global_load_lds((const unsigned*)((const char*)(gbase) + (voff)[_i]), (PG8_LAS unsigned*)(lds + (bufoff) + ldsw + _i * 8192), 16, 0, 0); } while (0)
; #define PG8_LDA(dst, b, h) do { _Pragma("unroll") for (int m = 0; m < 4; ++m) _Pragma("unroll") for (int k = 0; k < 2; ++k) dst[m][k] = *(const PG8_LAS bf16x8*)(lds + PG8_SA(b, h) + aoff + m * 2048 + k * 1024); } while (0)
; #define PG8_LDB(dst, b, h) do { _Pragma("unroll") for (int n = 0; n < 2; ++n) _Pragma("unroll") for (int k = 0; k < 2; ++k) dst[n][k] = *(const PG8_LAS bf16x8*)(lds + PG8_SB(b, h) + boff + n * 2048 + k * 1024); } while (0)
; #define PG8_MMA(ai, bj, At, Bt) do { __builtin_amdgcn_s_setprio(1); _Pragma("unroll") for (int m = 0; m < 4; ++m) _Pragma("unroll") for (int n = 0; n < 2; ++n) _Pragma("unroll") for (int k = 0; k < 2; ++k) \
;         acc[ai][bj][m][n] = __builtin_amdgcn_mfma_f32_16x16x32_bf16(Bt[n][k], At[m][k], acc[ai][bj][m][n], 0, 0, 0); __builtin_amdgcn_s_setprio(0); } while (0)
; #define PG8_WAIT_V(n) asm volatile("s_waitcnt vmcnt(" #n ")" ::: "memory")
; #define PG8_WAIT_L(n) asm volatile("s_waitcnt lgkmcnt(" #n ")" ::: "memory")
; template <class Epi, class Sched, bool ALIGN_EPI = false, bool SP2 = false>
; __device__ __forceinline__ void gemm_phase(PG8_LAS unsigned char* lds, const Gemm g, const Sched& S, const Epi& E, const int wave0) {
;     ...
;             const bool last = (t == nt - 2);
;             const char* a1 = cA + (size_t)(t + 1) * kstep;
;             const char* a2 = last ? nA : cA + (size_t)(t + 2) * kstep; const char* b2 = last ? nB : cB + (size_t)(t + 2) * kstep;
;             const char* a3 = a2 + kstep; const char* b3 = b2 + kstep;
;             if (last && has_next) S.a_ready(nxt);
;             if constexpr (SP2) {
;             PG8_LDB(B0, 0, 0); PG8_LDB(B1, 0, 1); PG8_SCHED; PG8_LDA(At, 0, 0); PG8_STAGE(PG8_SA(1, 1), a1 + hstepA, voffA);
;             PG8_WAIT_V(8); PG8_WAIT_L(0); PG8_BAR; PG8_MMA(0, 0, At, B0); PG8_MMA(0, 1, At, B1); PG8_BAR; PG8_SCHED;
;             PG8_LDA(At, 0, 1); PG8_STAGE(PG8_SB(0, 0), b2, voffB); PG8_STAGE(PG8_SB(0, 1), b2 + hstepB, voffB); PG8_STAGE(PG8_SA(0, 0), a2, voffA);
;             PG8_WAIT_V(8); PG8_WAIT_L(0); PG8_BAR; PG8_MMA(1, 0, At, B0); PG8_MMA(1, 1, At, B1); PG8_BAR; PG8_SCHED;
.LBB0_316:
	s_add_u32 s16, s0, 0xfff80080
	s_addc_u32 s17, s1, -1
	s_add_i32 s38, 0, 0x10000
	s_cmp_eq_u32 s37, 28
	s_cselect_b32 s19, s11, s17
	s_cselect_b32 s18, s33, s16
	s_cselect_b32 s17, s9, s36
	s_cselect_b32 s16, s34, s35
	s_add_i32 s40, 0, 0x14000
	ds_read_b128 v[144:147], v252
	ds_read_b128 v[148:151], v252 offset:1024
	ds_read_b128 v[152:155], v252 offset:2048
	ds_read_b128 v[156:159], v252 offset:3072
	ds_read_b128 v[178:181], v253
	ds_read_b128 v[182:185], v253 offset:1024
	ds_read_b128 v[186:189], v253 offset:2048
	ds_read_b128 v[190:193], v253 offset:3072
	s_add_i32 m0, s23, 0xc000
	ds_read_b128 v[194:197], v143
	ds_read_b128 v[208:211], v143 offset:1024
	ds_read_b128 v[212:215], v143 offset:2048
	ds_read_b128 v[216:219], v143 offset:3072
	ds_read_b128 v[220:223], v143 offset:4096
	ds_read_b128 v[224:227], v143 offset:5120
	ds_read_b128 v[228:231], v143 offset:6144
	ds_read_b128 v[232:235], v143 offset:7168
	global_load_lds_dwordx4 v136, s[0:1]
	s_add_i32 m0, s23, 0xe000
	s_nop 0
	global_load_lds_dwordx4 v138, s[0:1]
	s_waitcnt vmcnt(8)
	s_waitcnt lgkmcnt(0)
	s_barrier
	s_setprio 1
	v_mfma_f32_16x16x32_bf16 v[126:129], v[144:147], v[194:197], v[126:129]
	v_mfma_f32_16x16x32_bf16 v[122:125], v[152:155], v[194:197], v[122:125]
	v_mfma_f32_16x16x32_bf16 v[118:121], v[144:147], v[212:215], v[118:121]
	v_mfma_f32_16x16x32_bf16 v[114:117], v[152:155], v[212:215], v[114:117]
	v_mfma_f32_16x16x32_bf16 v[102:105], v[144:147], v[220:223], v[102:105]
	v_mfma_f32_16x16x32_bf16 v[98:101], v[152:155], v[220:223], v[98:101]
	v_mfma_f32_16x16x32_bf16 v[86:89], v[144:147], v[228:231], v[86:89]
	v_mfma_f32_16x16x32_bf16 v[82:85], v[152:155], v[228:231], v[82:85]
	s_setprio 0
	s_setprio 1
	v_mfma_f32_16x16x32_bf16 v[126:129], v[148:151], v[208:211], v[126:129]
	v_mfma_f32_16x16x32_bf16 v[122:125], v[156:159], v[208:211], v[122:125]
	v_mfma_f32_16x16x32_bf16 v[118:121], v[148:151], v[216:219], v[118:121]
	v_mfma_f32_16x16x32_bf16 v[114:117], v[156:159], v[216:219], v[114:117]
	v_mfma_f32_16x16x32_bf16 v[102:105], v[148:151], v[224:227], v[102:105]
	v_mfma_f32_16x16x32_bf16 v[98:101], v[156:159], v[224:227], v[98:101]
	v_mfma_f32_16x16x32_bf16 v[86:89], v[148:151], v[232:235], v[86:89]
	v_mfma_f32_16x16x32_bf16 v[82:85], v[156:159], v[232:235], v[82:85]
	s_setprio 0
	s_setprio 1
	v_mfma_f32_16x16x32_bf16 v[110:113], v[178:181], v[194:197], v[110:113]
	v_mfma_f32_16x16x32_bf16 v[106:109], v[186:189], v[194:197], v[106:109]
	v_mfma_f32_16x16x32_bf16 v[94:97], v[178:181], v[212:215], v[94:97]
	v_mfma_f32_16x16x32_bf16 v[90:93], v[186:189], v[212:215], v[90:93]
	v_mfma_f32_16x16x32_bf16 v[78:81], v[178:181], v[220:223], v[78:81]
	v_mfma_f32_16x16x32_bf16 v[74:77], v[186:189], v[220:223], v[74:77]
	v_mfma_f32_16x16x32_bf16 v[70:73], v[178:181], v[228:231], v[70:73]
	v_mfma_f32_16x16x32_bf16 v[66:69], v[186:189], v[228:231], v[66:69]
	s_setprio 0
	s_setprio 1
	v_mfma_f32_16x16x32_bf16 v[110:113], v[182:185], v[208:211], v[110:113]
	v_mfma_f32_16x16x32_bf16 v[106:109], v[190:193], v[208:211], v[106:109]
	v_mfma_f32_16x16x32_bf16 v[94:97], v[182:185], v[216:219], v[94:97]
	v_mfma_f32_16x16x32_bf16 v[90:93], v[190:193], v[216:219], v[90:93]
	v_mfma_f32_16x16x32_bf16 v[78:81], v[182:185], v[224:227], v[78:81]
	v_mfma_f32_16x16x32_bf16 v[74:77], v[190:193], v[224:227], v[74:77]
	v_mfma_f32_16x16x32_bf16 v[70:73], v[182:185], v[232:235], v[70:73]
	v_mfma_f32_16x16x32_bf16 v[66:69], v[190:193], v[232:235], v[66:69]
	s_setprio 0
	s_barrier
	s_add_i32 s38, s38, s22
	s_mov_b32 m0, s38
	ds_read_b128 v[194:197], v143 offset:16384
	ds_read_b128 v[208:211], v143 offset:17408
	ds_read_b128 v[212:215], v143 offset:18432
	ds_read_b128 v[216:219], v143 offset:19456
	ds_read_b128 v[220:223], v143 offset:20480
	ds_read_b128 v[224:227], v143 offset:21504
	ds_read_b128 v[228:231], v143 offset:22528
	ds_read_b128 v[232:235], v143 offset:23552
	global_load_lds_dwordx4 v64, s[16:17]
	s_add_i32 m0, s38, 0x2000
	s_add_u32 s38, s16, 0x80000
	s_addc_u32 s39, s17, 0
	s_add_i32 s40, s40, s22
	global_load_lds_dwordx4 v130, s[16:17]
	s_mov_b32 m0, s40
	s_mov_b64 s[100:101], s[18:19]
	global_load_lds_dwordx4 v64, s[38:39]
	s_add_i32 m0, s40, 0x2000
	s_nop 0
	global_load_lds_dwordx4 v130, s[38:39]
	s_mov_b32 m0, s23
	s_nop 0
	global_load_lds_dwordx4 v134, s[18:19]
	s_mov_b32 m0, s24
	s_nop 0
	global_load_lds_dwordx4 v132, s[18:19]
	s_waitcnt vmcnt(8)
	s_waitcnt lgkmcnt(0)
	s_barrier
	s_setprio 1
	v_mfma_f32_16x16x32_bf16 v[60:63], v[144:147], v[194:197], v[60:63]
	v_mfma_f32_16x16x32_bf16 v[56:59], v[152:155], v[194:197], v[56:59]
	v_mfma_f32_16x16x32_bf16 v[52:55], v[144:147], v[212:215], v[52:55]
	v_mfma_f32_16x16x32_bf16 v[48:51], v[152:155], v[212:215], v[48:51]
	v_mfma_f32_16x16x32_bf16 v[36:39], v[144:147], v[220:223], v[36:39]
	v_mfma_f32_16x16x32_bf16 v[32:35], v[152:155], v[220:223], v[32:35]
	v_mfma_f32_16x16x32_bf16 v[20:23], v[144:147], v[228:231], v[20:23]
	v_mfma_f32_16x16x32_bf16 v[16:19], v[152:155], v[228:231], v[16:19]
	s_setprio 0
	s_setprio 1
	v_mfma_f32_16x16x32_bf16 v[60:63], v[148:151], v[208:211], v[60:63]
	v_mfma_f32_16x16x32_bf16 v[56:59], v[156:159], v[208:211], v[56:59]
	v_mfma_f32_16x16x32_bf16 v[52:55], v[148:151], v[216:219], v[52:55]
	v_mfma_f32_16x16x32_bf16 v[48:51], v[156:159], v[216:219], v[48:51]
	v_mfma_f32_16x16x32_bf16 v[36:39], v[148:151], v[224:227], v[36:39]
	v_mfma_f32_16x16x32_bf16 v[32:35], v[156:159], v[224:227], v[32:35]
	v_mfma_f32_16x16x32_bf16 v[20:23], v[148:151], v[232:235], v[20:23]
	v_mfma_f32_16x16x32_bf16 v[16:19], v[156:159], v[232:235], v[16:19]
	s_setprio 0
	s_setprio 1
	v_mfma_f32_16x16x32_bf16 v[44:47], v[178:181], v[194:197], v[44:47]
	v_mfma_f32_16x16x32_bf16 v[40:43], v[186:189], v[194:197], v[40:43]
	v_mfma_f32_16x16x32_bf16 v[28:31], v[178:181], v[212:215], v[28:31]
	v_mfma_f32_16x16x32_bf16 v[24:27], v[186:189], v[212:215], v[24:27]
	v_mfma_f32_16x16x32_bf16 v[12:15], v[178:181], v[220:223], v[12:15]
	v_mfma_f32_16x16x32_bf16 v[8:11], v[186:189], v[220:223], v[8:11]
	v_mfma_f32_16x16x32_bf16 v[4:7], v[178:181], v[228:231], v[4:7]
	v_mfma_f32_16x16x32_bf16 v[0:3], v[186:189], v[228:231], v[0:3]
	s_setprio 0
	s_setprio 1
	v_mfma_f32_16x16x32_bf16 v[44:47], v[182:185], v[208:211], v[44:47]
	v_mfma_f32_16x16x32_bf16 v[40:43], v[190:193], v[208:211], v[40:43]
	v_mfma_f32_16x16x32_bf16 v[28:31], v[182:185], v[216:219], v[28:31]
	v_mfma_f32_16x16x32_bf16 v[24:27], v[190:193], v[216:219], v[24:27]
	v_mfma_f32_16x16x32_bf16 v[12:15], v[182:185], v[224:227], v[12:15]
	v_mfma_f32_16x16x32_bf16 v[8:11], v[190:193], v[224:227], v[8:11]
	v_mfma_f32_16x16x32_bf16 v[4:7], v[182:185], v[232:235], v[4:7]
	v_mfma_f32_16x16x32_bf16 v[0:3], v[190:193], v[232:235], v[0:3]
	s_setprio 0
	s_barrier
; #define PG8_STAGE(bufoff, gbase, voff) do { _Pragma("unroll") for (int _i = 0; _i < 2; ++_i) \
;         __builtin_amdgcn_global_load_lds((const unsigned*)((const char*)(gbase) + (voff)[_i]), (PG8_LAS unsigned*)(lds + (bufoff) + ldsw + _i * 8192), 16, 0, 0); } while (0)
; #define PG8_LDA(dst, b, h) do { _Pragma("unroll") for (int m = 0; m < 4; ++m) _Pragma("unroll") for (int k = 0; k < 2; ++k) dst[m][k] = *(const PG8_LAS bf16x8*)(lds + PG8_SA(b, h) + aoff + m * 2048 + k * 1024); } while (0)
; #define PG8_LDB(dst, b, h) do { _Pragma("unroll") for (int n = 0; n < 2; ++n) _Pragma("unroll") for (int k = 0; k < 2; ++k) dst[n][k] = *(const PG8_LAS bf16x8*)(lds + PG8_SB(b, h) + boff + n * 2048 + k * 1024); } while (0)
; #define PG8_MMA(ai, bj, At, Bt) do { __builtin_amdgcn_s_setprio(1); _Pragma("unroll") for (int m = 0; m < 4; ++m) _Pragma("unroll") for (int n = 0; n < 2; ++n) _Pragma("unroll") for (int k = 0; k < 2; ++k) \
;         acc[ai][bj][m][n] = __builtin_amdgcn_mfma_f32_16x16x32_bf16(Bt[n][k], At[m][k], acc[ai][bj][m][n], 0, 0, 0); __builtin_amdgcn_s_setprio(0); } while (0)
; #define PG8_WAIT_V(n) asm volatile("s_waitcnt vmcnt(" #n ")" ::: "memory")
; #define PG8_WAIT_L(n) asm volatile("s_waitcnt lgkmcnt(" #n ")" ::: "memory")
; #define PG8_BAR __builtin_amdgcn_s_barrier()
; #define PG8_SCHED __builtin_amdgcn_sched_barrier(0)
; template <class Epi, class Sched, bool ALIGN_EPI = false, bool SP2 = false>
; __device__ __forceinline__ void gemm_phase(PG8_LAS unsigned char* lds, const Gemm g, const Sched& S, const Epi& E, const int wave0) {
;     ...
;         for (int t = 0; t < nt; t += 2) {
;             const bool last = (t == nt - 2);
;             const char* a1 = cA + (size_t)(t + 1) * kstep;
;             const char* a2 = last ? nA : cA + (size_t)(t + 2) * kstep; const char* b2 = last ? nB : cB + (size_t)(t + 2) * kstep;
;     ...
;             PG8_LDB(B0, 1, 0); PG8_LDB(B1, 1, 1); PG8_SCHED; PG8_LDA(At, 1, 0); PG8_STAGE(PG8_SA(0, 1), a2 + hstepA, voffA);
;             PG8_WAIT_V(8); PG8_WAIT_L(0); PG8_BAR; PG8_MMA(0, 0, At, B0); PG8_MMA(0, 1, At, B1); PG8_BAR; PG8_SCHED;
;             PG8_LDA(At, 1, 1); PG8_STAGE(PG8_SB(1, 0), b3, voffB); PG8_STAGE(PG8_SB(1, 1), b3 + hstepB, voffB); PG8_STAGE(PG8_SA(1, 0), a3, voffA);
;             PG8_WAIT_V(8); PG8_WAIT_L(0); PG8_BAR; PG8_MMA(1, 0, At, B0); PG8_MMA(1, 1, At, B1); PG8_BAR; PG8_SCHED;
	s_add_i32 s38, 0, 0x18000
	s_add_i32 s39, 0, 0x1c000
	ds_read_b128 v[144:147], v254
	ds_read_b128 v[148:151], v254 offset:1024
	ds_read_b128 v[152:155], v254 offset:2048
	ds_read_b128 v[156:159], v254 offset:3072
	ds_read_b128 v[178:181], v255
	ds_read_b128 v[182:185], v255 offset:1024
	ds_read_b128 v[186:189], v255 offset:2048
	ds_read_b128 v[190:193], v255 offset:3072
	s_add_u32 s18, s18, 0x80000
	s_addc_u32 s19, s19, 0
	s_mov_b32 m0, s25
	ds_read_b128 v[194:197], v143 offset:32768
	ds_read_b128 v[208:211], v143 offset:33792
	ds_read_b128 v[212:215], v143 offset:34816
	ds_read_b128 v[216:219], v143 offset:35840
	ds_read_b128 v[220:223], v143 offset:36864
	ds_read_b128 v[224:227], v143 offset:37888
	ds_read_b128 v[228:231], v143 offset:38912
	ds_read_b128 v[232:235], v143 offset:39936
	global_load_lds_dwordx4 v134, s[18:19]
	s_mov_b32 m0, s26
	s_nop 0
	global_load_lds_dwordx4 v132, s[18:19]
	s_waitcnt vmcnt(8)
	s_waitcnt lgkmcnt(0)
	s_barrier
	s_setprio 1
	v_mfma_f32_16x16x32_bf16 v[126:129], v[144:147], v[194:197], v[126:129]
	v_mfma_f32_16x16x32_bf16 v[122:125], v[152:155], v[194:197], v[122:125]
	v_mfma_f32_16x16x32_bf16 v[118:121], v[144:147], v[212:215], v[118:121]
	v_mfma_f32_16x16x32_bf16 v[114:117], v[152:155], v[212:215], v[114:117]
	v_mfma_f32_16x16x32_bf16 v[102:105], v[144:147], v[220:223], v[102:105]
	v_mfma_f32_16x16x32_bf16 v[98:101], v[152:155], v[220:223], v[98:101]
	v_mfma_f32_16x16x32_bf16 v[86:89], v[144:147], v[228:231], v[86:89]
	v_mfma_f32_16x16x32_bf16 v[82:85], v[152:155], v[228:231], v[82:85]
	s_setprio 0
	s_setprio 1
	v_mfma_f32_16x16x32_bf16 v[126:129], v[148:151], v[208:211], v[126:129]
	v_mfma_f32_16x16x32_bf16 v[122:125], v[156:159], v[208:211], v[122:125]
	v_mfma_f32_16x16x32_bf16 v[118:121], v[148:151], v[216:219], v[118:121]
	v_mfma_f32_16x16x32_bf16 v[114:117], v[156:159], v[216:219], v[114:117]
	v_mfma_f32_16x16x32_bf16 v[102:105], v[148:151], v[224:227], v[102:105]
	v_mfma_f32_16x16x32_bf16 v[98:101], v[156:159], v[224:227], v[98:101]
	v_mfma_f32_16x16x32_bf16 v[86:89], v[148:151], v[232:235], v[86:89]
	v_mfma_f32_16x16x32_bf16 v[82:85], v[156:159], v[232:235], v[82:85]
	s_setprio 0
	s_setprio 1
	v_mfma_f32_16x16x32_bf16 v[110:113], v[178:181], v[194:197], v[110:113]
	v_mfma_f32_16x16x32_bf16 v[106:109], v[186:189], v[194:197], v[106:109]
	v_mfma_f32_16x16x32_bf16 v[94:97], v[178:181], v[212:215], v[94:97]
	v_mfma_f32_16x16x32_bf16 v[90:93], v[186:189], v[212:215], v[90:93]
	v_mfma_f32_16x16x32_bf16 v[78:81], v[178:181], v[220:223], v[78:81]
	v_mfma_f32_16x16x32_bf16 v[74:77], v[186:189], v[220:223], v[74:77]
	v_mfma_f32_16x16x32_bf16 v[70:73], v[178:181], v[228:231], v[70:73]
	v_mfma_f32_16x16x32_bf16 v[66:69], v[186:189], v[228:231], v[66:69]
	s_setprio 0
	s_setprio 1
	v_mfma_f32_16x16x32_bf16 v[110:113], v[182:185], v[208:211], v[110:113]
	v_mfma_f32_16x16x32_bf16 v[106:109], v[190:193], v[208:211], v[106:109]
	v_mfma_f32_16x16x32_bf16 v[94:97], v[182:185], v[216:219], v[94:97]
	v_mfma_f32_16x16x32_bf16 v[90:93], v[190:193], v[216:219], v[90:93]
	v_mfma_f32_16x16x32_bf16 v[78:81], v[182:185], v[224:227], v[78:81]
	v_mfma_f32_16x16x32_bf16 v[74:77], v[190:193], v[224:227], v[74:77]
	v_mfma_f32_16x16x32_bf16 v[70:73], v[182:185], v[232:235], v[70:73]
	v_mfma_f32_16x16x32_bf16 v[66:69], v[190:193], v[232:235], v[66:69]
	s_setprio 0
	s_barrier
	s_add_i32 s18, s38, s22
	s_add_u32 s42, s16, 0x80
	s_addc_u32 s43, s17, 0
	s_mov_b32 m0, s18
	ds_read_b128 v[194:197], v143 offset:49152
	ds_read_b128 v[208:211], v143 offset:50176
	ds_read_b128 v[212:215], v143 offset:51200
	ds_read_b128 v[216:219], v143 offset:52224
	ds_read_b128 v[220:223], v143 offset:53248
	ds_read_b128 v[224:227], v143 offset:54272
	ds_read_b128 v[228:231], v143 offset:55296
	ds_read_b128 v[232:235], v143 offset:56320
	global_load_lds_dwordx4 v64, s[42:43]
	s_add_i32 m0, s18, 0x2000
	s_add_u32 s16, s16, 0x80080
	s_addc_u32 s17, s17, 0
	s_add_i32 s18, s39, s22
	global_load_lds_dwordx4 v130, s[42:43]
	s_mov_b32 m0, s18
	s_nop 0
	global_load_lds_dwordx4 v64, s[16:17]
	s_add_i32 m0, s18, 0x2000
	s_nop 0
	global_load_lds_dwordx4 v130, s[16:17]
	s_add_u32 s100, s100, 0x80
	s_addc_u32 s101, s101, 0
	s_mov_b32 m0, s27
	s_nop 0
	global_load_lds_dwordx4 v134, s[100:101]
	s_mov_b32 m0, s28
	s_nop 0
	global_load_lds_dwordx4 v132, s[100:101]
	s_waitcnt vmcnt(8)
	s_waitcnt lgkmcnt(0)
	s_barrier
	s_setprio 1
	v_mfma_f32_16x16x32_bf16 v[60:63], v[144:147], v[194:197], v[60:63]
	v_mfma_f32_16x16x32_bf16 v[56:59], v[152:155], v[194:197], v[56:59]
	v_mfma_f32_16x16x32_bf16 v[52:55], v[144:147], v[212:215], v[52:55]
	v_mfma_f32_16x16x32_bf16 v[48:51], v[152:155], v[212:215], v[48:51]
	v_mfma_f32_16x16x32_bf16 v[36:39], v[144:147], v[220:223], v[36:39]
	v_mfma_f32_16x16x32_bf16 v[32:35], v[152:155], v[220:223], v[32:35]
	v_mfma_f32_16x16x32_bf16 v[20:23], v[144:147], v[228:231], v[20:23]
	v_mfma_f32_16x16x32_bf16 v[16:19], v[152:155], v[228:231], v[16:19]
	s_setprio 0
	s_setprio 1
	v_mfma_f32_16x16x32_bf16 v[60:63], v[148:151], v[208:211], v[60:63]
	v_mfma_f32_16x16x32_bf16 v[56:59], v[156:159], v[208:211], v[56:59]
	v_mfma_f32_16x16x32_bf16 v[52:55], v[148:151], v[216:219], v[52:55]
	v_mfma_f32_16x16x32_bf16 v[48:51], v[156:159], v[216:219], v[48:51]
	v_mfma_f32_16x16x32_bf16 v[36:39], v[148:151], v[224:227], v[36:39]
	v_mfma_f32_16x16x32_bf16 v[32:35], v[156:159], v[224:227], v[32:35]
	v_mfma_f32_16x16x32_bf16 v[20:23], v[148:151], v[232:235], v[20:23]
	v_mfma_f32_16x16x32_bf16 v[16:19], v[156:159], v[232:235], v[16:19]
	s_setprio 0
	s_setprio 1
	v_mfma_f32_16x16x32_bf16 v[44:47], v[178:181], v[194:197], v[44:47]
	v_mfma_f32_16x16x32_bf16 v[40:43], v[186:189], v[194:197], v[40:43]
	v_mfma_f32_16x16x32_bf16 v[28:31], v[178:181], v[212:215], v[28:31]
	v_mfma_f32_16x16x32_bf16 v[24:27], v[186:189], v[212:215], v[24:27]
	v_mfma_f32_16x16x32_bf16 v[12:15], v[178:181], v[220:223], v[12:15]
	v_mfma_f32_16x16x32_bf16 v[8:11], v[186:189], v[220:223], v[8:11]
	v_mfma_f32_16x16x32_bf16 v[4:7], v[178:181], v[228:231], v[4:7]
	v_mfma_f32_16x16x32_bf16 v[0:3], v[186:189], v[228:231], v[0:3]
	s_setprio 0
	s_setprio 1
	v_mfma_f32_16x16x32_bf16 v[44:47], v[182:185], v[208:211], v[44:47]
	v_mfma_f32_16x16x32_bf16 v[40:43], v[190:193], v[208:211], v[40:43]
	v_mfma_f32_16x16x32_bf16 v[28:31], v[182:185], v[216:219], v[28:31]
	v_mfma_f32_16x16x32_bf16 v[24:27], v[190:193], v[216:219], v[24:27]
	v_mfma_f32_16x16x32_bf16 v[12:15], v[182:185], v[224:227], v[12:15]
	v_mfma_f32_16x16x32_bf16 v[8:11], v[190:193], v[224:227], v[8:11]
	v_mfma_f32_16x16x32_bf16 v[4:7], v[182:185], v[232:235], v[4:7]
	v_mfma_f32_16x16x32_bf16 v[0:3], v[190:193], v[232:235], v[0:3]
	s_setprio 0
	s_barrier
	s_add_i32 s37, s37, 2
	s_add_u32 s0, s0, 0x100
	s_addc_u32 s1, s1, 0
	s_add_u32 s35, s35, 0x100
	s_addc_u32 s36, s36, 0
	s_cmp_gt_u32 s37, 29
	s_cbranch_scc0 .LBB0_316
	s_mov_b64 s[42:43], 0x80
	s_and_b64 vcc, exec, s[6:7]
	s_mov_b64 s[34:35], 0x45000
	s_cbranch_vccz .LBB0_319
	s_barrier

; #define PG8_STAGE(bufoff, gbase, voff) do { _Pragma("unroll") for (int _i = 0; _i < 2; ++_i) \
;         __builtin_amdgcn_global_load_lds((const unsigned*)((const char*)(gbase) + (voff)[_i]), (PG8_LAS unsigned*)(lds + (bufoff) + ldsw + _i * 8192), 16, 0, 0); } while (0)
; #define PG8_LDA(dst, b, h) do { _Pragma("unroll") for (int m = 0; m < 4; ++m) _Pragma("unroll") for (int k = 0; k < 2; ++k) dst[m][k] = *(const PG8_LAS bf16x8*)(lds + PG8_SA(b, h) + aoff + m * 2048 + k * 1024); } while (0)
; #define PG8_LDB(dst, b, h) do { _Pragma("unroll") for (int n = 0; n < 2; ++n) _Pragma("unroll") for (int k = 0; k < 2; ++k) dst[n][k] = *(const PG8_LAS bf16x8*)(lds + PG8_SB(b, h) + boff + n * 2048 + k * 1024); } while (0)
; #define PG8_MMA(ai, bj, At, Bt) do { __builtin_amdgcn_s_setprio(1); _Pragma("unroll") for (int m = 0; m < 4; ++m) _Pragma("unroll") for (int n = 0; n < 2; ++n) _Pragma("unroll") for (int k = 0; k < 2; ++k) \
;         acc[ai][bj][m][n] = __builtin_amdgcn_mfma_f32_16x16x32_bf16(Bt[n][k], At[m][k], acc[ai][bj][m][n], 0, 0, 0); __builtin_amdgcn_s_setprio(0); } while (0)
; #define PG8_WAIT_V(n) asm volatile("s_waitcnt vmcnt(" #n ")" ::: "memory")
; #define PG8_WAIT_L(n) asm volatile("s_waitcnt lgkmcnt(" #n ")" ::: "memory")
; template <class Epi, class Sched, bool ALIGN_EPI = false, bool SP2 = false>
; __device__ __forceinline__ void gemm_phase(PG8_LAS unsigned char* lds, const Gemm g, const Sched& S, const Epi& E, const int wave0) {
;     ...
;             const bool last = (t == nt - 2);
;             const char* a1 = cA + (size_t)(t + 1) * kstep;
;             const char* a2 = last ? nA : cA + (size_t)(t + 2) * kstep; const char* b2 = last ? nB : cB + (size_t)(t + 2) * kstep;
;             const char* a3 = a2 + kstep; const char* b3 = b2 + kstep;
;             if (last && has_next) S.a_ready(nxt);
;             if constexpr (SP2) {
;             PG8_LDB(B0, 0, 0); PG8_LDB(B1, 0, 1); PG8_SCHED; PG8_LDA(At, 0, 0); PG8_STAGE(PG8_SA(1, 1), a1 + hstepA, voffA);
;             PG8_WAIT_V(8); PG8_WAIT_L(0); PG8_BAR; PG8_MMA(0, 0, At, B0); PG8_MMA(0, 1, At, B1); PG8_BAR; PG8_SCHED;
;             PG8_LDA(At, 0, 1); PG8_STAGE(PG8_SB(0, 0), b2, voffB); PG8_STAGE(PG8_SB(0, 1), b2 + hstepB, voffB); PG8_STAGE(PG8_SA(0, 0), a2, voffA);
;             PG8_WAIT_V(8); PG8_WAIT_L(0); PG8_BAR; PG8_MMA(1, 0, At, B0); PG8_MMA(1, 1, At, B1); PG8_BAR; PG8_SCHED;
.LBB0_1178:
	s_add_u32 s2, s0, 0xfffc0080
	s_addc_u32 s3, s1, -1
	s_add_i32 s31, 0, 0x10000
	s_cmp_eq_u32 s19, 12
	s_cselect_b32 s17, s45, s3
	s_cselect_b32 s16, s44, s2
	s_cselect_b32 s3, s9, s18
	s_cselect_b32 s2, s11, s13
	s_add_i32 s33, 0, 0x14000
	ds_read_b128 v[130:133], v252
	ds_read_b128 v[134:137], v252 offset:1024
	ds_read_b128 v[148:151], v252 offset:2048
	ds_read_b128 v[152:155], v252 offset:3072
	ds_read_b128 v[178:181], v253
	ds_read_b128 v[182:185], v253 offset:1024
	ds_read_b128 v[186:189], v253 offset:2048
	ds_read_b128 v[190:193], v253 offset:3072
	s_add_i32 m0, s23, 0xc000
	ds_read_b128 v[194:197], v159
	ds_read_b128 v[208:211], v159 offset:1024
	ds_read_b128 v[212:215], v159 offset:2048
	ds_read_b128 v[216:219], v159 offset:3072
	ds_read_b128 v[220:223], v159 offset:4096
	ds_read_b128 v[224:227], v159 offset:5120
	ds_read_b128 v[228:231], v159 offset:6144
	ds_read_b128 v[232:235], v159 offset:7168
	global_load_lds_dwordx4 v144, s[0:1]
	s_add_i32 m0, s23, 0xe000
	s_nop 0
	global_load_lds_dwordx4 v146, s[0:1]
	s_waitcnt vmcnt(8)
	s_waitcnt lgkmcnt(0)
	s_barrier
	s_setprio 1
	v_mfma_f32_16x16x32_bf16 v[126:129], v[130:133], v[194:197], v[126:129]
	v_mfma_f32_16x16x32_bf16 v[122:125], v[148:151], v[194:197], v[122:125]
	v_mfma_f32_16x16x32_bf16 v[110:113], v[130:133], v[212:215], v[110:113]
	v_mfma_f32_16x16x32_bf16 v[106:109], v[148:151], v[212:215], v[106:109]
	v_mfma_f32_16x16x32_bf16 v[94:97], v[130:133], v[220:223], v[94:97]
	v_mfma_f32_16x16x32_bf16 v[90:93], v[148:151], v[220:223], v[90:93]
	v_mfma_f32_16x16x32_bf16 v[78:81], v[130:133], v[228:231], v[78:81]
	v_mfma_f32_16x16x32_bf16 v[74:77], v[148:151], v[228:231], v[74:77]
	s_setprio 0
	s_setprio 1
	v_mfma_f32_16x16x32_bf16 v[126:129], v[134:137], v[208:211], v[126:129]
	v_mfma_f32_16x16x32_bf16 v[122:125], v[152:155], v[208:211], v[122:125]
	v_mfma_f32_16x16x32_bf16 v[110:113], v[134:137], v[216:219], v[110:113]
	v_mfma_f32_16x16x32_bf16 v[106:109], v[152:155], v[216:219], v[106:109]
	v_mfma_f32_16x16x32_bf16 v[94:97], v[134:137], v[224:227], v[94:97]
	v_mfma_f32_16x16x32_bf16 v[90:93], v[152:155], v[224:227], v[90:93]
	v_mfma_f32_16x16x32_bf16 v[78:81], v[134:137], v[232:235], v[78:81]
	v_mfma_f32_16x16x32_bf16 v[74:77], v[152:155], v[232:235], v[74:77]
	s_setprio 0
	s_setprio 1
	v_mfma_f32_16x16x32_bf16 v[118:121], v[178:181], v[194:197], v[118:121]
	v_mfma_f32_16x16x32_bf16 v[114:117], v[186:189], v[194:197], v[114:117]
	v_mfma_f32_16x16x32_bf16 v[102:105], v[178:181], v[212:215], v[102:105]
	v_mfma_f32_16x16x32_bf16 v[98:101], v[186:189], v[212:215], v[98:101]
	v_mfma_f32_16x16x32_bf16 v[86:89], v[178:181], v[220:223], v[86:89]
	v_mfma_f32_16x16x32_bf16 v[82:85], v[186:189], v[220:223], v[82:85]
	v_mfma_f32_16x16x32_bf16 v[70:73], v[178:181], v[228:231], v[70:73]
	v_mfma_f32_16x16x32_bf16 v[66:69], v[186:189], v[228:231], v[66:69]
	s_setprio 0
	s_setprio 1
	v_mfma_f32_16x16x32_bf16 v[118:121], v[182:185], v[208:211], v[118:121]
	v_mfma_f32_16x16x32_bf16 v[114:117], v[190:193], v[208:211], v[114:117]
	v_mfma_f32_16x16x32_bf16 v[102:105], v[182:185], v[216:219], v[102:105]
	v_mfma_f32_16x16x32_bf16 v[98:101], v[190:193], v[216:219], v[98:101]
	v_mfma_f32_16x16x32_bf16 v[86:89], v[182:185], v[224:227], v[86:89]
	v_mfma_f32_16x16x32_bf16 v[82:85], v[190:193], v[224:227], v[82:85]
	v_mfma_f32_16x16x32_bf16 v[70:73], v[182:185], v[232:235], v[70:73]
	v_mfma_f32_16x16x32_bf16 v[66:69], v[190:193], v[232:235], v[66:69]
	s_setprio 0
	s_barrier
	s_add_i32 s31, s31, s22
	s_mov_b32 m0, s31
	ds_read_b128 v[194:197], v159 offset:16384
	ds_read_b128 v[208:211], v159 offset:17408
	ds_read_b128 v[212:215], v159 offset:18432
	ds_read_b128 v[216:219], v159 offset:19456
	ds_read_b128 v[220:223], v159 offset:20480
	ds_read_b128 v[224:227], v159 offset:21504
	ds_read_b128 v[228:231], v159 offset:22528
	ds_read_b128 v[232:235], v159 offset:23552
	global_load_lds_dwordx4 v64, s[2:3]
	s_add_i32 m0, s31, 0x2000
	s_add_u32 s34, s2, 0x40000
	s_addc_u32 s35, s3, 0
	s_add_i32 s31, s33, s22
	global_load_lds_dwordx4 v138, s[2:3]
	s_mov_b32 m0, s31
	s_mov_b64 s[100:101], s[16:17]
	global_load_lds_dwordx4 v64, s[34:35]
	s_add_i32 m0, s31, 0x2000
	s_nop 0
	global_load_lds_dwordx4 v138, s[34:35]
	s_mov_b32 m0, s23
	s_nop 0
	global_load_lds_dwordx4 v142, s[16:17]
	s_mov_b32 m0, s24
	s_nop 0
	global_load_lds_dwordx4 v140, s[16:17]
	s_waitcnt vmcnt(8)
	s_waitcnt lgkmcnt(0)
	s_barrier
	s_setprio 1
	v_mfma_f32_16x16x32_bf16 v[60:63], v[130:133], v[194:197], v[60:63]
	v_mfma_f32_16x16x32_bf16 v[56:59], v[148:151], v[194:197], v[56:59]
	v_mfma_f32_16x16x32_bf16 v[44:47], v[130:133], v[212:215], v[44:47]
	v_mfma_f32_16x16x32_bf16 v[40:43], v[148:151], v[212:215], v[40:43]
	v_mfma_f32_16x16x32_bf16 v[28:31], v[130:133], v[220:223], v[28:31]
	v_mfma_f32_16x16x32_bf16 v[24:27], v[148:151], v[220:223], v[24:27]
	v_mfma_f32_16x16x32_bf16 v[12:15], v[130:133], v[228:231], v[12:15]
	v_mfma_f32_16x16x32_bf16 v[8:11], v[148:151], v[228:231], v[8:11]
	s_setprio 0
	s_setprio 1
	v_mfma_f32_16x16x32_bf16 v[60:63], v[134:137], v[208:211], v[60:63]
	v_mfma_f32_16x16x32_bf16 v[56:59], v[152:155], v[208:211], v[56:59]
	v_mfma_f32_16x16x32_bf16 v[44:47], v[134:137], v[216:219], v[44:47]
	v_mfma_f32_16x16x32_bf16 v[40:43], v[152:155], v[216:219], v[40:43]
	v_mfma_f32_16x16x32_bf16 v[28:31], v[134:137], v[224:227], v[28:31]
	v_mfma_f32_16x16x32_bf16 v[24:27], v[152:155], v[224:227], v[24:27]
	v_mfma_f32_16x16x32_bf16 v[12:15], v[134:137], v[232:235], v[12:15]
	v_mfma_f32_16x16x32_bf16 v[8:11], v[152:155], v[232:235], v[8:11]
	s_setprio 0
	s_setprio 1
	v_mfma_f32_16x16x32_bf16 v[52:55], v[178:181], v[194:197], v[52:55]
	v_mfma_f32_16x16x32_bf16 v[48:51], v[186:189], v[194:197], v[48:51]
	v_mfma_f32_16x16x32_bf16 v[36:39], v[178:181], v[212:215], v[36:39]
	v_mfma_f32_16x16x32_bf16 v[32:35], v[186:189], v[212:215], v[32:35]
	v_mfma_f32_16x16x32_bf16 v[20:23], v[178:181], v[220:223], v[20:23]
	v_mfma_f32_16x16x32_bf16 v[16:19], v[186:189], v[220:223], v[16:19]
	v_mfma_f32_16x16x32_bf16 v[4:7], v[178:181], v[228:231], v[4:7]
	v_mfma_f32_16x16x32_bf16 v[0:3], v[186:189], v[228:231], v[0:3]
	s_setprio 0
	s_setprio 1
	v_mfma_f32_16x16x32_bf16 v[52:55], v[182:185], v[208:211], v[52:55]
	v_mfma_f32_16x16x32_bf16 v[48:51], v[190:193], v[208:211], v[48:51]
	v_mfma_f32_16x16x32_bf16 v[36:39], v[182:185], v[216:219], v[36:39]
	v_mfma_f32_16x16x32_bf16 v[32:35], v[190:193], v[216:219], v[32:35]
	v_mfma_f32_16x16x32_bf16 v[20:23], v[182:185], v[224:227], v[20:23]
	v_mfma_f32_16x16x32_bf16 v[16:19], v[190:193], v[224:227], v[16:19]
	v_mfma_f32_16x16x32_bf16 v[4:7], v[182:185], v[232:235], v[4:7]
	v_mfma_f32_16x16x32_bf16 v[0:3], v[190:193], v[232:235], v[0:3]
	s_setprio 0
	s_barrier
; #define PG8_STAGE(bufoff, gbase, voff) do { _Pragma("unroll") for (int _i = 0; _i < 2; ++_i) \
;         __builtin_amdgcn_global_load_lds((const unsigned*)((const char*)(gbase) + (voff)[_i]), (PG8_LAS unsigned*)(lds + (bufoff) + ldsw + _i * 8192), 16, 0, 0); } while (0)
; #define PG8_LDA(dst, b, h) do { _Pragma("unroll") for (int m = 0; m < 4; ++m) _Pragma("unroll") for (int k = 0; k < 2; ++k) dst[m][k] = *(const PG8_LAS bf16x8*)(lds + PG8_SA(b, h) + aoff + m * 2048 + k * 1024); } while (0)
; #define PG8_LDB(dst, b, h) do { _Pragma("unroll") for (int n = 0; n < 2; ++n) _Pragma("unroll") for (int k = 0; k < 2; ++k) dst[n][k] = *(const PG8_LAS bf16x8*)(lds + PG8_SB(b, h) + boff + n * 2048 + k * 1024); } while (0)
; #define PG8_MMA(ai, bj, At, Bt) do { __builtin_amdgcn_s_setprio(1); _Pragma("unroll") for (int m = 0; m < 4; ++m) _Pragma("unroll") for (int n = 0; n < 2; ++n) _Pragma("unroll") for (int k = 0; k < 2; ++k) \
;         acc[ai][bj][m][n] = __builtin_amdgcn_mfma_f32_16x16x32_bf16(Bt[n][k], At[m][k], acc[ai][bj][m][n], 0, 0, 0); __builtin_amdgcn_s_setprio(0); } while (0)
; #define PG8_WAIT_V(n) asm volatile("s_waitcnt vmcnt(" #n ")" ::: "memory")
; #define PG8_WAIT_L(n) asm volatile("s_waitcnt lgkmcnt(" #n ")" ::: "memory")
; #define PG8_BAR __builtin_amdgcn_s_barrier()
; #define PG8_SCHED __builtin_amdgcn_sched_barrier(0)
; template <class Epi, class Sched, bool ALIGN_EPI = false, bool SP2 = false>
; __device__ __forceinline__ void gemm_phase(PG8_LAS unsigned char* lds, const Gemm g, const Sched& S, const Epi& E, const int wave0) {
;     ...
;         for (int t = 0; t < nt; t += 2) {
;             const bool last = (t == nt - 2);
;             const char* a1 = cA + (size_t)(t + 1) * kstep;
;             const char* a2 = last ? nA : cA + (size_t)(t + 2) * kstep; const char* b2 = last ? nB : cB + (size_t)(t + 2) * kstep;
;     ...
;             PG8_LDB(B0, 1, 0); PG8_LDB(B1, 1, 1); PG8_SCHED; PG8_LDA(At, 1, 0); PG8_STAGE(PG8_SA(0, 1), a2 + hstepA, voffA);
;             PG8_WAIT_V(8); PG8_WAIT_L(0); PG8_BAR; PG8_MMA(0, 0, At, B0); PG8_MMA(0, 1, At, B1); PG8_BAR; PG8_SCHED;
;             PG8_LDA(At, 1, 1); PG8_STAGE(PG8_SB(1, 0), b3, voffB); PG8_STAGE(PG8_SB(1, 1), b3 + hstepB, voffB); PG8_STAGE(PG8_SA(1, 0), a3, voffA);
;             PG8_WAIT_V(8); PG8_WAIT_L(0); PG8_BAR; PG8_MMA(1, 0, At, B0); PG8_MMA(1, 1, At, B1); PG8_BAR; PG8_SCHED;
	s_add_i32 s31, 0, 0x18000
	s_add_i32 s33, 0, 0x1c000
	ds_read_b128 v[130:133], v254
	ds_read_b128 v[134:137], v254 offset:1024
	ds_read_b128 v[148:151], v254 offset:2048
	ds_read_b128 v[152:155], v254 offset:3072
	ds_read_b128 v[178:181], v255
	ds_read_b128 v[182:185], v255 offset:1024
	ds_read_b128 v[186:189], v255 offset:2048
	ds_read_b128 v[190:193], v255 offset:3072
	s_add_u32 s16, s16, 0x40000
	s_addc_u32 s17, s17, 0
	s_mov_b32 m0, s25
	ds_read_b128 v[194:197], v159 offset:32768
	ds_read_b128 v[208:211], v159 offset:33792
	ds_read_b128 v[212:215], v159 offset:34816
	ds_read_b128 v[216:219], v159 offset:35840
	ds_read_b128 v[220:223], v159 offset:36864
	ds_read_b128 v[224:227], v159 offset:37888
	ds_read_b128 v[228:231], v159 offset:38912
	ds_read_b128 v[232:235], v159 offset:39936
	global_load_lds_dwordx4 v142, s[16:17]
	s_mov_b32 m0, s26
	s_nop 0
	global_load_lds_dwordx4 v140, s[16:17]
	s_waitcnt vmcnt(8)
	s_waitcnt lgkmcnt(0)
	s_barrier
	s_setprio 1
	v_mfma_f32_16x16x32_bf16 v[126:129], v[130:133], v[194:197], v[126:129]
	v_mfma_f32_16x16x32_bf16 v[122:125], v[148:151], v[194:197], v[122:125]
	v_mfma_f32_16x16x32_bf16 v[110:113], v[130:133], v[212:215], v[110:113]
	v_mfma_f32_16x16x32_bf16 v[106:109], v[148:151], v[212:215], v[106:109]
	v_mfma_f32_16x16x32_bf16 v[94:97], v[130:133], v[220:223], v[94:97]
	v_mfma_f32_16x16x32_bf16 v[90:93], v[148:151], v[220:223], v[90:93]
	v_mfma_f32_16x16x32_bf16 v[78:81], v[130:133], v[228:231], v[78:81]
	v_mfma_f32_16x16x32_bf16 v[74:77], v[148:151], v[228:231], v[74:77]
	s_setprio 0
	s_setprio 1
	v_mfma_f32_16x16x32_bf16 v[126:129], v[134:137], v[208:211], v[126:129]
	v_mfma_f32_16x16x32_bf16 v[122:125], v[152:155], v[208:211], v[122:125]
	v_mfma_f32_16x16x32_bf16 v[110:113], v[134:137], v[216:219], v[110:113]
	v_mfma_f32_16x16x32_bf16 v[106:109], v[152:155], v[216:219], v[106:109]
	v_mfma_f32_16x16x32_bf16 v[94:97], v[134:137], v[224:227], v[94:97]
	v_mfma_f32_16x16x32_bf16 v[90:93], v[152:155], v[224:227], v[90:93]
	v_mfma_f32_16x16x32_bf16 v[78:81], v[134:137], v[232:235], v[78:81]
	v_mfma_f32_16x16x32_bf16 v[74:77], v[152:155], v[232:235], v[74:77]
	s_setprio 0
	s_setprio 1
	v_mfma_f32_16x16x32_bf16 v[118:121], v[178:181], v[194:197], v[118:121]
	v_mfma_f32_16x16x32_bf16 v[114:117], v[186:189], v[194:197], v[114:117]
	v_mfma_f32_16x16x32_bf16 v[102:105], v[178:181], v[212:215], v[102:105]
	v_mfma_f32_16x16x32_bf16 v[98:101], v[186:189], v[212:215], v[98:101]
	v_mfma_f32_16x16x32_bf16 v[86:89], v[178:181], v[220:223], v[86:89]
	v_mfma_f32_16x16x32_bf16 v[82:85], v[186:189], v[220:223], v[82:85]
	v_mfma_f32_16x16x32_bf16 v[70:73], v[178:181], v[228:231], v[70:73]
	v_mfma_f32_16x16x32_bf16 v[66:69], v[186:189], v[228:231], v[66:69]
	s_setprio 0
	s_setprio 1
	v_mfma_f32_16x16x32_bf16 v[118:121], v[182:185], v[208:211], v[118:121]
	v_mfma_f32_16x16x32_bf16 v[114:117], v[190:193], v[208:211], v[114:117]
	v_mfma_f32_16x16x32_bf16 v[102:105], v[182:185], v[216:219], v[102:105]
	v_mfma_f32_16x16x32_bf16 v[98:101], v[190:193], v[216:219], v[98:101]
	v_mfma_f32_16x16x32_bf16 v[86:89], v[182:185], v[224:227], v[86:89]
	v_mfma_f32_16x16x32_bf16 v[82:85], v[190:193], v[224:227], v[82:85]
	v_mfma_f32_16x16x32_bf16 v[70:73], v[182:185], v[232:235], v[70:73]
	v_mfma_f32_16x16x32_bf16 v[66:69], v[190:193], v[232:235], v[66:69]
	s_setprio 0
	s_barrier
	s_add_i32 s16, s31, s22
	s_add_u32 s36, s2, 0x80
	s_addc_u32 s37, s3, 0
	s_mov_b32 m0, s16
	ds_read_b128 v[194:197], v159 offset:49152
	ds_read_b128 v[208:211], v159 offset:50176
	ds_read_b128 v[212:215], v159 offset:51200
	ds_read_b128 v[216:219], v159 offset:52224
	ds_read_b128 v[220:223], v159 offset:53248
	ds_read_b128 v[224:227], v159 offset:54272
	ds_read_b128 v[228:231], v159 offset:55296
	ds_read_b128 v[232:235], v159 offset:56320
	global_load_lds_dwordx4 v64, s[36:37]
	s_add_i32 m0, s16, 0x2000
	s_add_u32 s2, s2, 0x40080
	s_addc_u32 s3, s3, 0
	s_add_i32 s16, s33, s22
	global_load_lds_dwordx4 v138, s[36:37]
	s_mov_b32 m0, s16
	s_nop 0
	global_load_lds_dwordx4 v64, s[2:3]
	s_add_i32 m0, s16, 0x2000
	s_nop 0
	global_load_lds_dwordx4 v138, s[2:3]
	s_add_u32 s100, s100, 0x80
	s_addc_u32 s101, s101, 0
	s_mov_b32 m0, s27
	s_nop 0
	global_load_lds_dwordx4 v142, s[100:101]
	s_mov_b32 m0, s28
	s_nop 0
	global_load_lds_dwordx4 v140, s[100:101]
	s_waitcnt vmcnt(8)
	s_waitcnt lgkmcnt(0)
	s_barrier
	s_setprio 1
	v_mfma_f32_16x16x32_bf16 v[60:63], v[130:133], v[194:197], v[60:63]
	v_mfma_f32_16x16x32_bf16 v[56:59], v[148:151], v[194:197], v[56:59]
	v_mfma_f32_16x16x32_bf16 v[44:47], v[130:133], v[212:215], v[44:47]
	v_mfma_f32_16x16x32_bf16 v[40:43], v[148:151], v[212:215], v[40:43]
	v_mfma_f32_16x16x32_bf16 v[28:31], v[130:133], v[220:223], v[28:31]
	v_mfma_f32_16x16x32_bf16 v[24:27], v[148:151], v[220:223], v[24:27]
	v_mfma_f32_16x16x32_bf16 v[12:15], v[130:133], v[228:231], v[12:15]
	v_mfma_f32_16x16x32_bf16 v[8:11], v[148:151], v[228:231], v[8:11]
	s_setprio 0
	s_setprio 1
	v_mfma_f32_16x16x32_bf16 v[60:63], v[134:137], v[208:211], v[60:63]
	v_mfma_f32_16x16x32_bf16 v[56:59], v[152:155], v[208:211], v[56:59]
	v_mfma_f32_16x16x32_bf16 v[44:47], v[134:137], v[216:219], v[44:47]
	v_mfma_f32_16x16x32_bf16 v[40:43], v[152:155], v[216:219], v[40:43]
	v_mfma_f32_16x16x32_bf16 v[28:31], v[134:137], v[224:227], v[28:31]
	v_mfma_f32_16x16x32_bf16 v[24:27], v[152:155], v[224:227], v[24:27]
	v_mfma_f32_16x16x32_bf16 v[12:15], v[134:137], v[232:235], v[12:15]
	v_mfma_f32_16x16x32_bf16 v[8:11], v[152:155], v[232:235], v[8:11]
	s_setprio 0
	s_setprio 1
	v_mfma_f32_16x16x32_bf16 v[52:55], v[178:181], v[194:197], v[52:55]
	v_mfma_f32_16x16x32_bf16 v[48:51], v[186:189], v[194:197], v[48:51]
	v_mfma_f32_16x16x32_bf16 v[36:39], v[178:181], v[212:215], v[36:39]
	v_mfma_f32_16x16x32_bf16 v[32:35], v[186:189], v[212:215], v[32:35]
	v_mfma_f32_16x16x32_bf16 v[20:23], v[178:181], v[220:223], v[20:23]
	v_mfma_f32_16x16x32_bf16 v[16:19], v[186:189], v[220:223], v[16:19]
	v_mfma_f32_16x16x32_bf16 v[4:7], v[178:181], v[228:231], v[4:7]
	v_mfma_f32_16x16x32_bf16 v[0:3], v[186:189], v[228:231], v[0:3]
	s_setprio 0
	s_setprio 1
	v_mfma_f32_16x16x32_bf16 v[52:55], v[182:185], v[208:211], v[52:55]
	v_mfma_f32_16x16x32_bf16 v[48:51], v[190:193], v[208:211], v[48:51]
	v_mfma_f32_16x16x32_bf16 v[36:39], v[182:185], v[216:219], v[36:39]
	v_mfma_f32_16x16x32_bf16 v[32:35], v[190:193], v[216:219], v[32:35]
	v_mfma_f32_16x16x32_bf16 v[20:23], v[182:185], v[224:227], v[20:23]
	v_mfma_f32_16x16x32_bf16 v[16:19], v[190:193], v[224:227], v[16:19]
	v_mfma_f32_16x16x32_bf16 v[4:7], v[182:185], v[232:235], v[4:7]
	v_mfma_f32_16x16x32_bf16 v[0:3], v[190:193], v[232:235], v[0:3]
	s_setprio 0
	s_barrier
	s_add_i32 s19, s19, 2
	s_add_u32 s0, s0, 0x100
	s_addc_u32 s1, s1, 0
	s_add_u32 s13, s13, 0x100
	s_addc_u32 s18, s18, 0
	s_cmp_gt_u32 s19, 13
	s_cbranch_scc0 .LBB0_1178
	s_mov_b64 s[36:37], 0x80
	s_and_b64 vcc, exec, s[6:7]
	s_cbranch_vccz .LBB0_1181
	s_barrier

; #define PG8_STAGE(bufoff, gbase, voff) do { _Pragma("unroll") for (int _i = 0; _i < 2; ++_i) \
;         __builtin_amdgcn_global_load_lds((const unsigned*)((const char*)(gbase) + (voff)[_i]), (PG8_LAS unsigned*)(lds + (bufoff) + ldsw + _i * 8192), 16, 0, 0); } while (0)
; #define PG8_LDA(dst, b, h) do { _Pragma("unroll") for (int m = 0; m < 4; ++m) _Pragma("unroll") for (int k = 0; k < 2; ++k) dst[m][k] = *(const PG8_LAS bf16x8*)(lds + PG8_SA(b, h) + aoff + m * 2048 + k * 1024); } while (0)
; #define PG8_LDB(dst, b, h) do { _Pragma("unroll") for (int n = 0; n < 2; ++n) _Pragma("unroll") for (int k = 0; k < 2; ++k) dst[n][k] = *(const PG8_LAS bf16x8*)(lds + PG8_SB(b, h) + boff + n * 2048 + k * 1024); } while (0)
; #define PG8_MMA(ai, bj, At, Bt) do { __builtin_amdgcn_s_setprio(1); _Pragma("unroll") for (int m = 0; m < 4; ++m) _Pragma("unroll") for (int n = 0; n < 2; ++n) _Pragma("unroll") for (int k = 0; k < 2; ++k) \
;         acc[ai][bj][m][n] = __builtin_amdgcn_mfma_f32_16x16x32_bf16(Bt[n][k], At[m][k], acc[ai][bj][m][n], 0, 0, 0); __builtin_amdgcn_s_setprio(0); } while (0)
; #define PG8_WAIT_V(n) asm volatile("s_waitcnt vmcnt(" #n ")" ::: "memory")
; #define PG8_WAIT_L(n) asm volatile("s_waitcnt lgkmcnt(" #n ")" ::: "memory")
; template <class Epi, class Sched, bool ALIGN_EPI = false, bool SP2 = false>
; __device__ __forceinline__ void gemm_phase(PG8_LAS unsigned char* lds, const Gemm g, const Sched& S, const Epi& E, const int wave0) {
;     ...
;             const bool last = (t == nt - 2);
;             const char* a1 = cA + (size_t)(t + 1) * kstep;
;             const char* a2 = last ? nA : cA + (size_t)(t + 2) * kstep; const char* b2 = last ? nB : cB + (size_t)(t + 2) * kstep;
;             const char* a3 = a2 + kstep; const char* b3 = b2 + kstep;
;             if (last && has_next) S.a_ready(nxt);
;             if constexpr (SP2) {
;             PG8_LDB(B0, 0, 0); PG8_LDB(B1, 0, 1); PG8_SCHED; PG8_LDA(At, 0, 0); PG8_STAGE(PG8_SA(1, 1), a1 + hstepA, voffA);
;             PG8_WAIT_V(8); PG8_WAIT_L(0); PG8_BAR; PG8_MMA(0, 0, At, B0); PG8_MMA(0, 1, At, B1); PG8_BAR; PG8_SCHED;
;             PG8_LDA(At, 0, 1); PG8_STAGE(PG8_SB(0, 0), b2, voffB); PG8_STAGE(PG8_SB(0, 1), b2 + hstepB, voffB); PG8_STAGE(PG8_SA(0, 0), a2, voffA);
;             PG8_WAIT_V(8); PG8_WAIT_L(0); PG8_BAR; PG8_MMA(1, 0, At, B0); PG8_MMA(1, 1, At, B1); PG8_BAR; PG8_SCHED;
.LBB0_1231:
	s_add_u32 s2, s0, 0xfffc0080
	s_addc_u32 s3, s1, -1
	s_add_i32 s31, 0, 0x10000
	s_cmp_eq_u32 s19, 12
	s_cselect_b32 s17, s43, s3
	s_cselect_b32 s16, s42, s2
	s_cselect_b32 s3, s9, s18
	s_cselect_b32 s2, s11, s13
	s_add_i32 s33, 0, 0x14000
	ds_read_b128 v[140:143], v252
	ds_read_b128 v[144:147], v252 offset:1024
	ds_read_b128 v[154:157], v252 offset:2048
	ds_read_b128 v[158:161], v252 offset:3072
	ds_read_b128 v[178:181], v253
	ds_read_b128 v[182:185], v253 offset:1024
	ds_read_b128 v[186:189], v253 offset:2048
	ds_read_b128 v[190:193], v253 offset:3072
	s_add_i32 m0, s23, 0xc000
	ds_read_b128 v[194:197], v153
	ds_read_b128 v[208:211], v153 offset:1024
	ds_read_b128 v[212:215], v153 offset:2048
	ds_read_b128 v[216:219], v153 offset:3072
	ds_read_b128 v[220:223], v153 offset:4096
	ds_read_b128 v[224:227], v153 offset:5120
	ds_read_b128 v[228:231], v153 offset:6144
	ds_read_b128 v[232:235], v153 offset:7168
	global_load_lds_dwordx4 v136, s[0:1]
	s_add_i32 m0, s23, 0xe000
	s_nop 0
	global_load_lds_dwordx4 v138, s[0:1]
	s_waitcnt vmcnt(8)
	s_waitcnt lgkmcnt(0)
	s_barrier
	s_setprio 1
	v_mfma_f32_16x16x32_bf16 v[126:129], v[140:143], v[194:197], v[126:129]
	v_mfma_f32_16x16x32_bf16 v[122:125], v[154:157], v[194:197], v[122:125]
	v_mfma_f32_16x16x32_bf16 v[110:113], v[140:143], v[212:215], v[110:113]
	v_mfma_f32_16x16x32_bf16 v[106:109], v[154:157], v[212:215], v[106:109]
	v_mfma_f32_16x16x32_bf16 v[94:97], v[140:143], v[220:223], v[94:97]
	v_mfma_f32_16x16x32_bf16 v[90:93], v[154:157], v[220:223], v[90:93]
	v_mfma_f32_16x16x32_bf16 v[78:81], v[140:143], v[228:231], v[78:81]
	v_mfma_f32_16x16x32_bf16 v[74:77], v[154:157], v[228:231], v[74:77]
	s_setprio 0
	s_setprio 1
	v_mfma_f32_16x16x32_bf16 v[126:129], v[144:147], v[208:211], v[126:129]
	v_mfma_f32_16x16x32_bf16 v[122:125], v[158:161], v[208:211], v[122:125]
	v_mfma_f32_16x16x32_bf16 v[110:113], v[144:147], v[216:219], v[110:113]
	v_mfma_f32_16x16x32_bf16 v[106:109], v[158:161], v[216:219], v[106:109]
	v_mfma_f32_16x16x32_bf16 v[94:97], v[144:147], v[224:227], v[94:97]
	v_mfma_f32_16x16x32_bf16 v[90:93], v[158:161], v[224:227], v[90:93]
	v_mfma_f32_16x16x32_bf16 v[78:81], v[144:147], v[232:235], v[78:81]
	v_mfma_f32_16x16x32_bf16 v[74:77], v[158:161], v[232:235], v[74:77]
	s_setprio 0
	s_setprio 1
	v_mfma_f32_16x16x32_bf16 v[118:121], v[178:181], v[194:197], v[118:121]
	v_mfma_f32_16x16x32_bf16 v[114:117], v[186:189], v[194:197], v[114:117]
	v_mfma_f32_16x16x32_bf16 v[102:105], v[178:181], v[212:215], v[102:105]
	v_mfma_f32_16x16x32_bf16 v[98:101], v[186:189], v[212:215], v[98:101]
	v_mfma_f32_16x16x32_bf16 v[86:89], v[178:181], v[220:223], v[86:89]
	v_mfma_f32_16x16x32_bf16 v[82:85], v[186:189], v[220:223], v[82:85]
	v_mfma_f32_16x16x32_bf16 v[70:73], v[178:181], v[228:231], v[70:73]
	v_mfma_f32_16x16x32_bf16 v[66:69], v[186:189], v[228:231], v[66:69]
	s_setprio 0
	s_setprio 1
	v_mfma_f32_16x16x32_bf16 v[118:121], v[182:185], v[208:211], v[118:121]
	v_mfma_f32_16x16x32_bf16 v[114:117], v[190:193], v[208:211], v[114:117]
	v_mfma_f32_16x16x32_bf16 v[102:105], v[182:185], v[216:219], v[102:105]
	v_mfma_f32_16x16x32_bf16 v[98:101], v[190:193], v[216:219], v[98:101]
	v_mfma_f32_16x16x32_bf16 v[86:89], v[182:185], v[224:227], v[86:89]
	v_mfma_f32_16x16x32_bf16 v[82:85], v[190:193], v[224:227], v[82:85]
	v_mfma_f32_16x16x32_bf16 v[70:73], v[182:185], v[232:235], v[70:73]
	v_mfma_f32_16x16x32_bf16 v[66:69], v[190:193], v[232:235], v[66:69]
	s_setprio 0
	s_barrier
	s_add_i32 s31, s31, s22
	s_mov_b32 m0, s31
	ds_read_b128 v[194:197], v153 offset:16384
	ds_read_b128 v[208:211], v153 offset:17408
	ds_read_b128 v[212:215], v153 offset:18432
	ds_read_b128 v[216:219], v153 offset:19456
	ds_read_b128 v[220:223], v153 offset:20480
	ds_read_b128 v[224:227], v153 offset:21504
	ds_read_b128 v[228:231], v153 offset:22528
	ds_read_b128 v[232:235], v153 offset:23552
	global_load_lds_dwordx4 v64, s[2:3]
	s_add_i32 m0, s31, 0x2000
	s_add_u32 s34, s2, 0x40000
	s_addc_u32 s35, s3, 0
	s_add_i32 s31, s33, s22
	global_load_lds_dwordx4 v130, s[2:3]
	s_mov_b32 m0, s31
	s_mov_b64 s[100:101], s[16:17]
	global_load_lds_dwordx4 v64, s[34:35]
	s_add_i32 m0, s31, 0x2000
	s_nop 0
	global_load_lds_dwordx4 v130, s[34:35]
	s_mov_b32 m0, s23
	s_nop 0
	global_load_lds_dwordx4 v134, s[16:17]
	s_mov_b32 m0, s24
	s_nop 0
	global_load_lds_dwordx4 v132, s[16:17]
	s_waitcnt vmcnt(8)
	s_waitcnt lgkmcnt(0)
	s_barrier
	s_setprio 1
	v_mfma_f32_16x16x32_bf16 v[60:63], v[140:143], v[194:197], v[60:63]
	v_mfma_f32_16x16x32_bf16 v[56:59], v[154:157], v[194:197], v[56:59]
	v_mfma_f32_16x16x32_bf16 v[44:47], v[140:143], v[212:215], v[44:47]
	v_mfma_f32_16x16x32_bf16 v[40:43], v[154:157], v[212:215], v[40:43]
	v_mfma_f32_16x16x32_bf16 v[28:31], v[140:143], v[220:223], v[28:31]
	v_mfma_f32_16x16x32_bf16 v[24:27], v[154:157], v[220:223], v[24:27]
	v_mfma_f32_16x16x32_bf16 v[12:15], v[140:143], v[228:231], v[12:15]
	v_mfma_f32_16x16x32_bf16 v[8:11], v[154:157], v[228:231], v[8:11]
	s_setprio 0
	s_setprio 1
	v_mfma_f32_16x16x32_bf16 v[60:63], v[144:147], v[208:211], v[60:63]
	v_mfma_f32_16x16x32_bf16 v[56:59], v[158:161], v[208:211], v[56:59]
	v_mfma_f32_16x16x32_bf16 v[44:47], v[144:147], v[216:219], v[44:47]
	v_mfma_f32_16x16x32_bf16 v[40:43], v[158:161], v[216:219], v[40:43]
	v_mfma_f32_16x16x32_bf16 v[28:31], v[144:147], v[224:227], v[28:31]
	v_mfma_f32_16x16x32_bf16 v[24:27], v[158:161], v[224:227], v[24:27]
	v_mfma_f32_16x16x32_bf16 v[12:15], v[144:147], v[232:235], v[12:15]
	v_mfma_f32_16x16x32_bf16 v[8:11], v[158:161], v[232:235], v[8:11]
	s_setprio 0
	s_setprio 1
	v_mfma_f32_16x16x32_bf16 v[52:55], v[178:181], v[194:197], v[52:55]
	v_mfma_f32_16x16x32_bf16 v[48:51], v[186:189], v[194:197], v[48:51]
	v_mfma_f32_16x16x32_bf16 v[36:39], v[178:181], v[212:215], v[36:39]
	v_mfma_f32_16x16x32_bf16 v[32:35], v[186:189], v[212:215], v[32:35]
	v_mfma_f32_16x16x32_bf16 v[20:23], v[178:181], v[220:223], v[20:23]
	v_mfma_f32_16x16x32_bf16 v[16:19], v[186:189], v[220:223], v[16:19]
	v_mfma_f32_16x16x32_bf16 v[4:7], v[178:181], v[228:231], v[4:7]
	v_mfma_f32_16x16x32_bf16 v[0:3], v[186:189], v[228:231], v[0:3]
	s_setprio 0
	s_setprio 1
	v_mfma_f32_16x16x32_bf16 v[52:55], v[182:185], v[208:211], v[52:55]
	v_mfma_f32_16x16x32_bf16 v[48:51], v[190:193], v[208:211], v[48:51]
	v_mfma_f32_16x16x32_bf16 v[36:39], v[182:185], v[216:219], v[36:39]
	v_mfma_f32_16x16x32_bf16 v[32:35], v[190:193], v[216:219], v[32:35]
	v_mfma_f32_16x16x32_bf16 v[20:23], v[182:185], v[224:227], v[20:23]
	v_mfma_f32_16x16x32_bf16 v[16:19], v[190:193], v[224:227], v[16:19]
	v_mfma_f32_16x16x32_bf16 v[4:7], v[182:185], v[232:235], v[4:7]
	v_mfma_f32_16x16x32_bf16 v[0:3], v[190:193], v[232:235], v[0:3]
	s_setprio 0
	s_barrier
; #define PG8_STAGE(bufoff, gbase, voff) do { _Pragma("unroll") for (int _i = 0; _i < 2; ++_i) \
;         __builtin_amdgcn_global_load_lds((const unsigned*)((const char*)(gbase) + (voff)[_i]), (PG8_LAS unsigned*)(lds + (bufoff) + ldsw + _i * 8192), 16, 0, 0); } while (0)
; #define PG8_LDA(dst, b, h) do { _Pragma("unroll") for (int m = 0; m < 4; ++m) _Pragma("unroll") for (int k = 0; k < 2; ++k) dst[m][k] = *(const PG8_LAS bf16x8*)(lds + PG8_SA(b, h) + aoff + m * 2048 + k * 1024); } while (0)
; #define PG8_LDB(dst, b, h) do { _Pragma("unroll") for (int n = 0; n < 2; ++n) _Pragma("unroll") for (int k = 0; k < 2; ++k) dst[n][k] = *(const PG8_LAS bf16x8*)(lds + PG8_SB(b, h) + boff + n * 2048 + k * 1024); } while (0)
; #define PG8_MMA(ai, bj, At, Bt) do { __builtin_amdgcn_s_setprio(1); _Pragma("unroll") for (int m = 0; m < 4; ++m) _Pragma("unroll") for (int n = 0; n < 2; ++n) _Pragma("unroll") for (int k = 0; k < 2; ++k) \
;         acc[ai][bj][m][n] = __builtin_amdgcn_mfma_f32_16x16x32_bf16(Bt[n][k], At[m][k], acc[ai][bj][m][n], 0, 0, 0); __builtin_amdgcn_s_setprio(0); } while (0)
; #define PG8_WAIT_V(n) asm volatile("s_waitcnt vmcnt(" #n ")" ::: "memory")
; #define PG8_WAIT_L(n) asm volatile("s_waitcnt lgkmcnt(" #n ")" ::: "memory")
; #define PG8_BAR __builtin_amdgcn_s_barrier()
; #define PG8_SCHED __builtin_amdgcn_sched_barrier(0)
; template <class Epi, class Sched, bool ALIGN_EPI = false, bool SP2 = false>
; __device__ __forceinline__ void gemm_phase(PG8_LAS unsigned char* lds, const Gemm g, const Sched& S, const Epi& E, const int wave0) {
;     ...
;         for (int t = 0; t < nt; t += 2) {
;             const bool last = (t == nt - 2);
;             const char* a1 = cA + (size_t)(t + 1) * kstep;
;             const char* a2 = last ? nA : cA + (size_t)(t + 2) * kstep; const char* b2 = last ? nB : cB + (size_t)(t + 2) * kstep;
;     ...
;             PG8_LDB(B0, 1, 0); PG8_LDB(B1, 1, 1); PG8_SCHED; PG8_LDA(At, 1, 0); PG8_STAGE(PG8_SA(0, 1), a2 + hstepA, voffA);
;             PG8_WAIT_V(8); PG8_WAIT_L(0); PG8_BAR; PG8_MMA(0, 0, At, B0); PG8_MMA(0, 1, At, B1); PG8_BAR; PG8_SCHED;
;             PG8_LDA(At, 1, 1); PG8_STAGE(PG8_SB(1, 0), b3, voffB); PG8_STAGE(PG8_SB(1, 1), b3 + hstepB, voffB); PG8_STAGE(PG8_SA(1, 0), a3, voffA);
;             PG8_WAIT_V(8); PG8_WAIT_L(0); PG8_BAR; PG8_MMA(1, 0, At, B0); PG8_MMA(1, 1, At, B1); PG8_BAR; PG8_SCHED;
	s_add_i32 s31, 0, 0x18000
	s_add_i32 s33, 0, 0x1c000
	ds_read_b128 v[140:143], v254
	ds_read_b128 v[144:147], v254 offset:1024
	ds_read_b128 v[154:157], v254 offset:2048
	ds_read_b128 v[158:161], v254 offset:3072
	ds_read_b128 v[178:181], v255
	ds_read_b128 v[182:185], v255 offset:1024
	ds_read_b128 v[186:189], v255 offset:2048
	ds_read_b128 v[190:193], v255 offset:3072
	s_add_u32 s16, s16, 0x40000
	s_addc_u32 s17, s17, 0
	s_mov_b32 m0, s25
	ds_read_b128 v[194:197], v153 offset:32768
	ds_read_b128 v[208:211], v153 offset:33792
	ds_read_b128 v[212:215], v153 offset:34816
	ds_read_b128 v[216:219], v153 offset:35840
	ds_read_b128 v[220:223], v153 offset:36864
	ds_read_b128 v[224:227], v153 offset:37888
	ds_read_b128 v[228:231], v153 offset:38912
	ds_read_b128 v[232:235], v153 offset:39936
	global_load_lds_dwordx4 v134, s[16:17]
	s_mov_b32 m0, s26
	s_nop 0
	global_load_lds_dwordx4 v132, s[16:17]
	s_waitcnt vmcnt(8)
	s_waitcnt lgkmcnt(0)
	s_barrier
	s_setprio 1
	v_mfma_f32_16x16x32_bf16 v[126:129], v[140:143], v[194:197], v[126:129]
	v_mfma_f32_16x16x32_bf16 v[122:125], v[154:157], v[194:197], v[122:125]
	v_mfma_f32_16x16x32_bf16 v[110:113], v[140:143], v[212:215], v[110:113]
	v_mfma_f32_16x16x32_bf16 v[106:109], v[154:157], v[212:215], v[106:109]
	v_mfma_f32_16x16x32_bf16 v[94:97], v[140:143], v[220:223], v[94:97]
	v_mfma_f32_16x16x32_bf16 v[90:93], v[154:157], v[220:223], v[90:93]
	v_mfma_f32_16x16x32_bf16 v[78:81], v[140:143], v[228:231], v[78:81]
	v_mfma_f32_16x16x32_bf16 v[74:77], v[154:157], v[228:231], v[74:77]
	s_setprio 0
	s_setprio 1
	v_mfma_f32_16x16x32_bf16 v[126:129], v[144:147], v[208:211], v[126:129]
	v_mfma_f32_16x16x32_bf16 v[122:125], v[158:161], v[208:211], v[122:125]
	v_mfma_f32_16x16x32_bf16 v[110:113], v[144:147], v[216:219], v[110:113]
	v_mfma_f32_16x16x32_bf16 v[106:109], v[158:161], v[216:219], v[106:109]
	v_mfma_f32_16x16x32_bf16 v[94:97], v[144:147], v[224:227], v[94:97]
	v_mfma_f32_16x16x32_bf16 v[90:93], v[158:161], v[224:227], v[90:93]
	v_mfma_f32_16x16x32_bf16 v[78:81], v[144:147], v[232:235], v[78:81]
	v_mfma_f32_16x16x32_bf16 v[74:77], v[158:161], v[232:235], v[74:77]
	s_setprio 0
	s_setprio 1
	v_mfma_f32_16x16x32_bf16 v[118:121], v[178:181], v[194:197], v[118:121]
	v_mfma_f32_16x16x32_bf16 v[114:117], v[186:189], v[194:197], v[114:117]
	v_mfma_f32_16x16x32_bf16 v[102:105], v[178:181], v[212:215], v[102:105]
	v_mfma_f32_16x16x32_bf16 v[98:101], v[186:189], v[212:215], v[98:101]
	v_mfma_f32_16x16x32_bf16 v[86:89], v[178:181], v[220:223], v[86:89]
	v_mfma_f32_16x16x32_bf16 v[82:85], v[186:189], v[220:223], v[82:85]
	v_mfma_f32_16x16x32_bf16 v[70:73], v[178:181], v[228:231], v[70:73]
	v_mfma_f32_16x16x32_bf16 v[66:69], v[186:189], v[228:231], v[66:69]
	s_setprio 0
	s_setprio 1
	v_mfma_f32_16x16x32_bf16 v[118:121], v[182:185], v[208:211], v[118:121]
	v_mfma_f32_16x16x32_bf16 v[114:117], v[190:193], v[208:211], v[114:117]
	v_mfma_f32_16x16x32_bf16 v[102:105], v[182:185], v[216:219], v[102:105]
	v_mfma_f32_16x16x32_bf16 v[98:101], v[190:193], v[216:219], v[98:101]
	v_mfma_f32_16x16x32_bf16 v[86:89], v[182:185], v[224:227], v[86:89]
	v_mfma_f32_16x16x32_bf16 v[82:85], v[190:193], v[224:227], v[82:85]
	v_mfma_f32_16x16x32_bf16 v[70:73], v[182:185], v[232:235], v[70:73]
	v_mfma_f32_16x16x32_bf16 v[66:69], v[190:193], v[232:235], v[66:69]
	s_setprio 0
	s_barrier
	s_add_i32 s16, s31, s22
	s_add_u32 s36, s2, 0x80
	s_addc_u32 s37, s3, 0
	s_mov_b32 m0, s16
	ds_read_b128 v[194:197], v153 offset:49152
	ds_read_b128 v[208:211], v153 offset:50176
	ds_read_b128 v[212:215], v153 offset:51200
	ds_read_b128 v[216:219], v153 offset:52224
	ds_read_b128 v[220:223], v153 offset:53248
	ds_read_b128 v[224:227], v153 offset:54272
	ds_read_b128 v[228:231], v153 offset:55296
	ds_read_b128 v[232:235], v153 offset:56320
	global_load_lds_dwordx4 v64, s[36:37]
	s_add_i32 m0, s16, 0x2000
	s_add_u32 s2, s2, 0x40080
	s_addc_u32 s3, s3, 0
	s_add_i32 s16, s33, s22
	global_load_lds_dwordx4 v130, s[36:37]
	s_mov_b32 m0, s16
	s_nop 0
	global_load_lds_dwordx4 v64, s[2:3]
	s_add_i32 m0, s16, 0x2000
	s_nop 0
	global_load_lds_dwordx4 v130, s[2:3]
	s_add_u32 s100, s100, 0x80
	s_addc_u32 s101, s101, 0
	s_mov_b32 m0, s27
	s_nop 0
	global_load_lds_dwordx4 v134, s[100:101]
	s_mov_b32 m0, s28
	s_nop 0
	global_load_lds_dwordx4 v132, s[100:101]
	s_waitcnt vmcnt(8)
	s_waitcnt lgkmcnt(0)
	s_barrier
	s_setprio 1
	v_mfma_f32_16x16x32_bf16 v[60:63], v[140:143], v[194:197], v[60:63]
	v_mfma_f32_16x16x32_bf16 v[56:59], v[154:157], v[194:197], v[56:59]
	v_mfma_f32_16x16x32_bf16 v[44:47], v[140:143], v[212:215], v[44:47]
	v_mfma_f32_16x16x32_bf16 v[40:43], v[154:157], v[212:215], v[40:43]
	v_mfma_f32_16x16x32_bf16 v[28:31], v[140:143], v[220:223], v[28:31]
	v_mfma_f32_16x16x32_bf16 v[24:27], v[154:157], v[220:223], v[24:27]
	v_mfma_f32_16x16x32_bf16 v[12:15], v[140:143], v[228:231], v[12:15]
	v_mfma_f32_16x16x32_bf16 v[8:11], v[154:157], v[228:231], v[8:11]
	s_setprio 0
	s_setprio 1
	v_mfma_f32_16x16x32_bf16 v[60:63], v[144:147], v[208:211], v[60:63]
	v_mfma_f32_16x16x32_bf16 v[56:59], v[158:161], v[208:211], v[56:59]
	v_mfma_f32_16x16x32_bf16 v[44:47], v[144:147], v[216:219], v[44:47]
	v_mfma_f32_16x16x32_bf16 v[40:43], v[158:161], v[216:219], v[40:43]
	v_mfma_f32_16x16x32_bf16 v[28:31], v[144:147], v[224:227], v[28:31]
	v_mfma_f32_16x16x32_bf16 v[24:27], v[158:161], v[224:227], v[24:27]
	v_mfma_f32_16x16x32_bf16 v[12:15], v[144:147], v[232:235], v[12:15]
	v_mfma_f32_16x16x32_bf16 v[8:11], v[158:161], v[232:235], v[8:11]
	s_setprio 0
	s_setprio 1
	v_mfma_f32_16x16x32_bf16 v[52:55], v[178:181], v[194:197], v[52:55]
	v_mfma_f32_16x16x32_bf16 v[48:51], v[186:189], v[194:197], v[48:51]
	v_mfma_f32_16x16x32_bf16 v[36:39], v[178:181], v[212:215], v[36:39]
	v_mfma_f32_16x16x32_bf16 v[32:35], v[186:189], v[212:215], v[32:35]
	v_mfma_f32_16x16x32_bf16 v[20:23], v[178:181], v[220:223], v[20:23]
	v_mfma_f32_16x16x32_bf16 v[16:19], v[186:189], v[220:223], v[16:19]
	v_mfma_f32_16x16x32_bf16 v[4:7], v[178:181], v[228:231], v[4:7]
	v_mfma_f32_16x16x32_bf16 v[0:3], v[186:189], v[228:231], v[0:3]
	s_setprio 0
	s_setprio 1
	v_mfma_f32_16x16x32_bf16 v[52:55], v[182:185], v[208:211], v[52:55]
	v_mfma_f32_16x16x32_bf16 v[48:51], v[190:193], v[208:211], v[48:51]
	v_mfma_f32_16x16x32_bf16 v[36:39], v[182:185], v[216:219], v[36:39]
	v_mfma_f32_16x16x32_bf16 v[32:35], v[190:193], v[216:219], v[32:35]
	v_mfma_f32_16x16x32_bf16 v[20:23], v[182:185], v[224:227], v[20:23]
	v_mfma_f32_16x16x32_bf16 v[16:19], v[190:193], v[224:227], v[16:19]
	v_mfma_f32_16x16x32_bf16 v[4:7], v[182:185], v[232:235], v[4:7]
	v_mfma_f32_16x16x32_bf16 v[0:3], v[190:193], v[232:235], v[0:3]
	s_setprio 0
	s_barrier
	s_add_i32 s19, s19, 2
	s_add_u32 s0, s0, 0x100
	s_addc_u32 s1, s1, 0
	s_add_u32 s13, s13, 0x100
	s_addc_u32 s18, s18, 0
	s_cmp_gt_u32 s19, 13
	s_cbranch_scc0 .LBB0_1231
	s_mov_b64 s[36:37], 0x80
	s_and_b64 vcc, exec, s[6:7]
	s_cbranch_vccz .LBB0_1234
	s_barrier

; #define PG8_STAGE(bufoff, gbase, voff) do { _Pragma("unroll") for (int _i = 0; _i < 2; ++_i) \
;         __builtin_amdgcn_global_load_lds((const unsigned*)((const char*)(gbase) + (voff)[_i]), (PG8_LAS unsigned*)(lds + (bufoff) + ldsw + _i * 8192), 16, 0, 0); } while (0)
; #define PG8_LDA(dst, b, h) do { _Pragma("unroll") for (int m = 0; m < 4; ++m) _Pragma("unroll") for (int k = 0; k < 2; ++k) dst[m][k] = *(const PG8_LAS bf16x8*)(lds + PG8_SA(b, h) + aoff + m * 2048 + k * 1024); } while (0)
; #define PG8_LDB(dst, b, h) do { _Pragma("unroll") for (int n = 0; n < 2; ++n) _Pragma("unroll") for (int k = 0; k < 2; ++k) dst[n][k] = *(const PG8_LAS bf16x8*)(lds + PG8_SB(b, h) + boff + n * 2048 + k * 1024); } while (0)
; #define PG8_MMA(ai, bj, At, Bt) do { __builtin_amdgcn_s_setprio(1); _Pragma("unroll") for (int m = 0; m < 4; ++m) _Pragma("unroll") for (int n = 0; n < 2; ++n) _Pragma("unroll") for (int k = 0; k < 2; ++k) \
;         acc[ai][bj][m][n] = __builtin_amdgcn_mfma_f32_16x16x32_bf16(Bt[n][k], At[m][k], acc[ai][bj][m][n], 0, 0, 0); __builtin_amdgcn_s_setprio(0); } while (0)
; #define PG8_WAIT_V(n) asm volatile("s_waitcnt vmcnt(" #n ")" ::: "memory")
; #define PG8_WAIT_L(n) asm volatile("s_waitcnt lgkmcnt(" #n ")" ::: "memory")
; template <class Epi, class Sched, bool ALIGN_EPI = false, bool SP2 = false>
; __device__ __forceinline__ void gemm_phase(PG8_LAS unsigned char* lds, const Gemm g, const Sched& S, const Epi& E, const int wave0) {
;     ...
;             const bool last = (t == nt - 2);
;             const char* a1 = cA + (size_t)(t + 1) * kstep;
;             const char* a2 = last ? nA : cA + (size_t)(t + 2) * kstep; const char* b2 = last ? nB : cB + (size_t)(t + 2) * kstep;
;             const char* a3 = a2 + kstep; const char* b3 = b2 + kstep;
;             if (last && has_next) S.a_ready(nxt);
;             if constexpr (SP2) {
;             PG8_LDB(B0, 0, 0); PG8_LDB(B1, 0, 1); PG8_SCHED; PG8_LDA(At, 0, 0); PG8_STAGE(PG8_SA(1, 1), a1 + hstepA, voffA);
;             PG8_WAIT_V(8); PG8_WAIT_L(0); PG8_BAR; PG8_MMA(0, 0, At, B0); PG8_MMA(0, 1, At, B1); PG8_BAR; PG8_SCHED;
;             PG8_LDA(At, 0, 1); PG8_STAGE(PG8_SB(0, 0), b2, voffB); PG8_STAGE(PG8_SB(0, 1), b2 + hstepB, voffB); PG8_STAGE(PG8_SA(0, 0), a2, voffA);
;             PG8_WAIT_V(8); PG8_WAIT_L(0); PG8_BAR; PG8_MMA(1, 0, At, B0); PG8_MMA(1, 1, At, B1); PG8_BAR; PG8_SCHED;
.LBB0_1341:
	s_add_u32 s16, s0, 0xfff80080
	s_addc_u32 s17, s1, -1
	s_add_i32 s40, 0, 0x10000
	s_cmp_eq_u32 s37, 28
	s_cselect_b32 s19, s11, s17
	s_cselect_b32 s18, s33, s16
	s_cselect_b32 s17, s9, s36
	s_cselect_b32 s16, s34, s35
	s_add_i32 s42, 0, 0x14000
	ds_read_b128 v[144:147], v252
	ds_read_b128 v[148:151], v252 offset:1024
	ds_read_b128 v[152:155], v252 offset:2048
	ds_read_b128 v[156:159], v252 offset:3072
	ds_read_b128 v[178:181], v253
	ds_read_b128 v[182:185], v253 offset:1024
	ds_read_b128 v[186:189], v253 offset:2048
	ds_read_b128 v[190:193], v253 offset:3072
	s_add_i32 m0, s23, 0xc000
	ds_read_b128 v[194:197], v143
	ds_read_b128 v[208:211], v143 offset:1024
	ds_read_b128 v[212:215], v143 offset:2048
	ds_read_b128 v[216:219], v143 offset:3072
	ds_read_b128 v[220:223], v143 offset:4096
	ds_read_b128 v[224:227], v143 offset:5120
	ds_read_b128 v[228:231], v143 offset:6144
	ds_read_b128 v[232:235], v143 offset:7168
	global_load_lds_dwordx4 v136, s[0:1]
	s_add_i32 m0, s23, 0xe000
	s_nop 0
	global_load_lds_dwordx4 v138, s[0:1]
	s_waitcnt vmcnt(8)
	s_waitcnt lgkmcnt(0)
	s_barrier
	s_setprio 1
	v_mfma_f32_16x16x32_bf16 v[126:129], v[144:147], v[194:197], v[126:129]
	v_mfma_f32_16x16x32_bf16 v[122:125], v[152:155], v[194:197], v[122:125]
	v_mfma_f32_16x16x32_bf16 v[118:121], v[144:147], v[212:215], v[118:121]
	v_mfma_f32_16x16x32_bf16 v[114:117], v[152:155], v[212:215], v[114:117]
	v_mfma_f32_16x16x32_bf16 v[102:105], v[144:147], v[220:223], v[102:105]
	v_mfma_f32_16x16x32_bf16 v[98:101], v[152:155], v[220:223], v[98:101]
	v_mfma_f32_16x16x32_bf16 v[86:89], v[144:147], v[228:231], v[86:89]
	v_mfma_f32_16x16x32_bf16 v[82:85], v[152:155], v[228:231], v[82:85]
	s_setprio 0
	s_setprio 1
	v_mfma_f32_16x16x32_bf16 v[126:129], v[148:151], v[208:211], v[126:129]
	v_mfma_f32_16x16x32_bf16 v[122:125], v[156:159], v[208:211], v[122:125]
	v_mfma_f32_16x16x32_bf16 v[118:121], v[148:151], v[216:219], v[118:121]
	v_mfma_f32_16x16x32_bf16 v[114:117], v[156:159], v[216:219], v[114:117]
	v_mfma_f32_16x16x32_bf16 v[102:105], v[148:151], v[224:227], v[102:105]
	v_mfma_f32_16x16x32_bf16 v[98:101], v[156:159], v[224:227], v[98:101]
	v_mfma_f32_16x16x32_bf16 v[86:89], v[148:151], v[232:235], v[86:89]
	v_mfma_f32_16x16x32_bf16 v[82:85], v[156:159], v[232:235], v[82:85]
	s_setprio 0
	s_setprio 1
	v_mfma_f32_16x16x32_bf16 v[110:113], v[178:181], v[194:197], v[110:113]
	v_mfma_f32_16x16x32_bf16 v[106:109], v[186:189], v[194:197], v[106:109]
	v_mfma_f32_16x16x32_bf16 v[94:97], v[178:181], v[212:215], v[94:97]
	v_mfma_f32_16x16x32_bf16 v[90:93], v[186:189], v[212:215], v[90:93]
	v_mfma_f32_16x16x32_bf16 v[78:81], v[178:181], v[220:223], v[78:81]
	v_mfma_f32_16x16x32_bf16 v[74:77], v[186:189], v[220:223], v[74:77]
	v_mfma_f32_16x16x32_bf16 v[70:73], v[178:181], v[228:231], v[70:73]
	v_mfma_f32_16x16x32_bf16 v[66:69], v[186:189], v[228:231], v[66:69]
	s_setprio 0
	s_setprio 1
	v_mfma_f32_16x16x32_bf16 v[110:113], v[182:185], v[208:211], v[110:113]
	v_mfma_f32_16x16x32_bf16 v[106:109], v[190:193], v[208:211], v[106:109]
	v_mfma_f32_16x16x32_bf16 v[94:97], v[182:185], v[216:219], v[94:97]
	v_mfma_f32_16x16x32_bf16 v[90:93], v[190:193], v[216:219], v[90:93]
	v_mfma_f32_16x16x32_bf16 v[78:81], v[182:185], v[224:227], v[78:81]
	v_mfma_f32_16x16x32_bf16 v[74:77], v[190:193], v[224:227], v[74:77]
	v_mfma_f32_16x16x32_bf16 v[70:73], v[182:185], v[232:235], v[70:73]
	v_mfma_f32_16x16x32_bf16 v[66:69], v[190:193], v[232:235], v[66:69]
	s_setprio 0
	s_barrier
	s_add_i32 s40, s40, s22
	s_mov_b32 m0, s40
	ds_read_b128 v[194:197], v143 offset:16384
	ds_read_b128 v[208:211], v143 offset:17408
	ds_read_b128 v[212:215], v143 offset:18432
	ds_read_b128 v[216:219], v143 offset:19456
	ds_read_b128 v[220:223], v143 offset:20480
	ds_read_b128 v[224:227], v143 offset:21504
	ds_read_b128 v[228:231], v143 offset:22528
	ds_read_b128 v[232:235], v143 offset:23552
	global_load_lds_dwordx4 v64, s[16:17]
	s_add_i32 m0, s40, 0x2000
	s_add_u32 s40, s16, 0x80000
	s_addc_u32 s41, s17, 0
	s_add_i32 s42, s42, s22
	global_load_lds_dwordx4 v130, s[16:17]
	s_mov_b32 m0, s42
	s_mov_b64 s[100:101], s[18:19]
	global_load_lds_dwordx4 v64, s[40:41]
	s_add_i32 m0, s42, 0x2000
	s_nop 0
	global_load_lds_dwordx4 v130, s[40:41]
	s_mov_b32 m0, s23
	s_nop 0
	global_load_lds_dwordx4 v134, s[18:19]
	s_mov_b32 m0, s24
	s_nop 0
	global_load_lds_dwordx4 v132, s[18:19]
	s_waitcnt vmcnt(8)
	s_waitcnt lgkmcnt(0)
	s_barrier
	s_setprio 1
	v_mfma_f32_16x16x32_bf16 v[60:63], v[144:147], v[194:197], v[60:63]
	v_mfma_f32_16x16x32_bf16 v[56:59], v[152:155], v[194:197], v[56:59]
	v_mfma_f32_16x16x32_bf16 v[52:55], v[144:147], v[212:215], v[52:55]
	v_mfma_f32_16x16x32_bf16 v[48:51], v[152:155], v[212:215], v[48:51]
	v_mfma_f32_16x16x32_bf16 v[36:39], v[144:147], v[220:223], v[36:39]
	v_mfma_f32_16x16x32_bf16 v[32:35], v[152:155], v[220:223], v[32:35]
	v_mfma_f32_16x16x32_bf16 v[20:23], v[144:147], v[228:231], v[20:23]
	v_mfma_f32_16x16x32_bf16 v[16:19], v[152:155], v[228:231], v[16:19]
	s_setprio 0
	s_setprio 1
	v_mfma_f32_16x16x32_bf16 v[60:63], v[148:151], v[208:211], v[60:63]
	v_mfma_f32_16x16x32_bf16 v[56:59], v[156:159], v[208:211], v[56:59]
	v_mfma_f32_16x16x32_bf16 v[52:55], v[148:151], v[216:219], v[52:55]
	v_mfma_f32_16x16x32_bf16 v[48:51], v[156:159], v[216:219], v[48:51]
	v_mfma_f32_16x16x32_bf16 v[36:39], v[148:151], v[224:227], v[36:39]
	v_mfma_f32_16x16x32_bf16 v[32:35], v[156:159], v[224:227], v[32:35]
	v_mfma_f32_16x16x32_bf16 v[20:23], v[148:151], v[232:235], v[20:23]
	v_mfma_f32_16x16x32_bf16 v[16:19], v[156:159], v[232:235], v[16:19]
	s_setprio 0
	s_setprio 1
	v_mfma_f32_16x16x32_bf16 v[44:47], v[178:181], v[194:197], v[44:47]
	v_mfma_f32_16x16x32_bf16 v[40:43], v[186:189], v[194:197], v[40:43]
	v_mfma_f32_16x16x32_bf16 v[28:31], v[178:181], v[212:215], v[28:31]
	v_mfma_f32_16x16x32_bf16 v[24:27], v[186:189], v[212:215], v[24:27]
	v_mfma_f32_16x16x32_bf16 v[12:15], v[178:181], v[220:223], v[12:15]
	v_mfma_f32_16x16x32_bf16 v[8:11], v[186:189], v[220:223], v[8:11]
	v_mfma_f32_16x16x32_bf16 v[4:7], v[178:181], v[228:231], v[4:7]
	v_mfma_f32_16x16x32_bf16 v[0:3], v[186:189], v[228:231], v[0:3]
	s_setprio 0
	s_setprio 1
	v_mfma_f32_16x16x32_bf16 v[44:47], v[182:185], v[208:211], v[44:47]
	v_mfma_f32_16x16x32_bf16 v[40:43], v[190:193], v[208:211], v[40:43]
	v_mfma_f32_16x16x32_bf16 v[28:31], v[182:185], v[216:219], v[28:31]
	v_mfma_f32_16x16x32_bf16 v[24:27], v[190:193], v[216:219], v[24:27]
	v_mfma_f32_16x16x32_bf16 v[12:15], v[182:185], v[224:227], v[12:15]
	v_mfma_f32_16x16x32_bf16 v[8:11], v[190:193], v[224:227], v[8:11]
	v_mfma_f32_16x16x32_bf16 v[4:7], v[182:185], v[232:235], v[4:7]
	v_mfma_f32_16x16x32_bf16 v[0:3], v[190:193], v[232:235], v[0:3]
	s_setprio 0
	s_barrier
; #define PG8_STAGE(bufoff, gbase, voff) do { _Pragma("unroll") for (int _i = 0; _i < 2; ++_i) \
;         __builtin_amdgcn_global_load_lds((const unsigned*)((const char*)(gbase) + (voff)[_i]), (PG8_LAS unsigned*)(lds + (bufoff) + ldsw + _i * 8192), 16, 0, 0); } while (0)
; #define PG8_LDA(dst, b, h) do { _Pragma("unroll") for (int m = 0; m < 4; ++m) _Pragma("unroll") for (int k = 0; k < 2; ++k) dst[m][k] = *(const PG8_LAS bf16x8*)(lds + PG8_SA(b, h) + aoff + m * 2048 + k * 1024); } while (0)
; #define PG8_LDB(dst, b, h) do { _Pragma("unroll") for (int n = 0; n < 2; ++n) _Pragma("unroll") for (int k = 0; k < 2; ++k) dst[n][k] = *(const PG8_LAS bf16x8*)(lds + PG8_SB(b, h) + boff + n * 2048 + k * 1024); } while (0)
; #define PG8_MMA(ai, bj, At, Bt) do { __builtin_amdgcn_s_setprio(1); _Pragma("unroll") for (int m = 0; m < 4; ++m) _Pragma("unroll") for (int n = 0; n < 2; ++n) _Pragma("unroll") for (int k = 0; k < 2; ++k) \
;         acc[ai][bj][m][n] = __builtin_amdgcn_mfma_f32_16x16x32_bf16(Bt[n][k], At[m][k], acc[ai][bj][m][n], 0, 0, 0); __builtin_amdgcn_s_setprio(0); } while (0)
; #define PG8_WAIT_V(n) asm volatile("s_waitcnt vmcnt(" #n ")" ::: "memory")
; #define PG8_WAIT_L(n) asm volatile("s_waitcnt lgkmcnt(" #n ")" ::: "memory")
; #define PG8_BAR __builtin_amdgcn_s_barrier()
; #define PG8_SCHED __builtin_amdgcn_sched_barrier(0)
; template <class Epi, class Sched, bool ALIGN_EPI = false, bool SP2 = false>
; __device__ __forceinline__ void gemm_phase(PG8_LAS unsigned char* lds, const Gemm g, const Sched& S, const Epi& E, const int wave0) {
;     ...
;         for (int t = 0; t < nt; t += 2) {
;             const bool last = (t == nt - 2);
;             const char* a1 = cA + (size_t)(t + 1) * kstep;
;             const char* a2 = last ? nA : cA + (size_t)(t + 2) * kstep; const char* b2 = last ? nB : cB + (size_t)(t + 2) * kstep;
;     ...
;             PG8_LDB(B0, 1, 0); PG8_LDB(B1, 1, 1); PG8_SCHED; PG8_LDA(At, 1, 0); PG8_STAGE(PG8_SA(0, 1), a2 + hstepA, voffA);
;             PG8_WAIT_V(8); PG8_WAIT_L(0); PG8_BAR; PG8_MMA(0, 0, At, B0); PG8_MMA(0, 1, At, B1); PG8_BAR; PG8_SCHED;
;             PG8_LDA(At, 1, 1); PG8_STAGE(PG8_SB(1, 0), b3, voffB); PG8_STAGE(PG8_SB(1, 1), b3 + hstepB, voffB); PG8_STAGE(PG8_SA(1, 0), a3, voffA);
;             PG8_WAIT_V(8); PG8_WAIT_L(0); PG8_BAR; PG8_MMA(1, 0, At, B0); PG8_MMA(1, 1, At, B1); PG8_BAR; PG8_SCHED;
	s_add_i32 s40, 0, 0x18000
	s_add_i32 s41, 0, 0x1c000
	ds_read_b128 v[144:147], v254
	ds_read_b128 v[148:151], v254 offset:1024
	ds_read_b128 v[152:155], v254 offset:2048
	ds_read_b128 v[156:159], v254 offset:3072
	ds_read_b128 v[178:181], v255
	ds_read_b128 v[182:185], v255 offset:1024
	ds_read_b128 v[186:189], v255 offset:2048
	ds_read_b128 v[190:193], v255 offset:3072
	s_add_u32 s18, s18, 0x80000
	s_addc_u32 s19, s19, 0
	s_mov_b32 m0, s25
	ds_read_b128 v[194:197], v143 offset:32768
	ds_read_b128 v[208:211], v143 offset:33792
	ds_read_b128 v[212:215], v143 offset:34816
	ds_read_b128 v[216:219], v143 offset:35840
	ds_read_b128 v[220:223], v143 offset:36864
	ds_read_b128 v[224:227], v143 offset:37888
	ds_read_b128 v[228:231], v143 offset:38912
	ds_read_b128 v[232:235], v143 offset:39936
	global_load_lds_dwordx4 v134, s[18:19]
	s_mov_b32 m0, s26
	s_nop 0
	global_load_lds_dwordx4 v132, s[18:19]
	s_waitcnt vmcnt(8)
	s_waitcnt lgkmcnt(0)
	s_barrier
	s_setprio 1
	v_mfma_f32_16x16x32_bf16 v[126:129], v[144:147], v[194:197], v[126:129]
	v_mfma_f32_16x16x32_bf16 v[122:125], v[152:155], v[194:197], v[122:125]
	v_mfma_f32_16x16x32_bf16 v[118:121], v[144:147], v[212:215], v[118:121]
	v_mfma_f32_16x16x32_bf16 v[114:117], v[152:155], v[212:215], v[114:117]
	v_mfma_f32_16x16x32_bf16 v[102:105], v[144:147], v[220:223], v[102:105]
	v_mfma_f32_16x16x32_bf16 v[98:101], v[152:155], v[220:223], v[98:101]
	v_mfma_f32_16x16x32_bf16 v[86:89], v[144:147], v[228:231], v[86:89]
	v_mfma_f32_16x16x32_bf16 v[82:85], v[152:155], v[228:231], v[82:85]
	s_setprio 0
	s_setprio 1
	v_mfma_f32_16x16x32_bf16 v[126:129], v[148:151], v[208:211], v[126:129]
	v_mfma_f32_16x16x32_bf16 v[122:125], v[156:159], v[208:211], v[122:125]
	v_mfma_f32_16x16x32_bf16 v[118:121], v[148:151], v[216:219], v[118:121]
	v_mfma_f32_16x16x32_bf16 v[114:117], v[156:159], v[216:219], v[114:117]
	v_mfma_f32_16x16x32_bf16 v[102:105], v[148:151], v[224:227], v[102:105]
	v_mfma_f32_16x16x32_bf16 v[98:101], v[156:159], v[224:227], v[98:101]
	v_mfma_f32_16x16x32_bf16 v[86:89], v[148:151], v[232:235], v[86:89]
	v_mfma_f32_16x16x32_bf16 v[82:85], v[156:159], v[232:235], v[82:85]
	s_setprio 0
	s_setprio 1
	v_mfma_f32_16x16x32_bf16 v[110:113], v[178:181], v[194:197], v[110:113]
	v_mfma_f32_16x16x32_bf16 v[106:109], v[186:189], v[194:197], v[106:109]
	v_mfma_f32_16x16x32_bf16 v[94:97], v[178:181], v[212:215], v[94:97]
	v_mfma_f32_16x16x32_bf16 v[90:93], v[186:189], v[212:215], v[90:93]
	v_mfma_f32_16x16x32_bf16 v[78:81], v[178:181], v[220:223], v[78:81]
	v_mfma_f32_16x16x32_bf16 v[74:77], v[186:189], v[220:223], v[74:77]
	v_mfma_f32_16x16x32_bf16 v[70:73], v[178:181], v[228:231], v[70:73]
	v_mfma_f32_16x16x32_bf16 v[66:69], v[186:189], v[228:231], v[66:69]
	s_setprio 0
	s_setprio 1
	v_mfma_f32_16x16x32_bf16 v[110:113], v[182:185], v[208:211], v[110:113]
	v_mfma_f32_16x16x32_bf16 v[106:109], v[190:193], v[208:211], v[106:109]
	v_mfma_f32_16x16x32_bf16 v[94:97], v[182:185], v[216:219], v[94:97]
	v_mfma_f32_16x16x32_bf16 v[90:93], v[190:193], v[216:219], v[90:93]
	v_mfma_f32_16x16x32_bf16 v[78:81], v[182:185], v[224:227], v[78:81]
	v_mfma_f32_16x16x32_bf16 v[74:77], v[190:193], v[224:227], v[74:77]
	v_mfma_f32_16x16x32_bf16 v[70:73], v[182:185], v[232:235], v[70:73]
	v_mfma_f32_16x16x32_bf16 v[66:69], v[190:193], v[232:235], v[66:69]
	s_setprio 0
	s_barrier
	s_add_i32 s18, s40, s22
	s_add_u32 s44, s16, 0x80
	s_addc_u32 s45, s17, 0
	s_mov_b32 m0, s18
	ds_read_b128 v[194:197], v143 offset:49152
	ds_read_b128 v[208:211], v143 offset:50176
	ds_read_b128 v[212:215], v143 offset:51200
	ds_read_b128 v[216:219], v143 offset:52224
	ds_read_b128 v[220:223], v143 offset:53248
	ds_read_b128 v[224:227], v143 offset:54272
	ds_read_b128 v[228:231], v143 offset:55296
	ds_read_b128 v[232:235], v143 offset:56320
	global_load_lds_dwordx4 v64, s[44:45]
	s_add_i32 m0, s18, 0x2000
	s_add_u32 s16, s16, 0x80080
	s_addc_u32 s17, s17, 0
	s_add_i32 s18, s41, s22
	global_load_lds_dwordx4 v130, s[44:45]
	s_mov_b32 m0, s18
	s_nop 0
	global_load_lds_dwordx4 v64, s[16:17]
	s_add_i32 m0, s18, 0x2000
	s_nop 0
	global_load_lds_dwordx4 v130, s[16:17]
	s_add_u32 s100, s100, 0x80
	s_addc_u32 s101, s101, 0
	s_mov_b32 m0, s27
	s_nop 0
	global_load_lds_dwordx4 v134, s[100:101]
	s_mov_b32 m0, s28
	s_nop 0
	global_load_lds_dwordx4 v132, s[100:101]
	s_waitcnt vmcnt(8)
	s_waitcnt lgkmcnt(0)
	s_barrier
	s_setprio 1
	v_mfma_f32_16x16x32_bf16 v[60:63], v[144:147], v[194:197], v[60:63]
	v_mfma_f32_16x16x32_bf16 v[56:59], v[152:155], v[194:197], v[56:59]
	v_mfma_f32_16x16x32_bf16 v[52:55], v[144:147], v[212:215], v[52:55]
	v_mfma_f32_16x16x32_bf16 v[48:51], v[152:155], v[212:215], v[48:51]
	v_mfma_f32_16x16x32_bf16 v[36:39], v[144:147], v[220:223], v[36:39]
	v_mfma_f32_16x16x32_bf16 v[32:35], v[152:155], v[220:223], v[32:35]
	v_mfma_f32_16x16x32_bf16 v[20:23], v[144:147], v[228:231], v[20:23]
	v_mfma_f32_16x16x32_bf16 v[16:19], v[152:155], v[228:231], v[16:19]
	s_setprio 0
	s_setprio 1
	v_mfma_f32_16x16x32_bf16 v[60:63], v[148:151], v[208:211], v[60:63]
	v_mfma_f32_16x16x32_bf16 v[56:59], v[156:159], v[208:211], v[56:59]
	v_mfma_f32_16x16x32_bf16 v[52:55], v[148:151], v[216:219], v[52:55]
	v_mfma_f32_16x16x32_bf16 v[48:51], v[156:159], v[216:219], v[48:51]
	v_mfma_f32_16x16x32_bf16 v[36:39], v[148:151], v[224:227], v[36:39]
	v_mfma_f32_16x16x32_bf16 v[32:35], v[156:159], v[224:227], v[32:35]
	v_mfma_f32_16x16x32_bf16 v[20:23], v[148:151], v[232:235], v[20:23]
	v_mfma_f32_16x16x32_bf16 v[16:19], v[156:159], v[232:235], v[16:19]
	s_setprio 0
	s_setprio 1
	v_mfma_f32_16x16x32_bf16 v[44:47], v[178:181], v[194:197], v[44:47]
	v_mfma_f32_16x16x32_bf16 v[40:43], v[186:189], v[194:197], v[40:43]
	v_mfma_f32_16x16x32_bf16 v[28:31], v[178:181], v[212:215], v[28:31]
	v_mfma_f32_16x16x32_bf16 v[24:27], v[186:189], v[212:215], v[24:27]
	v_mfma_f32_16x16x32_bf16 v[12:15], v[178:181], v[220:223], v[12:15]
	v_mfma_f32_16x16x32_bf16 v[8:11], v[186:189], v[220:223], v[8:11]
	v_mfma_f32_16x16x32_bf16 v[4:7], v[178:181], v[228:231], v[4:7]
	v_mfma_f32_16x16x32_bf16 v[0:3], v[186:189], v[228:231], v[0:3]
	s_setprio 0
	s_setprio 1
	v_mfma_f32_16x16x32_bf16 v[44:47], v[182:185], v[208:211], v[44:47]
	v_mfma_f32_16x16x32_bf16 v[40:43], v[190:193], v[208:211], v[40:43]
	v_mfma_f32_16x16x32_bf16 v[28:31], v[182:185], v[216:219], v[28:31]
	v_mfma_f32_16x16x32_bf16 v[24:27], v[190:193], v[216:219], v[24:27]
	v_mfma_f32_16x16x32_bf16 v[12:15], v[182:185], v[224:227], v[12:15]
	v_mfma_f32_16x16x32_bf16 v[8:11], v[190:193], v[224:227], v[8:11]
	v_mfma_f32_16x16x32_bf16 v[4:7], v[182:185], v[232:235], v[4:7]
	v_mfma_f32_16x16x32_bf16 v[0:3], v[190:193], v[232:235], v[0:3]
	s_setprio 0
	s_barrier
	s_add_i32 s37, s37, 2
	s_add_u32 s0, s0, 0x100
	s_addc_u32 s1, s1, 0
	s_add_u32 s35, s35, 0x100
	s_addc_u32 s36, s36, 0
	s_cmp_gt_u32 s37, 29
	s_cbranch_scc0 .LBB0_1341
	s_mov_b64 s[44:45], 0x80
	s_and_b64 vcc, exec, s[6:7]
	s_mov_b64 s[34:35], 0x45000
	s_cbranch_vccz .LBB0_1344
	s_barrier

; #define PG8_STAGE(bufoff, gbase, voff) do { _Pragma("unroll") for (int _i = 0; _i < 2; ++_i) \
;         __builtin_amdgcn_global_load_lds((const unsigned*)((const char*)(gbase) + (voff)[_i]), (PG8_LAS unsigned*)(lds + (bufoff) + ldsw + _i * 8192), 16, 0, 0); } while (0)
; #define PG8_LDA(dst, b, h) do { _Pragma("unroll") for (int m = 0; m < 4; ++m) _Pragma("unroll") for (int k = 0; k < 2; ++k) dst[m][k] = *(const PG8_LAS bf16x8*)(lds + PG8_SA(b, h) + aoff + m * 2048 + k * 1024); } while (0)
; #define PG8_LDB(dst, b, h) do { _Pragma("unroll") for (int n = 0; n < 2; ++n) _Pragma("unroll") for (int k = 0; k < 2; ++k) dst[n][k] = *(const PG8_LAS bf16x8*)(lds + PG8_SB(b, h) + boff + n * 2048 + k * 1024); } while (0)
; #define PG8_MMA(ai, bj, At, Bt) do { __builtin_amdgcn_s_setprio(1); _Pragma("unroll") for (int m = 0; m < 4; ++m) _Pragma("unroll") for (int n = 0; n < 2; ++n) _Pragma("unroll") for (int k = 0; k < 2; ++k) \
;         acc[ai][bj][m][n] = __builtin_amdgcn_mfma_f32_16x16x32_bf16(Bt[n][k], At[m][k], acc[ai][bj][m][n], 0, 0, 0); __builtin_amdgcn_s_setprio(0); } while (0)
; #define PG8_WAIT_V(n) asm volatile("s_waitcnt vmcnt(" #n ")" ::: "memory")
; #define PG8_WAIT_L(n) asm volatile("s_waitcnt lgkmcnt(" #n ")" ::: "memory")
; template <class Epi, class Sched, bool ALIGN_EPI = false, bool SP2 = false>
; __device__ __forceinline__ void gemm_phase(PG8_LAS unsigned char* lds, const Gemm g, const Sched& S, const Epi& E, const int wave0) {
;     ...
;             const bool last = (t == nt - 2);
;             const char* a1 = cA + (size_t)(t + 1) * kstep;
;             const char* a2 = last ? nA : cA + (size_t)(t + 2) * kstep; const char* b2 = last ? nB : cB + (size_t)(t + 2) * kstep;
;             const char* a3 = a2 + kstep; const char* b3 = b2 + kstep;
;             if (last && has_next) S.a_ready(nxt);
;             if constexpr (SP2) {
;             PG8_LDB(B0, 0, 0); PG8_LDB(B1, 0, 1); PG8_SCHED; PG8_LDA(At, 0, 0); PG8_STAGE(PG8_SA(1, 1), a1 + hstepA, voffA);
;             PG8_WAIT_V(8); PG8_WAIT_L(0); PG8_BAR; PG8_MMA(0, 0, At, B0); PG8_MMA(0, 1, At, B1); PG8_BAR; PG8_SCHED;
;             PG8_LDA(At, 0, 1); PG8_STAGE(PG8_SB(0, 0), b2, voffB); PG8_STAGE(PG8_SB(0, 1), b2 + hstepB, voffB); PG8_STAGE(PG8_SA(0, 0), a2, voffA);
;             PG8_WAIT_V(8); PG8_WAIT_L(0); PG8_BAR; PG8_MMA(1, 0, At, B0); PG8_MMA(1, 1, At, B1); PG8_BAR; PG8_SCHED;
.LBB0_1360:
	s_add_u32 s16, s0, 0xfff80080
	s_addc_u32 s17, s1, -1
	s_add_i32 s42, 0, 0x10000
	s_cmp_eq_u32 s41, 12
	s_cselect_b32 s19, s5, s17
	s_cselect_b32 s18, s4, s16
	s_cselect_b32 s17, s11, s27
	s_cselect_b32 s16, s13, s15
	s_add_i32 s44, 0, 0x14000
	ds_read_b128 v[144:147], v252
	ds_read_b128 v[148:151], v252 offset:1024
	ds_read_b128 v[152:155], v252 offset:2048
	ds_read_b128 v[156:159], v252 offset:3072
	ds_read_b128 v[178:181], v253
	ds_read_b128 v[182:185], v253 offset:1024
	ds_read_b128 v[186:189], v253 offset:2048
	ds_read_b128 v[190:193], v253 offset:3072
	s_add_i32 m0, s23, 0xc000
	ds_read_b128 v[194:197], v143
	ds_read_b128 v[208:211], v143 offset:1024
	ds_read_b128 v[212:215], v143 offset:2048
	ds_read_b128 v[216:219], v143 offset:3072
	ds_read_b128 v[220:223], v143 offset:4096
	ds_read_b128 v[224:227], v143 offset:5120
	ds_read_b128 v[228:231], v143 offset:6144
	ds_read_b128 v[232:235], v143 offset:7168
	global_load_lds_dwordx4 v136, s[0:1]
	s_add_i32 m0, s23, 0xe000
	s_nop 0
	global_load_lds_dwordx4 v138, s[0:1]
	s_waitcnt vmcnt(8)
	s_waitcnt lgkmcnt(0)
	s_barrier
	s_setprio 1
	v_mfma_f32_16x16x32_bf16 v[126:129], v[144:147], v[194:197], v[126:129]
	v_mfma_f32_16x16x32_bf16 v[122:125], v[152:155], v[194:197], v[122:125]
	v_mfma_f32_16x16x32_bf16 v[118:121], v[144:147], v[212:215], v[118:121]
	v_mfma_f32_16x16x32_bf16 v[114:117], v[152:155], v[212:215], v[114:117]
	v_mfma_f32_16x16x32_bf16 v[102:105], v[144:147], v[220:223], v[102:105]
	v_mfma_f32_16x16x32_bf16 v[98:101], v[152:155], v[220:223], v[98:101]
	v_mfma_f32_16x16x32_bf16 v[86:89], v[144:147], v[228:231], v[86:89]
	v_mfma_f32_16x16x32_bf16 v[82:85], v[152:155], v[228:231], v[82:85]
	s_setprio 0
	s_setprio 1
	v_mfma_f32_16x16x32_bf16 v[126:129], v[148:151], v[208:211], v[126:129]
	v_mfma_f32_16x16x32_bf16 v[122:125], v[156:159], v[208:211], v[122:125]
	v_mfma_f32_16x16x32_bf16 v[118:121], v[148:151], v[216:219], v[118:121]
	v_mfma_f32_16x16x32_bf16 v[114:117], v[156:159], v[216:219], v[114:117]
	v_mfma_f32_16x16x32_bf16 v[102:105], v[148:151], v[224:227], v[102:105]
	v_mfma_f32_16x16x32_bf16 v[98:101], v[156:159], v[224:227], v[98:101]
	v_mfma_f32_16x16x32_bf16 v[86:89], v[148:151], v[232:235], v[86:89]
	v_mfma_f32_16x16x32_bf16 v[82:85], v[156:159], v[232:235], v[82:85]
	s_setprio 0
	s_setprio 1
	v_mfma_f32_16x16x32_bf16 v[110:113], v[178:181], v[194:197], v[110:113]
	v_mfma_f32_16x16x32_bf16 v[106:109], v[186:189], v[194:197], v[106:109]
	v_mfma_f32_16x16x32_bf16 v[94:97], v[178:181], v[212:215], v[94:97]
	v_mfma_f32_16x16x32_bf16 v[90:93], v[186:189], v[212:215], v[90:93]
	v_mfma_f32_16x16x32_bf16 v[78:81], v[178:181], v[220:223], v[78:81]
	v_mfma_f32_16x16x32_bf16 v[74:77], v[186:189], v[220:223], v[74:77]
	v_mfma_f32_16x16x32_bf16 v[70:73], v[178:181], v[228:231], v[70:73]
	v_mfma_f32_16x16x32_bf16 v[66:69], v[186:189], v[228:231], v[66:69]
	s_setprio 0
	s_setprio 1
	v_mfma_f32_16x16x32_bf16 v[110:113], v[182:185], v[208:211], v[110:113]
	v_mfma_f32_16x16x32_bf16 v[106:109], v[190:193], v[208:211], v[106:109]
	v_mfma_f32_16x16x32_bf16 v[94:97], v[182:185], v[216:219], v[94:97]
	v_mfma_f32_16x16x32_bf16 v[90:93], v[190:193], v[216:219], v[90:93]
	v_mfma_f32_16x16x32_bf16 v[78:81], v[182:185], v[224:227], v[78:81]
	v_mfma_f32_16x16x32_bf16 v[74:77], v[190:193], v[224:227], v[74:77]
	v_mfma_f32_16x16x32_bf16 v[70:73], v[182:185], v[232:235], v[70:73]
	v_mfma_f32_16x16x32_bf16 v[66:69], v[190:193], v[232:235], v[66:69]
	s_setprio 0
	s_barrier
	s_add_i32 s42, s42, s22
	s_mov_b32 m0, s42
	ds_read_b128 v[194:197], v143 offset:16384
	ds_read_b128 v[208:211], v143 offset:17408
	ds_read_b128 v[212:215], v143 offset:18432
	ds_read_b128 v[216:219], v143 offset:19456
	ds_read_b128 v[220:223], v143 offset:20480
	ds_read_b128 v[224:227], v143 offset:21504
	ds_read_b128 v[228:231], v143 offset:22528
	ds_read_b128 v[232:235], v143 offset:23552
	global_load_lds_dwordx4 v64, s[16:17]
	s_add_i32 m0, s42, 0x2000
	s_add_u32 s42, s16, 0x80000
	s_addc_u32 s43, s17, 0
	s_add_i32 s44, s44, s22
	global_load_lds_dwordx4 v130, s[16:17]
	s_mov_b32 m0, s44
	s_mov_b64 s[100:101], s[18:19]
	global_load_lds_dwordx4 v64, s[42:43]
	s_add_i32 m0, s44, 0x2000
	s_nop 0
	global_load_lds_dwordx4 v130, s[42:43]
	s_mov_b32 m0, s23
	s_nop 0
	global_load_lds_dwordx4 v134, s[18:19]
	s_mov_b32 m0, s24
	s_nop 0
	global_load_lds_dwordx4 v132, s[18:19]
	s_waitcnt vmcnt(8)
	s_waitcnt lgkmcnt(0)
	s_barrier
	s_setprio 1
	v_mfma_f32_16x16x32_bf16 v[60:63], v[144:147], v[194:197], v[60:63]
	v_mfma_f32_16x16x32_bf16 v[56:59], v[152:155], v[194:197], v[56:59]
	v_mfma_f32_16x16x32_bf16 v[52:55], v[144:147], v[212:215], v[52:55]
	v_mfma_f32_16x16x32_bf16 v[48:51], v[152:155], v[212:215], v[48:51]
	v_mfma_f32_16x16x32_bf16 v[36:39], v[144:147], v[220:223], v[36:39]
	v_mfma_f32_16x16x32_bf16 v[32:35], v[152:155], v[220:223], v[32:35]
	v_mfma_f32_16x16x32_bf16 v[20:23], v[144:147], v[228:231], v[20:23]
	v_mfma_f32_16x16x32_bf16 v[16:19], v[152:155], v[228:231], v[16:19]
	s_setprio 0
	s_setprio 1
	v_mfma_f32_16x16x32_bf16 v[60:63], v[148:151], v[208:211], v[60:63]
	v_mfma_f32_16x16x32_bf16 v[56:59], v[156:159], v[208:211], v[56:59]
	v_mfma_f32_16x16x32_bf16 v[52:55], v[148:151], v[216:219], v[52:55]
	v_mfma_f32_16x16x32_bf16 v[48:51], v[156:159], v[216:219], v[48:51]
	v_mfma_f32_16x16x32_bf16 v[36:39], v[148:151], v[224:227], v[36:39]
	v_mfma_f32_16x16x32_bf16 v[32:35], v[156:159], v[224:227], v[32:35]
	v_mfma_f32_16x16x32_bf16 v[20:23], v[148:151], v[232:235], v[20:23]
	v_mfma_f32_16x16x32_bf16 v[16:19], v[156:159], v[232:235], v[16:19]
	s_setprio 0
	s_setprio 1
	v_mfma_f32_16x16x32_bf16 v[44:47], v[178:181], v[194:197], v[44:47]
	v_mfma_f32_16x16x32_bf16 v[40:43], v[186:189], v[194:197], v[40:43]
	v_mfma_f32_16x16x32_bf16 v[28:31], v[178:181], v[212:215], v[28:31]
	v_mfma_f32_16x16x32_bf16 v[24:27], v[186:189], v[212:215], v[24:27]
	v_mfma_f32_16x16x32_bf16 v[12:15], v[178:181], v[220:223], v[12:15]
	v_mfma_f32_16x16x32_bf16 v[8:11], v[186:189], v[220:223], v[8:11]
	v_mfma_f32_16x16x32_bf16 v[4:7], v[178:181], v[228:231], v[4:7]
	v_mfma_f32_16x16x32_bf16 v[0:3], v[186:189], v[228:231], v[0:3]
	s_setprio 0
	s_setprio 1
	v_mfma_f32_16x16x32_bf16 v[44:47], v[182:185], v[208:211], v[44:47]
	v_mfma_f32_16x16x32_bf16 v[40:43], v[190:193], v[208:211], v[40:43]
	v_mfma_f32_16x16x32_bf16 v[28:31], v[182:185], v[216:219], v[28:31]
	v_mfma_f32_16x16x32_bf16 v[24:27], v[190:193], v[216:219], v[24:27]
	v_mfma_f32_16x16x32_bf16 v[12:15], v[182:185], v[224:227], v[12:15]
	v_mfma_f32_16x16x32_bf16 v[8:11], v[190:193], v[224:227], v[8:11]
	v_mfma_f32_16x16x32_bf16 v[4:7], v[182:185], v[232:235], v[4:7]
	v_mfma_f32_16x16x32_bf16 v[0:3], v[190:193], v[232:235], v[0:3]
	s_setprio 0
	s_barrier
; #define PG8_STAGE(bufoff, gbase, voff) do { _Pragma("unroll") for (int _i = 0; _i < 2; ++_i) \
;         __builtin_amdgcn_global_load_lds((const unsigned*)((const char*)(gbase) + (voff)[_i]), (PG8_LAS unsigned*)(lds + (bufoff) + ldsw + _i * 8192), 16, 0, 0); } while (0)
; #define PG8_LDA(dst, b, h) do { _Pragma("unroll") for (int m = 0; m < 4; ++m) _Pragma("unroll") for (int k = 0; k < 2; ++k) dst[m][k] = *(const PG8_LAS bf16x8*)(lds + PG8_SA(b, h) + aoff + m * 2048 + k * 1024); } while (0)
; #define PG8_LDB(dst, b, h) do { _Pragma("unroll") for (int n = 0; n < 2; ++n) _Pragma("unroll") for (int k = 0; k < 2; ++k) dst[n][k] = *(const PG8_LAS bf16x8*)(lds + PG8_SB(b, h) + boff + n * 2048 + k * 1024); } while (0)
; #define PG8_MMA(ai, bj, At, Bt) do { __builtin_amdgcn_s_setprio(1); _Pragma("unroll") for (int m = 0; m < 4; ++m) _Pragma("unroll") for (int n = 0; n < 2; ++n) _Pragma("unroll") for (int k = 0; k < 2; ++k) \
;         acc[ai][bj][m][n] = __builtin_amdgcn_mfma_f32_16x16x32_bf16(Bt[n][k], At[m][k], acc[ai][bj][m][n], 0, 0, 0); __builtin_amdgcn_s_setprio(0); } while (0)
; #define PG8_WAIT_V(n) asm volatile("s_waitcnt vmcnt(" #n ")" ::: "memory")
; #define PG8_WAIT_L(n) asm volatile("s_waitcnt lgkmcnt(" #n ")" ::: "memory")
; #define PG8_BAR __builtin_amdgcn_s_barrier()
; #define PG8_SCHED __builtin_amdgcn_sched_barrier(0)
; template <class Epi, class Sched, bool ALIGN_EPI = false, bool SP2 = false>
; __device__ __forceinline__ void gemm_phase(PG8_LAS unsigned char* lds, const Gemm g, const Sched& S, const Epi& E, const int wave0) {
;     ...
;         for (int t = 0; t < nt; t += 2) {
;             const bool last = (t == nt - 2);
;             const char* a1 = cA + (size_t)(t + 1) * kstep;
;             const char* a2 = last ? nA : cA + (size_t)(t + 2) * kstep; const char* b2 = last ? nB : cB + (size_t)(t + 2) * kstep;
;     ...
;             PG8_LDB(B0, 1, 0); PG8_LDB(B1, 1, 1); PG8_SCHED; PG8_LDA(At, 1, 0); PG8_STAGE(PG8_SA(0, 1), a2 + hstepA, voffA);
;             PG8_WAIT_V(8); PG8_WAIT_L(0); PG8_BAR; PG8_MMA(0, 0, At, B0); PG8_MMA(0, 1, At, B1); PG8_BAR; PG8_SCHED;
;             PG8_LDA(At, 1, 1); PG8_STAGE(PG8_SB(1, 0), b3, voffB); PG8_STAGE(PG8_SB(1, 1), b3 + hstepB, voffB); PG8_STAGE(PG8_SA(1, 0), a3, voffA);
;             PG8_WAIT_V(8); PG8_WAIT_L(0); PG8_BAR; PG8_MMA(1, 0, At, B0); PG8_MMA(1, 1, At, B1); PG8_BAR; PG8_SCHED;
	s_add_i32 s42, 0, 0x18000
	s_add_i32 s43, 0, 0x1c000
	ds_read_b128 v[144:147], v254
	ds_read_b128 v[148:151], v254 offset:1024
	ds_read_b128 v[152:155], v254 offset:2048
	ds_read_b128 v[156:159], v254 offset:3072
	ds_read_b128 v[178:181], v255
	ds_read_b128 v[182:185], v255 offset:1024
	ds_read_b128 v[186:189], v255 offset:2048
	ds_read_b128 v[190:193], v255 offset:3072
	s_add_u32 s18, s18, 0x80000
	s_addc_u32 s19, s19, 0
	s_mov_b32 m0, s25
	ds_read_b128 v[194:197], v143 offset:32768
	ds_read_b128 v[208:211], v143 offset:33792
	ds_read_b128 v[212:215], v143 offset:34816
	ds_read_b128 v[216:219], v143 offset:35840
	ds_read_b128 v[220:223], v143 offset:36864
	ds_read_b128 v[224:227], v143 offset:37888
	ds_read_b128 v[228:231], v143 offset:38912
	ds_read_b128 v[232:235], v143 offset:39936
	global_load_lds_dwordx4 v134, s[18:19]
	s_mov_b32 m0, s33
	s_nop 0
	global_load_lds_dwordx4 v132, s[18:19]
	s_waitcnt vmcnt(8)
	s_waitcnt lgkmcnt(0)
	s_barrier
	s_setprio 1
	v_mfma_f32_16x16x32_bf16 v[126:129], v[144:147], v[194:197], v[126:129]
	v_mfma_f32_16x16x32_bf16 v[122:125], v[152:155], v[194:197], v[122:125]
	v_mfma_f32_16x16x32_bf16 v[118:121], v[144:147], v[212:215], v[118:121]
	v_mfma_f32_16x16x32_bf16 v[114:117], v[152:155], v[212:215], v[114:117]
	v_mfma_f32_16x16x32_bf16 v[102:105], v[144:147], v[220:223], v[102:105]
	v_mfma_f32_16x16x32_bf16 v[98:101], v[152:155], v[220:223], v[98:101]
	v_mfma_f32_16x16x32_bf16 v[86:89], v[144:147], v[228:231], v[86:89]
	v_mfma_f32_16x16x32_bf16 v[82:85], v[152:155], v[228:231], v[82:85]
	s_setprio 0
	s_setprio 1
	v_mfma_f32_16x16x32_bf16 v[126:129], v[148:151], v[208:211], v[126:129]
	v_mfma_f32_16x16x32_bf16 v[122:125], v[156:159], v[208:211], v[122:125]
	v_mfma_f32_16x16x32_bf16 v[118:121], v[148:151], v[216:219], v[118:121]
	v_mfma_f32_16x16x32_bf16 v[114:117], v[156:159], v[216:219], v[114:117]
	v_mfma_f32_16x16x32_bf16 v[102:105], v[148:151], v[224:227], v[102:105]
	v_mfma_f32_16x16x32_bf16 v[98:101], v[156:159], v[224:227], v[98:101]
	v_mfma_f32_16x16x32_bf16 v[86:89], v[148:151], v[232:235], v[86:89]
	v_mfma_f32_16x16x32_bf16 v[82:85], v[156:159], v[232:235], v[82:85]
	s_setprio 0
	s_setprio 1
	v_mfma_f32_16x16x32_bf16 v[110:113], v[178:181], v[194:197], v[110:113]
	v_mfma_f32_16x16x32_bf16 v[106:109], v[186:189], v[194:197], v[106:109]
	v_mfma_f32_16x16x32_bf16 v[94:97], v[178:181], v[212:215], v[94:97]
	v_mfma_f32_16x16x32_bf16 v[90:93], v[186:189], v[212:215], v[90:93]
	v_mfma_f32_16x16x32_bf16 v[78:81], v[178:181], v[220:223], v[78:81]
	v_mfma_f32_16x16x32_bf16 v[74:77], v[186:189], v[220:223], v[74:77]
	v_mfma_f32_16x16x32_bf16 v[70:73], v[178:181], v[228:231], v[70:73]
	v_mfma_f32_16x16x32_bf16 v[66:69], v[186:189], v[228:231], v[66:69]
	s_setprio 0
	s_setprio 1
	v_mfma_f32_16x16x32_bf16 v[110:113], v[182:185], v[208:211], v[110:113]
	v_mfma_f32_16x16x32_bf16 v[106:109], v[190:193], v[208:211], v[106:109]
	v_mfma_f32_16x16x32_bf16 v[94:97], v[182:185], v[216:219], v[94:97]
	v_mfma_f32_16x16x32_bf16 v[90:93], v[190:193], v[216:219], v[90:93]
	v_mfma_f32_16x16x32_bf16 v[78:81], v[182:185], v[224:227], v[78:81]
	v_mfma_f32_16x16x32_bf16 v[74:77], v[190:193], v[224:227], v[74:77]
	v_mfma_f32_16x16x32_bf16 v[70:73], v[182:185], v[232:235], v[70:73]
	v_mfma_f32_16x16x32_bf16 v[66:69], v[190:193], v[232:235], v[66:69]
	s_setprio 0
	s_barrier
	s_add_i32 s18, s42, s22
	s_add_u32 s46, s16, 0x80
	s_addc_u32 s47, s17, 0
	s_mov_b32 m0, s18
	ds_read_b128 v[194:197], v143 offset:49152
	ds_read_b128 v[208:211], v143 offset:50176
	ds_read_b128 v[212:215], v143 offset:51200
	ds_read_b128 v[216:219], v143 offset:52224
	ds_read_b128 v[220:223], v143 offset:53248
	ds_read_b128 v[224:227], v143 offset:54272
	ds_read_b128 v[228:231], v143 offset:55296
	ds_read_b128 v[232:235], v143 offset:56320
	global_load_lds_dwordx4 v64, s[46:47]
	s_add_i32 m0, s18, 0x2000
	s_add_u32 s16, s16, 0x80080
	s_addc_u32 s17, s17, 0
	s_add_i32 s18, s43, s22
	global_load_lds_dwordx4 v130, s[46:47]
	s_mov_b32 m0, s18
	s_nop 0
	global_load_lds_dwordx4 v64, s[16:17]
	s_add_i32 m0, s18, 0x2000
	s_nop 0
	global_load_lds_dwordx4 v130, s[16:17]
	s_add_u32 s100, s100, 0x80
	s_addc_u32 s101, s101, 0
	s_mov_b32 m0, s34
	s_nop 0
	global_load_lds_dwordx4 v134, s[100:101]
	s_mov_b32 m0, s35
	s_nop 0
	global_load_lds_dwordx4 v132, s[100:101]
	s_waitcnt vmcnt(8)
	s_waitcnt lgkmcnt(0)
	s_barrier
	s_setprio 1
	v_mfma_f32_16x16x32_bf16 v[60:63], v[144:147], v[194:197], v[60:63]
	v_mfma_f32_16x16x32_bf16 v[56:59], v[152:155], v[194:197], v[56:59]
	v_mfma_f32_16x16x32_bf16 v[52:55], v[144:147], v[212:215], v[52:55]
	v_mfma_f32_16x16x32_bf16 v[48:51], v[152:155], v[212:215], v[48:51]
	v_mfma_f32_16x16x32_bf16 v[36:39], v[144:147], v[220:223], v[36:39]
	v_mfma_f32_16x16x32_bf16 v[32:35], v[152:155], v[220:223], v[32:35]
	v_mfma_f32_16x16x32_bf16 v[20:23], v[144:147], v[228:231], v[20:23]
	v_mfma_f32_16x16x32_bf16 v[16:19], v[152:155], v[228:231], v[16:19]
	s_setprio 0
	s_setprio 1
	v_mfma_f32_16x16x32_bf16 v[60:63], v[148:151], v[208:211], v[60:63]
	v_mfma_f32_16x16x32_bf16 v[56:59], v[156:159], v[208:211], v[56:59]
	v_mfma_f32_16x16x32_bf16 v[52:55], v[148:151], v[216:219], v[52:55]
	v_mfma_f32_16x16x32_bf16 v[48:51], v[156:159], v[216:219], v[48:51]
	v_mfma_f32_16x16x32_bf16 v[36:39], v[148:151], v[224:227], v[36:39]
	v_mfma_f32_16x16x32_bf16 v[32:35], v[156:159], v[224:227], v[32:35]
	v_mfma_f32_16x16x32_bf16 v[20:23], v[148:151], v[232:235], v[20:23]
	v_mfma_f32_16x16x32_bf16 v[16:19], v[156:159], v[232:235], v[16:19]
	s_setprio 0
	s_setprio 1
	v_mfma_f32_16x16x32_bf16 v[44:47], v[178:181], v[194:197], v[44:47]
	v_mfma_f32_16x16x32_bf16 v[40:43], v[186:189], v[194:197], v[40:43]
	v_mfma_f32_16x16x32_bf16 v[28:31], v[178:181], v[212:215], v[28:31]
	v_mfma_f32_16x16x32_bf16 v[24:27], v[186:189], v[212:215], v[24:27]
	v_mfma_f32_16x16x32_bf16 v[12:15], v[178:181], v[220:223], v[12:15]
	v_mfma_f32_16x16x32_bf16 v[8:11], v[186:189], v[220:223], v[8:11]
	v_mfma_f32_16x16x32_bf16 v[4:7], v[178:181], v[228:231], v[4:7]
	v_mfma_f32_16x16x32_bf16 v[0:3], v[186:189], v[228:231], v[0:3]
	s_setprio 0
	s_setprio 1
	v_mfma_f32_16x16x32_bf16 v[44:47], v[182:185], v[208:211], v[44:47]
	v_mfma_f32_16x16x32_bf16 v[40:43], v[190:193], v[208:211], v[40:43]
	v_mfma_f32_16x16x32_bf16 v[28:31], v[182:185], v[216:219], v[28:31]
	v_mfma_f32_16x16x32_bf16 v[24:27], v[190:193], v[216:219], v[24:27]
	v_mfma_f32_16x16x32_bf16 v[12:15], v[182:185], v[224:227], v[12:15]
	v_mfma_f32_16x16x32_bf16 v[8:11], v[190:193], v[224:227], v[8:11]
	v_mfma_f32_16x16x32_bf16 v[4:7], v[182:185], v[232:235], v[4:7]
	v_mfma_f32_16x16x32_bf16 v[0:3], v[190:193], v[232:235], v[0:3]
	s_setprio 0
	s_barrier
	s_add_i32 s41, s41, 2
	s_add_u32 s0, s0, 0x100
	s_addc_u32 s1, s1, 0
	s_add_u32 s15, s15, 0x100
	s_addc_u32 s27, s27, 0
	s_cmp_gt_u32 s41, 13
	s_cbranch_scc0 .LBB0_1360
	s_mov_b64 s[46:47], 0x80
	s_and_b64 vcc, exec, s[8:9]
	s_cbranch_vccz .LBB0_1363
	s_barrier

; #define PG8_STAGE(bufoff, gbase, voff) do { _Pragma("unroll") for (int _i = 0; _i < 2; ++_i) \
;         __builtin_amdgcn_global_load_lds((const unsigned*)((const char*)(gbase) + (voff)[_i]), (PG8_LAS unsigned*)(lds + (bufoff) + ldsw + _i * 8192), 16, 0, 0); } while (0)
; #define PG8_LDA(dst, b, h) do { _Pragma("unroll") for (int m = 0; m < 4; ++m) _Pragma("unroll") for (int k = 0; k < 2; ++k) dst[m][k] = *(const PG8_LAS bf16x8*)(lds + PG8_SA(b, h) + aoff + m * 2048 + k * 1024); } while (0)
; #define PG8_LDB(dst, b, h) do { _Pragma("unroll") for (int n = 0; n < 2; ++n) _Pragma("unroll") for (int k = 0; k < 2; ++k) dst[n][k] = *(const PG8_LAS bf16x8*)(lds + PG8_SB(b, h) + boff + n * 2048 + k * 1024); } while (0)
; #define PG8_MMA(ai, bj, At, Bt) do { __builtin_amdgcn_s_setprio(1); _Pragma("unroll") for (int m = 0; m < 4; ++m) _Pragma("unroll") for (int n = 0; n < 2; ++n) _Pragma("unroll") for (int k = 0; k < 2; ++k) \
;         acc[ai][bj][m][n] = __builtin_amdgcn_mfma_f32_16x16x32_bf16(Bt[n][k], At[m][k], acc[ai][bj][m][n], 0, 0, 0); __builtin_amdgcn_s_setprio(0); } while (0)
; template <class Epi, class Sched, bool ALIGN_EPI = false, bool SP2 = false>
; __device__ __forceinline__ void gemm_phase(PG8_LAS unsigned char* lds, const Gemm g, const Sched& S, const Epi& E, const int wave0) {
;     ...
;         const char* nA = has_next ? (const char*)g.A + (size_t)nxt.z * g.zsA + (size_t)nxt.pm * tstepA + (size_t)nxt.k0 * 2 : cA; const char* nB = has_next ? (const char*)g.Bt + (size_t)nxt.z * g.zsB + (size_t)nxt.pn * tstepB + (size_t)nxt.k0 * 2 : cB;
;         for (int t = 0; t < nt; t += 2) {
;             const bool last = (t == nt - 2);
;             const char* a1 = cA + (size_t)(t + 1) * kstep;
;             const char* a2 = last ? nA : cA + (size_t)(t + 2) * kstep; const char* b2 = last ? nB : cB + (size_t)(t + 2) * kstep;
;     ...
;             PG8_LDB(B0, 0, 0); PG8_LDB(B1, 0, 1); PG8_SCHED; PG8_LDA(At, 0, 0); PG8_STAGE(PG8_SA(1, 1), a1 + hstepA, voffA);
;             PG8_WAIT_V(8); PG8_WAIT_L(0); PG8_BAR; PG8_MMA(0, 0, At, B0); PG8_MMA(0, 1, At, B1); PG8_BAR; PG8_SCHED;
;             PG8_LDA(At, 0, 1); PG8_STAGE(PG8_SB(0, 0), b2, voffB); PG8_STAGE(PG8_SB(0, 1), b2 + hstepB, voffB); PG8_STAGE(PG8_SA(0, 0), a2, voffA);
;             PG8_WAIT_V(8); PG8_WAIT_L(0); PG8_BAR; PG8_MMA(1, 0, At, B0); PG8_MMA(1, 1, At, B1); PG8_BAR; PG8_SCHED;
.LBB0_1571:
	s_add_u32 s16, s0, 0xfff80080
	s_addc_u32 s17, s1, -1
	s_add_i32 s46, 0, 0x10000
	s_cmp_eq_u32 s45, 28
	s_cselect_b32 s19, s9, s17
	s_cselect_b32 s18, s33, s16
	s_cselect_b32 s17, s7, s44
	s_cselect_b32 s16, s36, s37
	s_add_i32 s48, 0, 0x14000
	ds_read_b128 v[140:143], v252
	ds_read_b128 v[148:151], v252 offset:1024
	ds_read_b128 v[152:155], v252 offset:2048
	ds_read_b128 v[156:159], v252 offset:3072
	ds_read_b128 v[178:181], v253
	ds_read_b128 v[182:185], v253 offset:1024
	ds_read_b128 v[186:189], v253 offset:2048
	ds_read_b128 v[190:193], v253 offset:3072
	s_add_i32 m0, s15, 0xc000
	ds_read_b128 v[194:197], v147
	ds_read_b128 v[208:211], v147 offset:1024
	ds_read_b128 v[212:215], v147 offset:2048
	ds_read_b128 v[216:219], v147 offset:3072
	ds_read_b128 v[220:223], v147 offset:4096
	ds_read_b128 v[224:227], v147 offset:5120
	ds_read_b128 v[228:231], v147 offset:6144
	ds_read_b128 v[232:235], v147 offset:7168
	global_load_lds_dwordx4 v136, s[0:1]
	s_add_i32 m0, s15, 0xe000
	s_nop 0
	global_load_lds_dwordx4 v138, s[0:1]
	s_waitcnt vmcnt(8)
	s_waitcnt lgkmcnt(0)
	s_barrier
	s_setprio 1
	v_mfma_f32_16x16x32_bf16 v[126:129], v[140:143], v[194:197], v[126:129]
	v_mfma_f32_16x16x32_bf16 v[122:125], v[152:155], v[194:197], v[122:125]
	v_mfma_f32_16x16x32_bf16 v[110:113], v[140:143], v[212:215], v[110:113]
	v_mfma_f32_16x16x32_bf16 v[106:109], v[152:155], v[212:215], v[106:109]
	v_mfma_f32_16x16x32_bf16 v[94:97], v[140:143], v[220:223], v[94:97]
	v_mfma_f32_16x16x32_bf16 v[90:93], v[152:155], v[220:223], v[90:93]
	v_mfma_f32_16x16x32_bf16 v[78:81], v[140:143], v[228:231], v[78:81]
	v_mfma_f32_16x16x32_bf16 v[74:77], v[152:155], v[228:231], v[74:77]
	s_setprio 0
	s_setprio 1
	v_mfma_f32_16x16x32_bf16 v[126:129], v[148:151], v[208:211], v[126:129]
	v_mfma_f32_16x16x32_bf16 v[122:125], v[156:159], v[208:211], v[122:125]
	v_mfma_f32_16x16x32_bf16 v[110:113], v[148:151], v[216:219], v[110:113]
	v_mfma_f32_16x16x32_bf16 v[106:109], v[156:159], v[216:219], v[106:109]
	v_mfma_f32_16x16x32_bf16 v[94:97], v[148:151], v[224:227], v[94:97]
	v_mfma_f32_16x16x32_bf16 v[90:93], v[156:159], v[224:227], v[90:93]
	v_mfma_f32_16x16x32_bf16 v[78:81], v[148:151], v[232:235], v[78:81]
	v_mfma_f32_16x16x32_bf16 v[74:77], v[156:159], v[232:235], v[74:77]
	s_setprio 0
	s_setprio 1
	v_mfma_f32_16x16x32_bf16 v[118:121], v[178:181], v[194:197], v[118:121]
	v_mfma_f32_16x16x32_bf16 v[114:117], v[186:189], v[194:197], v[114:117]
	v_mfma_f32_16x16x32_bf16 v[102:105], v[178:181], v[212:215], v[102:105]
	v_mfma_f32_16x16x32_bf16 v[98:101], v[186:189], v[212:215], v[98:101]
	v_mfma_f32_16x16x32_bf16 v[86:89], v[178:181], v[220:223], v[86:89]
	v_mfma_f32_16x16x32_bf16 v[82:85], v[186:189], v[220:223], v[82:85]
	v_mfma_f32_16x16x32_bf16 v[70:73], v[178:181], v[228:231], v[70:73]
	v_mfma_f32_16x16x32_bf16 v[66:69], v[186:189], v[228:231], v[66:69]
	s_setprio 0
	s_setprio 1
	v_mfma_f32_16x16x32_bf16 v[118:121], v[182:185], v[208:211], v[118:121]
	v_mfma_f32_16x16x32_bf16 v[114:117], v[190:193], v[208:211], v[114:117]
	v_mfma_f32_16x16x32_bf16 v[102:105], v[182:185], v[216:219], v[102:105]
	v_mfma_f32_16x16x32_bf16 v[98:101], v[190:193], v[216:219], v[98:101]
	v_mfma_f32_16x16x32_bf16 v[86:89], v[182:185], v[224:227], v[86:89]
	v_mfma_f32_16x16x32_bf16 v[82:85], v[190:193], v[224:227], v[82:85]
	v_mfma_f32_16x16x32_bf16 v[70:73], v[182:185], v[232:235], v[70:73]
	v_mfma_f32_16x16x32_bf16 v[66:69], v[190:193], v[232:235], v[66:69]
	s_setprio 0
	s_barrier
	s_add_i32 s46, s46, s28
	s_mov_b32 m0, s46
	ds_read_b128 v[194:197], v147 offset:16384
	ds_read_b128 v[208:211], v147 offset:17408
	ds_read_b128 v[212:215], v147 offset:18432
	ds_read_b128 v[216:219], v147 offset:19456
	ds_read_b128 v[220:223], v147 offset:20480
	ds_read_b128 v[224:227], v147 offset:21504
	ds_read_b128 v[228:231], v147 offset:22528
	ds_read_b128 v[232:235], v147 offset:23552
	global_load_lds_dwordx4 v64, s[16:17]
	s_add_i32 m0, s46, 0x2000
	s_add_u32 s46, s16, 0x80000
	s_addc_u32 s47, s17, 0
	s_add_i32 s48, s48, s28
	global_load_lds_dwordx4 v130, s[16:17]
	s_mov_b32 m0, s48
	s_mov_b64 s[100:101], s[18:19]
	global_load_lds_dwordx4 v64, s[46:47]
	s_add_i32 m0, s48, 0x2000
	s_nop 0
	global_load_lds_dwordx4 v130, s[46:47]
	s_mov_b32 m0, s15
	s_nop 0
	global_load_lds_dwordx4 v134, s[18:19]
	s_mov_b32 m0, s27
	s_nop 0
	global_load_lds_dwordx4 v132, s[18:19]
	s_waitcnt vmcnt(8)
	s_waitcnt lgkmcnt(0)
	s_barrier
	s_setprio 1
	v_mfma_f32_16x16x32_bf16 v[60:63], v[140:143], v[194:197], v[60:63]
	v_mfma_f32_16x16x32_bf16 v[56:59], v[152:155], v[194:197], v[56:59]
	v_mfma_f32_16x16x32_bf16 v[44:47], v[140:143], v[212:215], v[44:47]
	v_mfma_f32_16x16x32_bf16 v[40:43], v[152:155], v[212:215], v[40:43]
	v_mfma_f32_16x16x32_bf16 v[28:31], v[140:143], v[220:223], v[28:31]
	v_mfma_f32_16x16x32_bf16 v[24:27], v[152:155], v[220:223], v[24:27]
	v_mfma_f32_16x16x32_bf16 v[12:15], v[140:143], v[228:231], v[12:15]
	v_mfma_f32_16x16x32_bf16 v[8:11], v[152:155], v[228:231], v[8:11]
	s_setprio 0
	s_setprio 1
	v_mfma_f32_16x16x32_bf16 v[60:63], v[148:151], v[208:211], v[60:63]
	v_mfma_f32_16x16x32_bf16 v[56:59], v[156:159], v[208:211], v[56:59]
	v_mfma_f32_16x16x32_bf16 v[44:47], v[148:151], v[216:219], v[44:47]
	v_mfma_f32_16x16x32_bf16 v[40:43], v[156:159], v[216:219], v[40:43]
	v_mfma_f32_16x16x32_bf16 v[28:31], v[148:151], v[224:227], v[28:31]
	v_mfma_f32_16x16x32_bf16 v[24:27], v[156:159], v[224:227], v[24:27]
	v_mfma_f32_16x16x32_bf16 v[12:15], v[148:151], v[232:235], v[12:15]
	v_mfma_f32_16x16x32_bf16 v[8:11], v[156:159], v[232:235], v[8:11]
	s_setprio 0
	s_setprio 1
	v_mfma_f32_16x16x32_bf16 v[52:55], v[178:181], v[194:197], v[52:55]
	v_mfma_f32_16x16x32_bf16 v[48:51], v[186:189], v[194:197], v[48:51]
	v_mfma_f32_16x16x32_bf16 v[36:39], v[178:181], v[212:215], v[36:39]
	v_mfma_f32_16x16x32_bf16 v[32:35], v[186:189], v[212:215], v[32:35]
	v_mfma_f32_16x16x32_bf16 v[20:23], v[178:181], v[220:223], v[20:23]
	v_mfma_f32_16x16x32_bf16 v[16:19], v[186:189], v[220:223], v[16:19]
	v_mfma_f32_16x16x32_bf16 v[4:7], v[178:181], v[228:231], v[4:7]
	v_mfma_f32_16x16x32_bf16 v[0:3], v[186:189], v[228:231], v[0:3]
	s_setprio 0
	s_setprio 1
	v_mfma_f32_16x16x32_bf16 v[52:55], v[182:185], v[208:211], v[52:55]
	v_mfma_f32_16x16x32_bf16 v[48:51], v[190:193], v[208:211], v[48:51]
	v_mfma_f32_16x16x32_bf16 v[36:39], v[182:185], v[216:219], v[36:39]
	v_mfma_f32_16x16x32_bf16 v[32:35], v[190:193], v[216:219], v[32:35]
	v_mfma_f32_16x16x32_bf16 v[20:23], v[182:185], v[224:227], v[20:23]
	v_mfma_f32_16x16x32_bf16 v[16:19], v[190:193], v[224:227], v[16:19]
	v_mfma_f32_16x16x32_bf16 v[4:7], v[182:185], v[232:235], v[4:7]
	v_mfma_f32_16x16x32_bf16 v[0:3], v[190:193], v[232:235], v[0:3]
	s_setprio 0
	s_barrier
; #define PG8_STAGE(bufoff, gbase, voff) do { _Pragma("unroll") for (int _i = 0; _i < 2; ++_i) \
;         __builtin_amdgcn_global_load_lds((const unsigned*)((const char*)(gbase) + (voff)[_i]), (PG8_LAS unsigned*)(lds + (bufoff) + ldsw + _i * 8192), 16, 0, 0); } while (0)
; #define PG8_LDA(dst, b, h) do { _Pragma("unroll") for (int m = 0; m < 4; ++m) _Pragma("unroll") for (int k = 0; k < 2; ++k) dst[m][k] = *(const PG8_LAS bf16x8*)(lds + PG8_SA(b, h) + aoff + m * 2048 + k * 1024); } while (0)
; #define PG8_LDB(dst, b, h) do { _Pragma("unroll") for (int n = 0; n < 2; ++n) _Pragma("unroll") for (int k = 0; k < 2; ++k) dst[n][k] = *(const PG8_LAS bf16x8*)(lds + PG8_SB(b, h) + boff + n * 2048 + k * 1024); } while (0)
; #define PG8_MMA(ai, bj, At, Bt) do { __builtin_amdgcn_s_setprio(1); _Pragma("unroll") for (int m = 0; m < 4; ++m) _Pragma("unroll") for (int n = 0; n < 2; ++n) _Pragma("unroll") for (int k = 0; k < 2; ++k) \
;         acc[ai][bj][m][n] = __builtin_amdgcn_mfma_f32_16x16x32_bf16(Bt[n][k], At[m][k], acc[ai][bj][m][n], 0, 0, 0); __builtin_amdgcn_s_setprio(0); } while (0)
; #define PG8_WAIT_V(n) asm volatile("s_waitcnt vmcnt(" #n ")" ::: "memory")
; #define PG8_WAIT_L(n) asm volatile("s_waitcnt lgkmcnt(" #n ")" ::: "memory")
; #define PG8_BAR __builtin_amdgcn_s_barrier()
; #define PG8_SCHED __builtin_amdgcn_sched_barrier(0)
; template <class Epi, class Sched, bool ALIGN_EPI = false, bool SP2 = false>
; __device__ __forceinline__ void gemm_phase(PG8_LAS unsigned char* lds, const Gemm g, const Sched& S, const Epi& E, const int wave0) {
;     ...
;         for (int t = 0; t < nt; t += 2) {
;             const bool last = (t == nt - 2);
;             const char* a1 = cA + (size_t)(t + 1) * kstep;
;             const char* a2 = last ? nA : cA + (size_t)(t + 2) * kstep; const char* b2 = last ? nB : cB + (size_t)(t + 2) * kstep;
;     ...
;             PG8_LDB(B0, 1, 0); PG8_LDB(B1, 1, 1); PG8_SCHED; PG8_LDA(At, 1, 0); PG8_STAGE(PG8_SA(0, 1), a2 + hstepA, voffA);
;             PG8_WAIT_V(8); PG8_WAIT_L(0); PG8_BAR; PG8_MMA(0, 0, At, B0); PG8_MMA(0, 1, At, B1); PG8_BAR; PG8_SCHED;
;             PG8_LDA(At, 1, 1); PG8_STAGE(PG8_SB(1, 0), b3, voffB); PG8_STAGE(PG8_SB(1, 1), b3 + hstepB, voffB); PG8_STAGE(PG8_SA(1, 0), a3, voffA);
;             PG8_WAIT_V(8); PG8_WAIT_L(0); PG8_BAR; PG8_MMA(1, 0, At, B0); PG8_MMA(1, 1, At, B1); PG8_BAR; PG8_SCHED;
	s_add_i32 s46, 0, 0x18000
	s_add_i32 s47, 0, 0x1c000
	ds_read_b128 v[140:143], v254
	ds_read_b128 v[148:151], v254 offset:1024
	ds_read_b128 v[152:155], v254 offset:2048
	ds_read_b128 v[156:159], v254 offset:3072
	ds_read_b128 v[178:181], v255
	ds_read_b128 v[182:185], v255 offset:1024
	ds_read_b128 v[186:189], v255 offset:2048
	ds_read_b128 v[190:193], v255 offset:3072
	s_add_u32 s18, s18, 0x80000
	s_addc_u32 s19, s19, 0
	s_mov_b32 m0, s29
	ds_read_b128 v[194:197], v147 offset:32768
	ds_read_b128 v[208:211], v147 offset:33792
	ds_read_b128 v[212:215], v147 offset:34816
	ds_read_b128 v[216:219], v147 offset:35840
	ds_read_b128 v[220:223], v147 offset:36864
	ds_read_b128 v[224:227], v147 offset:37888
	ds_read_b128 v[228:231], v147 offset:38912
	ds_read_b128 v[232:235], v147 offset:39936
	global_load_lds_dwordx4 v134, s[18:19]
	s_mov_b32 m0, s30
	s_nop 0
	global_load_lds_dwordx4 v132, s[18:19]
	s_waitcnt vmcnt(8)
	s_waitcnt lgkmcnt(0)
	s_barrier
	s_setprio 1
	v_mfma_f32_16x16x32_bf16 v[126:129], v[140:143], v[194:197], v[126:129]
	v_mfma_f32_16x16x32_bf16 v[122:125], v[152:155], v[194:197], v[122:125]
	v_mfma_f32_16x16x32_bf16 v[110:113], v[140:143], v[212:215], v[110:113]
	v_mfma_f32_16x16x32_bf16 v[106:109], v[152:155], v[212:215], v[106:109]
	v_mfma_f32_16x16x32_bf16 v[94:97], v[140:143], v[220:223], v[94:97]
	v_mfma_f32_16x16x32_bf16 v[90:93], v[152:155], v[220:223], v[90:93]
	v_mfma_f32_16x16x32_bf16 v[78:81], v[140:143], v[228:231], v[78:81]
	v_mfma_f32_16x16x32_bf16 v[74:77], v[152:155], v[228:231], v[74:77]
	s_setprio 0
	s_setprio 1
	v_mfma_f32_16x16x32_bf16 v[126:129], v[148:151], v[208:211], v[126:129]
	v_mfma_f32_16x16x32_bf16 v[122:125], v[156:159], v[208:211], v[122:125]
	v_mfma_f32_16x16x32_bf16 v[110:113], v[148:151], v[216:219], v[110:113]
	v_mfma_f32_16x16x32_bf16 v[106:109], v[156:159], v[216:219], v[106:109]
	v_mfma_f32_16x16x32_bf16 v[94:97], v[148:151], v[224:227], v[94:97]
	v_mfma_f32_16x16x32_bf16 v[90:93], v[156:159], v[224:227], v[90:93]
	v_mfma_f32_16x16x32_bf16 v[78:81], v[148:151], v[232:235], v[78:81]
	v_mfma_f32_16x16x32_bf16 v[74:77], v[156:159], v[232:235], v[74:77]
	s_setprio 0
	s_setprio 1
	v_mfma_f32_16x16x32_bf16 v[118:121], v[178:181], v[194:197], v[118:121]
	v_mfma_f32_16x16x32_bf16 v[114:117], v[186:189], v[194:197], v[114:117]
	v_mfma_f32_16x16x32_bf16 v[102:105], v[178:181], v[212:215], v[102:105]
	v_mfma_f32_16x16x32_bf16 v[98:101], v[186:189], v[212:215], v[98:101]
	v_mfma_f32_16x16x32_bf16 v[86:89], v[178:181], v[220:223], v[86:89]
	v_mfma_f32_16x16x32_bf16 v[82:85], v[186:189], v[220:223], v[82:85]
	v_mfma_f32_16x16x32_bf16 v[70:73], v[178:181], v[228:231], v[70:73]
	v_mfma_f32_16x16x32_bf16 v[66:69], v[186:189], v[228:231], v[66:69]
	s_setprio 0
	s_setprio 1
	v_mfma_f32_16x16x32_bf16 v[118:121], v[182:185], v[208:211], v[118:121]
	v_mfma_f32_16x16x32_bf16 v[114:117], v[190:193], v[208:211], v[114:117]
	v_mfma_f32_16x16x32_bf16 v[102:105], v[182:185], v[216:219], v[102:105]
	v_mfma_f32_16x16x32_bf16 v[98:101], v[190:193], v[216:219], v[98:101]
	v_mfma_f32_16x16x32_bf16 v[86:89], v[182:185], v[224:227], v[86:89]
	v_mfma_f32_16x16x32_bf16 v[82:85], v[190:193], v[224:227], v[82:85]
	v_mfma_f32_16x16x32_bf16 v[70:73], v[182:185], v[232:235], v[70:73]
	v_mfma_f32_16x16x32_bf16 v[66:69], v[190:193], v[232:235], v[66:69]
	s_setprio 0
	s_barrier
	s_add_i32 s18, s46, s28
	s_add_u32 s50, s16, 0x80
	s_addc_u32 s51, s17, 0
	s_mov_b32 m0, s18
	ds_read_b128 v[194:197], v147 offset:49152
	ds_read_b128 v[208:211], v147 offset:50176
	ds_read_b128 v[212:215], v147 offset:51200
	ds_read_b128 v[216:219], v147 offset:52224
	ds_read_b128 v[220:223], v147 offset:53248
	ds_read_b128 v[224:227], v147 offset:54272
	ds_read_b128 v[228:231], v147 offset:55296
	ds_read_b128 v[232:235], v147 offset:56320
	global_load_lds_dwordx4 v64, s[50:51]
	s_add_i32 m0, s18, 0x2000
	s_add_u32 s16, s16, 0x80080
	s_addc_u32 s17, s17, 0
	s_add_i32 s18, s47, s28
	global_load_lds_dwordx4 v130, s[50:51]
	s_mov_b32 m0, s18
	s_nop 0
	global_load_lds_dwordx4 v64, s[16:17]
	s_add_i32 m0, s18, 0x2000
	s_nop 0
	global_load_lds_dwordx4 v130, s[16:17]
	s_add_u32 s100, s100, 0x80
	s_addc_u32 s101, s101, 0
	s_mov_b32 m0, s31
	s_nop 0
	global_load_lds_dwordx4 v134, s[100:101]
	s_mov_b32 m0, s34
	s_nop 0
	global_load_lds_dwordx4 v132, s[100:101]
	s_waitcnt vmcnt(8)
	s_waitcnt lgkmcnt(0)
	s_barrier
	s_setprio 1
	v_mfma_f32_16x16x32_bf16 v[60:63], v[140:143], v[194:197], v[60:63]
	v_mfma_f32_16x16x32_bf16 v[56:59], v[152:155], v[194:197], v[56:59]
	v_mfma_f32_16x16x32_bf16 v[44:47], v[140:143], v[212:215], v[44:47]
	v_mfma_f32_16x16x32_bf16 v[40:43], v[152:155], v[212:215], v[40:43]
	v_mfma_f32_16x16x32_bf16 v[28:31], v[140:143], v[220:223], v[28:31]
	v_mfma_f32_16x16x32_bf16 v[24:27], v[152:155], v[220:223], v[24:27]
	v_mfma_f32_16x16x32_bf16 v[12:15], v[140:143], v[228:231], v[12:15]
	v_mfma_f32_16x16x32_bf16 v[8:11], v[152:155], v[228:231], v[8:11]
	s_setprio 0
	s_setprio 1
	v_mfma_f32_16x16x32_bf16 v[60:63], v[148:151], v[208:211], v[60:63]
	v_mfma_f32_16x16x32_bf16 v[56:59], v[156:159], v[208:211], v[56:59]
	v_mfma_f32_16x16x32_bf16 v[44:47], v[148:151], v[216:219], v[44:47]
	v_mfma_f32_16x16x32_bf16 v[40:43], v[156:159], v[216:219], v[40:43]
	v_mfma_f32_16x16x32_bf16 v[28:31], v[148:151], v[224:227], v[28:31]
	v_mfma_f32_16x16x32_bf16 v[24:27], v[156:159], v[224:227], v[24:27]
	v_mfma_f32_16x16x32_bf16 v[12:15], v[148:151], v[232:235], v[12:15]
	v_mfma_f32_16x16x32_bf16 v[8:11], v[156:159], v[232:235], v[8:11]
	s_setprio 0
	s_setprio 1
	v_mfma_f32_16x16x32_bf16 v[52:55], v[178:181], v[194:197], v[52:55]
	v_mfma_f32_16x16x32_bf16 v[48:51], v[186:189], v[194:197], v[48:51]
	v_mfma_f32_16x16x32_bf16 v[36:39], v[178:181], v[212:215], v[36:39]
	v_mfma_f32_16x16x32_bf16 v[32:35], v[186:189], v[212:215], v[32:35]
	v_mfma_f32_16x16x32_bf16 v[20:23], v[178:181], v[220:223], v[20:23]
	v_mfma_f32_16x16x32_bf16 v[16:19], v[186:189], v[220:223], v[16:19]
	v_mfma_f32_16x16x32_bf16 v[4:7], v[178:181], v[228:231], v[4:7]
	v_mfma_f32_16x16x32_bf16 v[0:3], v[186:189], v[228:231], v[0:3]
	s_setprio 0
	s_setprio 1
	v_mfma_f32_16x16x32_bf16 v[52:55], v[182:185], v[208:211], v[52:55]
	v_mfma_f32_16x16x32_bf16 v[48:51], v[190:193], v[208:211], v[48:51]
	v_mfma_f32_16x16x32_bf16 v[36:39], v[182:185], v[216:219], v[36:39]
	v_mfma_f32_16x16x32_bf16 v[32:35], v[190:193], v[216:219], v[32:35]
	v_mfma_f32_16x16x32_bf16 v[20:23], v[182:185], v[224:227], v[20:23]
	v_mfma_f32_16x16x32_bf16 v[16:19], v[190:193], v[224:227], v[16:19]
	v_mfma_f32_16x16x32_bf16 v[4:7], v[182:185], v[232:235], v[4:7]
	v_mfma_f32_16x16x32_bf16 v[0:3], v[190:193], v[232:235], v[0:3]
	s_setprio 0
	s_barrier
	s_add_i32 s45, s45, 2
	s_add_u32 s0, s0, 0x100
	s_addc_u32 s1, s1, 0
	s_add_u32 s37, s37, 0x100
	s_addc_u32 s44, s44, 0
	s_cmp_gt_u32 s45, 29
	s_cbranch_scc0 .LBB0_1571
	s_mov_b64 s[50:51], 0x80
	s_and_b64 vcc, exec, s[4:5]
	s_cbranch_vccz .LBB0_1574
	s_barrier

; #define PG8_STAGE(bufoff, gbase, voff) do { _Pragma("unroll") for (int _i = 0; _i < 2; ++_i) \
;         __builtin_amdgcn_global_load_lds((const unsigned*)((const char*)(gbase) + (voff)[_i]), (PG8_LAS unsigned*)(lds + (bufoff) + ldsw + _i * 8192), 16, 0, 0); } while (0)
; #define PG8_LDA(dst, b, h) do { _Pragma("unroll") for (int m = 0; m < 4; ++m) _Pragma("unroll") for (int k = 0; k < 2; ++k) dst[m][k] = *(const PG8_LAS bf16x8*)(lds + PG8_SA(b, h) + aoff + m * 2048 + k * 1024); } while (0)
; #define PG8_LDB(dst, b, h) do { _Pragma("unroll") for (int n = 0; n < 2; ++n) _Pragma("unroll") for (int k = 0; k < 2; ++k) dst[n][k] = *(const PG8_LAS bf16x8*)(lds + PG8_SB(b, h) + boff + n * 2048 + k * 1024); } while (0)
; #define PG8_MMA(ai, bj, At, Bt) do { __builtin_amdgcn_s_setprio(1); _Pragma("unroll") for (int m = 0; m < 4; ++m) _Pragma("unroll") for (int n = 0; n < 2; ++n) _Pragma("unroll") for (int k = 0; k < 2; ++k) \
;         acc[ai][bj][m][n] = __builtin_amdgcn_mfma_f32_16x16x32_bf16(Bt[n][k], At[m][k], acc[ai][bj][m][n], 0, 0, 0); __builtin_amdgcn_s_setprio(0); } while (0)
; template <class Epi, class Sched, bool ALIGN_EPI = false, bool SP2 = false>
; __device__ __forceinline__ void gemm_phase(PG8_LAS unsigned char* lds, const Gemm g, const Sched& S, const Epi& E, const int wave0) {
;     ...
;         const char* nA = has_next ? (const char*)g.A + (size_t)nxt.z * g.zsA + (size_t)nxt.pm * tstepA + (size_t)nxt.k0 * 2 : cA; const char* nB = has_next ? (const char*)g.Bt + (size_t)nxt.z * g.zsB + (size_t)nxt.pn * tstepB + (size_t)nxt.k0 * 2 : cB;
;         for (int t = 0; t < nt; t += 2) {
;             const bool last = (t == nt - 2);
;             const char* a1 = cA + (size_t)(t + 1) * kstep;
;             const char* a2 = last ? nA : cA + (size_t)(t + 2) * kstep; const char* b2 = last ? nB : cB + (size_t)(t + 2) * kstep;
;     ...
;             PG8_LDB(B0, 0, 0); PG8_LDB(B1, 0, 1); PG8_SCHED; PG8_LDA(At, 0, 0); PG8_STAGE(PG8_SA(1, 1), a1 + hstepA, voffA);
;             PG8_WAIT_V(8); PG8_WAIT_L(0); PG8_BAR; PG8_MMA(0, 0, At, B0); PG8_MMA(0, 1, At, B1); PG8_BAR; PG8_SCHED;
;             PG8_LDA(At, 0, 1); PG8_STAGE(PG8_SB(0, 0), b2, voffB); PG8_STAGE(PG8_SB(0, 1), b2 + hstepB, voffB); PG8_STAGE(PG8_SA(0, 0), a2, voffA);
;             PG8_WAIT_V(8); PG8_WAIT_L(0); PG8_BAR; PG8_MMA(1, 0, At, B0); PG8_MMA(1, 1, At, B1); PG8_BAR; PG8_SCHED;
.LBB0_1685:
	s_add_u32 s16, s0, 0xffe00080
	s_addc_u32 s17, s1, -1
	s_add_i32 s43, 0, 0x10000
	s_cmpk_eq_i32 s42, 0x7c
	s_cselect_b32 s19, s11, s17
	s_cselect_b32 s18, s34, s16
	s_cselect_b32 s17, s9, s37
	s_cselect_b32 s16, s35, s36
	s_add_i32 s46, 0, 0x14000
	ds_read_b128 v[144:147], v252
	ds_read_b128 v[148:151], v252 offset:1024
	ds_read_b128 v[152:155], v252 offset:2048
	ds_read_b128 v[156:159], v252 offset:3072
	ds_read_b128 v[178:181], v253
	ds_read_b128 v[182:185], v253 offset:1024
	ds_read_b128 v[186:189], v253 offset:2048
	ds_read_b128 v[190:193], v253 offset:3072
	s_add_i32 m0, s21, 0xc000
	ds_read_b128 v[194:197], v143
	ds_read_b128 v[208:211], v143 offset:1024
	ds_read_b128 v[212:215], v143 offset:2048
	ds_read_b128 v[216:219], v143 offset:3072
	ds_read_b128 v[220:223], v143 offset:4096
	ds_read_b128 v[224:227], v143 offset:5120
	ds_read_b128 v[228:231], v143 offset:6144
	ds_read_b128 v[232:235], v143 offset:7168
	global_load_lds_dwordx4 v136, s[0:1]
	s_add_i32 m0, s21, 0xe000
	s_nop 0
	global_load_lds_dwordx4 v138, s[0:1]
	s_waitcnt vmcnt(8)
	s_waitcnt lgkmcnt(0)
	s_barrier
	s_setprio 1
	v_mfma_f32_16x16x32_bf16 v[126:129], v[144:147], v[194:197], v[126:129]
	v_mfma_f32_16x16x32_bf16 v[122:125], v[152:155], v[194:197], v[122:125]
	v_mfma_f32_16x16x32_bf16 v[118:121], v[144:147], v[212:215], v[118:121]
	v_mfma_f32_16x16x32_bf16 v[114:117], v[152:155], v[212:215], v[114:117]
	v_mfma_f32_16x16x32_bf16 v[102:105], v[144:147], v[220:223], v[102:105]
	v_mfma_f32_16x16x32_bf16 v[98:101], v[152:155], v[220:223], v[98:101]
	v_mfma_f32_16x16x32_bf16 v[86:89], v[144:147], v[228:231], v[86:89]
	v_mfma_f32_16x16x32_bf16 v[82:85], v[152:155], v[228:231], v[82:85]
	s_setprio 0
	s_setprio 1
	v_mfma_f32_16x16x32_bf16 v[126:129], v[148:151], v[208:211], v[126:129]
	v_mfma_f32_16x16x32_bf16 v[122:125], v[156:159], v[208:211], v[122:125]
	v_mfma_f32_16x16x32_bf16 v[118:121], v[148:151], v[216:219], v[118:121]
	v_mfma_f32_16x16x32_bf16 v[114:117], v[156:159], v[216:219], v[114:117]
	v_mfma_f32_16x16x32_bf16 v[102:105], v[148:151], v[224:227], v[102:105]
	v_mfma_f32_16x16x32_bf16 v[98:101], v[156:159], v[224:227], v[98:101]
	v_mfma_f32_16x16x32_bf16 v[86:89], v[148:151], v[232:235], v[86:89]
	v_mfma_f32_16x16x32_bf16 v[82:85], v[156:159], v[232:235], v[82:85]
	s_setprio 0
	s_setprio 1
	v_mfma_f32_16x16x32_bf16 v[110:113], v[178:181], v[194:197], v[110:113]
	v_mfma_f32_16x16x32_bf16 v[106:109], v[186:189], v[194:197], v[106:109]
	v_mfma_f32_16x16x32_bf16 v[94:97], v[178:181], v[212:215], v[94:97]
	v_mfma_f32_16x16x32_bf16 v[90:93], v[186:189], v[212:215], v[90:93]
	v_mfma_f32_16x16x32_bf16 v[78:81], v[178:181], v[220:223], v[78:81]
	v_mfma_f32_16x16x32_bf16 v[74:77], v[186:189], v[220:223], v[74:77]
	v_mfma_f32_16x16x32_bf16 v[70:73], v[178:181], v[228:231], v[70:73]
	v_mfma_f32_16x16x32_bf16 v[66:69], v[186:189], v[228:231], v[66:69]
	s_setprio 0
	s_setprio 1
	v_mfma_f32_16x16x32_bf16 v[110:113], v[182:185], v[208:211], v[110:113]
	v_mfma_f32_16x16x32_bf16 v[106:109], v[190:193], v[208:211], v[106:109]
	v_mfma_f32_16x16x32_bf16 v[94:97], v[182:185], v[216:219], v[94:97]
	v_mfma_f32_16x16x32_bf16 v[90:93], v[190:193], v[216:219], v[90:93]
	v_mfma_f32_16x16x32_bf16 v[78:81], v[182:185], v[224:227], v[78:81]
	v_mfma_f32_16x16x32_bf16 v[74:77], v[190:193], v[224:227], v[74:77]
	v_mfma_f32_16x16x32_bf16 v[70:73], v[182:185], v[232:235], v[70:73]
	v_mfma_f32_16x16x32_bf16 v[66:69], v[190:193], v[232:235], v[66:69]
	s_setprio 0
	s_barrier
	s_add_i32 s43, s43, s20
	s_mov_b32 m0, s43
	ds_read_b128 v[194:197], v143 offset:16384
	ds_read_b128 v[208:211], v143 offset:17408
	ds_read_b128 v[212:215], v143 offset:18432
	ds_read_b128 v[216:219], v143 offset:19456
	ds_read_b128 v[220:223], v143 offset:20480
	ds_read_b128 v[224:227], v143 offset:21504
	ds_read_b128 v[228:231], v143 offset:22528
	ds_read_b128 v[232:235], v143 offset:23552
	global_load_lds_dwordx4 v64, s[16:17]
	s_add_i32 m0, s43, 0x2000
	s_add_u32 s44, s16, 0x200000
	s_addc_u32 s45, s17, 0
	s_add_i32 s43, s46, s20
	global_load_lds_dwordx4 v130, s[16:17]
	s_mov_b32 m0, s43
	s_mov_b64 s[100:101], s[18:19]
	global_load_lds_dwordx4 v64, s[44:45]
	s_add_i32 m0, s43, 0x2000
	s_nop 0
	global_load_lds_dwordx4 v130, s[44:45]
	s_mov_b32 m0, s21
	s_nop 0
	global_load_lds_dwordx4 v134, s[18:19]
	s_mov_b32 m0, s25
	s_nop 0
	global_load_lds_dwordx4 v132, s[18:19]
	s_waitcnt vmcnt(8)
	s_waitcnt lgkmcnt(0)
	s_barrier
	s_setprio 1
	v_mfma_f32_16x16x32_bf16 v[60:63], v[144:147], v[194:197], v[60:63]
	v_mfma_f32_16x16x32_bf16 v[56:59], v[152:155], v[194:197], v[56:59]
	v_mfma_f32_16x16x32_bf16 v[52:55], v[144:147], v[212:215], v[52:55]
	v_mfma_f32_16x16x32_bf16 v[48:51], v[152:155], v[212:215], v[48:51]
	v_mfma_f32_16x16x32_bf16 v[36:39], v[144:147], v[220:223], v[36:39]
	v_mfma_f32_16x16x32_bf16 v[32:35], v[152:155], v[220:223], v[32:35]
	v_mfma_f32_16x16x32_bf16 v[20:23], v[144:147], v[228:231], v[20:23]
	v_mfma_f32_16x16x32_bf16 v[16:19], v[152:155], v[228:231], v[16:19]
	s_setprio 0
	s_setprio 1
	v_mfma_f32_16x16x32_bf16 v[60:63], v[148:151], v[208:211], v[60:63]
	v_mfma_f32_16x16x32_bf16 v[56:59], v[156:159], v[208:211], v[56:59]
	v_mfma_f32_16x16x32_bf16 v[52:55], v[148:151], v[216:219], v[52:55]
	v_mfma_f32_16x16x32_bf16 v[48:51], v[156:159], v[216:219], v[48:51]
	v_mfma_f32_16x16x32_bf16 v[36:39], v[148:151], v[224:227], v[36:39]
	v_mfma_f32_16x16x32_bf16 v[32:35], v[156:159], v[224:227], v[32:35]
	v_mfma_f32_16x16x32_bf16 v[20:23], v[148:151], v[232:235], v[20:23]
	v_mfma_f32_16x16x32_bf16 v[16:19], v[156:159], v[232:235], v[16:19]
	s_setprio 0
	s_setprio 1
	v_mfma_f32_16x16x32_bf16 v[44:47], v[178:181], v[194:197], v[44:47]
	v_mfma_f32_16x16x32_bf16 v[40:43], v[186:189], v[194:197], v[40:43]
	v_mfma_f32_16x16x32_bf16 v[28:31], v[178:181], v[212:215], v[28:31]
	v_mfma_f32_16x16x32_bf16 v[24:27], v[186:189], v[212:215], v[24:27]
	v_mfma_f32_16x16x32_bf16 v[12:15], v[178:181], v[220:223], v[12:15]
	v_mfma_f32_16x16x32_bf16 v[8:11], v[186:189], v[220:223], v[8:11]
	v_mfma_f32_16x16x32_bf16 v[4:7], v[178:181], v[228:231], v[4:7]
	v_mfma_f32_16x16x32_bf16 v[0:3], v[186:189], v[228:231], v[0:3]
	s_setprio 0
	s_setprio 1
	v_mfma_f32_16x16x32_bf16 v[44:47], v[182:185], v[208:211], v[44:47]
	v_mfma_f32_16x16x32_bf16 v[40:43], v[190:193], v[208:211], v[40:43]
	v_mfma_f32_16x16x32_bf16 v[28:31], v[182:185], v[216:219], v[28:31]
	v_mfma_f32_16x16x32_bf16 v[24:27], v[190:193], v[216:219], v[24:27]
	v_mfma_f32_16x16x32_bf16 v[12:15], v[182:185], v[224:227], v[12:15]
	v_mfma_f32_16x16x32_bf16 v[8:11], v[190:193], v[224:227], v[8:11]
	v_mfma_f32_16x16x32_bf16 v[4:7], v[182:185], v[232:235], v[4:7]
	v_mfma_f32_16x16x32_bf16 v[0:3], v[190:193], v[232:235], v[0:3]
	s_setprio 0
	s_barrier
; #define PG8_STAGE(bufoff, gbase, voff) do { _Pragma("unroll") for (int _i = 0; _i < 2; ++_i) \
;         __builtin_amdgcn_global_load_lds((const unsigned*)((const char*)(gbase) + (voff)[_i]), (PG8_LAS unsigned*)(lds + (bufoff) + ldsw + _i * 8192), 16, 0, 0); } while (0)
; #define PG8_LDA(dst, b, h) do { _Pragma("unroll") for (int m = 0; m < 4; ++m) _Pragma("unroll") for (int k = 0; k < 2; ++k) dst[m][k] = *(const PG8_LAS bf16x8*)(lds + PG8_SA(b, h) + aoff + m * 2048 + k * 1024); } while (0)
; #define PG8_LDB(dst, b, h) do { _Pragma("unroll") for (int n = 0; n < 2; ++n) _Pragma("unroll") for (int k = 0; k < 2; ++k) dst[n][k] = *(const PG8_LAS bf16x8*)(lds + PG8_SB(b, h) + boff + n * 2048 + k * 1024); } while (0)
; #define PG8_MMA(ai, bj, At, Bt) do { __builtin_amdgcn_s_setprio(1); _Pragma("unroll") for (int m = 0; m < 4; ++m) _Pragma("unroll") for (int n = 0; n < 2; ++n) _Pragma("unroll") for (int k = 0; k < 2; ++k) \
;         acc[ai][bj][m][n] = __builtin_amdgcn_mfma_f32_16x16x32_bf16(Bt[n][k], At[m][k], acc[ai][bj][m][n], 0, 0, 0); __builtin_amdgcn_s_setprio(0); } while (0)
; #define PG8_WAIT_V(n) asm volatile("s_waitcnt vmcnt(" #n ")" ::: "memory")
; #define PG8_WAIT_L(n) asm volatile("s_waitcnt lgkmcnt(" #n ")" ::: "memory")
; #define PG8_BAR __builtin_amdgcn_s_barrier()
; #define PG8_SCHED __builtin_amdgcn_sched_barrier(0)
; template <class Epi, class Sched, bool ALIGN_EPI = false, bool SP2 = false>
; __device__ __forceinline__ void gemm_phase(PG8_LAS unsigned char* lds, const Gemm g, const Sched& S, const Epi& E, const int wave0) {
;     ...
;         for (int t = 0; t < nt; t += 2) {
;             const bool last = (t == nt - 2);
;             const char* a1 = cA + (size_t)(t + 1) * kstep;
;             const char* a2 = last ? nA : cA + (size_t)(t + 2) * kstep; const char* b2 = last ? nB : cB + (size_t)(t + 2) * kstep;
;     ...
;             PG8_LDB(B0, 1, 0); PG8_LDB(B1, 1, 1); PG8_SCHED; PG8_LDA(At, 1, 0); PG8_STAGE(PG8_SA(0, 1), a2 + hstepA, voffA);
;             PG8_WAIT_V(8); PG8_WAIT_L(0); PG8_BAR; PG8_MMA(0, 0, At, B0); PG8_MMA(0, 1, At, B1); PG8_BAR; PG8_SCHED;
;             PG8_LDA(At, 1, 1); PG8_STAGE(PG8_SB(1, 0), b3, voffB); PG8_STAGE(PG8_SB(1, 1), b3 + hstepB, voffB); PG8_STAGE(PG8_SA(1, 0), a3, voffA);
;             PG8_WAIT_V(8); PG8_WAIT_L(0); PG8_BAR; PG8_MMA(1, 0, At, B0); PG8_MMA(1, 1, At, B1); PG8_BAR; PG8_SCHED;
	s_add_i32 s43, 0, 0x18000
	s_add_i32 s44, 0, 0x1c000
	ds_read_b128 v[144:147], v254
	ds_read_b128 v[148:151], v254 offset:1024
	ds_read_b128 v[152:155], v254 offset:2048
	ds_read_b128 v[156:159], v254 offset:3072
	ds_read_b128 v[178:181], v255
	ds_read_b128 v[182:185], v255 offset:1024
	ds_read_b128 v[186:189], v255 offset:2048
	ds_read_b128 v[190:193], v255 offset:3072
	s_add_u32 s18, s18, 0x200000
	s_addc_u32 s19, s19, 0
	s_mov_b32 m0, s26
	ds_read_b128 v[194:197], v143 offset:32768
	ds_read_b128 v[208:211], v143 offset:33792
	ds_read_b128 v[212:215], v143 offset:34816
	ds_read_b128 v[216:219], v143 offset:35840
	ds_read_b128 v[220:223], v143 offset:36864
	ds_read_b128 v[224:227], v143 offset:37888
	ds_read_b128 v[228:231], v143 offset:38912
	ds_read_b128 v[232:235], v143 offset:39936
	global_load_lds_dwordx4 v134, s[18:19]
	s_mov_b32 m0, s27
	s_nop 0
	global_load_lds_dwordx4 v132, s[18:19]
	s_waitcnt vmcnt(8)
	s_waitcnt lgkmcnt(0)
	s_barrier
	s_setprio 1
	v_mfma_f32_16x16x32_bf16 v[126:129], v[144:147], v[194:197], v[126:129]
	v_mfma_f32_16x16x32_bf16 v[122:125], v[152:155], v[194:197], v[122:125]
	v_mfma_f32_16x16x32_bf16 v[118:121], v[144:147], v[212:215], v[118:121]
	v_mfma_f32_16x16x32_bf16 v[114:117], v[152:155], v[212:215], v[114:117]
	v_mfma_f32_16x16x32_bf16 v[102:105], v[144:147], v[220:223], v[102:105]
	v_mfma_f32_16x16x32_bf16 v[98:101], v[152:155], v[220:223], v[98:101]
	v_mfma_f32_16x16x32_bf16 v[86:89], v[144:147], v[228:231], v[86:89]
	v_mfma_f32_16x16x32_bf16 v[82:85], v[152:155], v[228:231], v[82:85]
	s_setprio 0
	s_setprio 1
	v_mfma_f32_16x16x32_bf16 v[126:129], v[148:151], v[208:211], v[126:129]
	v_mfma_f32_16x16x32_bf16 v[122:125], v[156:159], v[208:211], v[122:125]
	v_mfma_f32_16x16x32_bf16 v[118:121], v[148:151], v[216:219], v[118:121]
	v_mfma_f32_16x16x32_bf16 v[114:117], v[156:159], v[216:219], v[114:117]
	v_mfma_f32_16x16x32_bf16 v[102:105], v[148:151], v[224:227], v[102:105]
	v_mfma_f32_16x16x32_bf16 v[98:101], v[156:159], v[224:227], v[98:101]
	v_mfma_f32_16x16x32_bf16 v[86:89], v[148:151], v[232:235], v[86:89]
	v_mfma_f32_16x16x32_bf16 v[82:85], v[156:159], v[232:235], v[82:85]
	s_setprio 0
	s_setprio 1
	v_mfma_f32_16x16x32_bf16 v[110:113], v[178:181], v[194:197], v[110:113]
	v_mfma_f32_16x16x32_bf16 v[106:109], v[186:189], v[194:197], v[106:109]
	v_mfma_f32_16x16x32_bf16 v[94:97], v[178:181], v[212:215], v[94:97]
	v_mfma_f32_16x16x32_bf16 v[90:93], v[186:189], v[212:215], v[90:93]
	v_mfma_f32_16x16x32_bf16 v[78:81], v[178:181], v[220:223], v[78:81]
	v_mfma_f32_16x16x32_bf16 v[74:77], v[186:189], v[220:223], v[74:77]
	v_mfma_f32_16x16x32_bf16 v[70:73], v[178:181], v[228:231], v[70:73]
	v_mfma_f32_16x16x32_bf16 v[66:69], v[186:189], v[228:231], v[66:69]
	s_setprio 0
	s_setprio 1
	v_mfma_f32_16x16x32_bf16 v[110:113], v[182:185], v[208:211], v[110:113]
	v_mfma_f32_16x16x32_bf16 v[106:109], v[190:193], v[208:211], v[106:109]
	v_mfma_f32_16x16x32_bf16 v[94:97], v[182:185], v[216:219], v[94:97]
	v_mfma_f32_16x16x32_bf16 v[90:93], v[190:193], v[216:219], v[90:93]
	v_mfma_f32_16x16x32_bf16 v[78:81], v[182:185], v[224:227], v[78:81]
	v_mfma_f32_16x16x32_bf16 v[74:77], v[190:193], v[224:227], v[74:77]
	v_mfma_f32_16x16x32_bf16 v[70:73], v[182:185], v[232:235], v[70:73]
	v_mfma_f32_16x16x32_bf16 v[66:69], v[190:193], v[232:235], v[66:69]
	s_setprio 0
	s_barrier
	s_add_i32 s18, s43, s20
	s_add_u32 s48, s16, 0x80
	s_addc_u32 s49, s17, 0
	s_mov_b32 m0, s18
	ds_read_b128 v[194:197], v143 offset:49152
	ds_read_b128 v[208:211], v143 offset:50176
	ds_read_b128 v[212:215], v143 offset:51200
	ds_read_b128 v[216:219], v143 offset:52224
	ds_read_b128 v[220:223], v143 offset:53248
	ds_read_b128 v[224:227], v143 offset:54272
	ds_read_b128 v[228:231], v143 offset:55296
	ds_read_b128 v[232:235], v143 offset:56320
	global_load_lds_dwordx4 v64, s[48:49]
	s_add_i32 m0, s18, 0x2000
	s_add_u32 s16, s16, 0x200080
	s_addc_u32 s17, s17, 0
	s_add_i32 s18, s44, s20
	global_load_lds_dwordx4 v130, s[48:49]
	s_mov_b32 m0, s18
	s_nop 0
	global_load_lds_dwordx4 v64, s[16:17]
	s_add_i32 m0, s18, 0x2000
	s_nop 0
	global_load_lds_dwordx4 v130, s[16:17]
	s_add_u32 s100, s100, 0x80
	s_addc_u32 s101, s101, 0
	s_mov_b32 m0, s28
	s_nop 0
	global_load_lds_dwordx4 v134, s[100:101]
	s_mov_b32 m0, s29
	s_nop 0
	global_load_lds_dwordx4 v132, s[100:101]
	s_waitcnt vmcnt(8)
	s_waitcnt lgkmcnt(0)
	s_barrier
	s_setprio 1
	v_mfma_f32_16x16x32_bf16 v[60:63], v[144:147], v[194:197], v[60:63]
	v_mfma_f32_16x16x32_bf16 v[56:59], v[152:155], v[194:197], v[56:59]
	v_mfma_f32_16x16x32_bf16 v[52:55], v[144:147], v[212:215], v[52:55]
	v_mfma_f32_16x16x32_bf16 v[48:51], v[152:155], v[212:215], v[48:51]
	v_mfma_f32_16x16x32_bf16 v[36:39], v[144:147], v[220:223], v[36:39]
	v_mfma_f32_16x16x32_bf16 v[32:35], v[152:155], v[220:223], v[32:35]
	v_mfma_f32_16x16x32_bf16 v[20:23], v[144:147], v[228:231], v[20:23]
	v_mfma_f32_16x16x32_bf16 v[16:19], v[152:155], v[228:231], v[16:19]
	s_setprio 0
	s_setprio 1
	v_mfma_f32_16x16x32_bf16 v[60:63], v[148:151], v[208:211], v[60:63]
	v_mfma_f32_16x16x32_bf16 v[56:59], v[156:159], v[208:211], v[56:59]
	v_mfma_f32_16x16x32_bf16 v[52:55], v[148:151], v[216:219], v[52:55]
	v_mfma_f32_16x16x32_bf16 v[48:51], v[156:159], v[216:219], v[48:51]
	v_mfma_f32_16x16x32_bf16 v[36:39], v[148:151], v[224:227], v[36:39]
	v_mfma_f32_16x16x32_bf16 v[32:35], v[156:159], v[224:227], v[32:35]
	v_mfma_f32_16x16x32_bf16 v[20:23], v[148:151], v[232:235], v[20:23]
	v_mfma_f32_16x16x32_bf16 v[16:19], v[156:159], v[232:235], v[16:19]
	s_setprio 0
	s_setprio 1
	v_mfma_f32_16x16x32_bf16 v[44:47], v[178:181], v[194:197], v[44:47]
	v_mfma_f32_16x16x32_bf16 v[40:43], v[186:189], v[194:197], v[40:43]
	v_mfma_f32_16x16x32_bf16 v[28:31], v[178:181], v[212:215], v[28:31]
	v_mfma_f32_16x16x32_bf16 v[24:27], v[186:189], v[212:215], v[24:27]
	v_mfma_f32_16x16x32_bf16 v[12:15], v[178:181], v[220:223], v[12:15]
	v_mfma_f32_16x16x32_bf16 v[8:11], v[186:189], v[220:223], v[8:11]
	v_mfma_f32_16x16x32_bf16 v[4:7], v[178:181], v[228:231], v[4:7]
	v_mfma_f32_16x16x32_bf16 v[0:3], v[186:189], v[228:231], v[0:3]
	s_setprio 0
	s_setprio 1
	v_mfma_f32_16x16x32_bf16 v[44:47], v[182:185], v[208:211], v[44:47]
	v_mfma_f32_16x16x32_bf16 v[40:43], v[190:193], v[208:211], v[40:43]
	v_mfma_f32_16x16x32_bf16 v[28:31], v[182:185], v[216:219], v[28:31]
	v_mfma_f32_16x16x32_bf16 v[24:27], v[190:193], v[216:219], v[24:27]
	v_mfma_f32_16x16x32_bf16 v[12:15], v[182:185], v[224:227], v[12:15]
	v_mfma_f32_16x16x32_bf16 v[8:11], v[190:193], v[224:227], v[8:11]
	v_mfma_f32_16x16x32_bf16 v[4:7], v[182:185], v[232:235], v[4:7]
	v_mfma_f32_16x16x32_bf16 v[0:3], v[190:193], v[232:235], v[0:3]
	s_setprio 0
	s_barrier
	s_add_i32 s42, s42, 2
	s_add_u32 s0, s0, 0x100
	s_addc_u32 s1, s1, 0
	s_add_u32 s36, s36, 0x100
	s_addc_u32 s37, s37, 0
	s_cmpk_gt_u32 s42, 0x7d
	s_cbranch_scc0 .LBB0_1685
	s_mov_b64 s[48:49], 0x80
	s_and_b64 vcc, exec, s[6:7]
	s_mov_b64 s[34:35], 0x45000
	s_cbranch_vccz .LBB0_1688
	s_barrier

; #define PG8_STAGE(bufoff, gbase, voff) do { _Pragma("unroll") for (int _i = 0; _i < 2; ++_i) \
;         __builtin_amdgcn_global_load_lds((const unsigned*)((const char*)(gbase) + (voff)[_i]), (PG8_LAS unsigned*)(lds + (bufoff) + ldsw + _i * 8192), 16, 0, 0); } while (0)
; #define PG8_LDA(dst, b, h) do { _Pragma("unroll") for (int m = 0; m < 4; ++m) _Pragma("unroll") for (int k = 0; k < 2; ++k) dst[m][k] = *(const PG8_LAS bf16x8*)(lds + PG8_SA(b, h) + aoff + m * 2048 + k * 1024); } while (0)
; #define PG8_LDB(dst, b, h) do { _Pragma("unroll") for (int n = 0; n < 2; ++n) _Pragma("unroll") for (int k = 0; k < 2; ++k) dst[n][k] = *(const PG8_LAS bf16x8*)(lds + PG8_SB(b, h) + boff + n * 2048 + k * 1024); } while (0)
; #define PG8_MMA(ai, bj, At, Bt) do { __builtin_amdgcn_s_setprio(1); _Pragma("unroll") for (int m = 0; m < 4; ++m) _Pragma("unroll") for (int n = 0; n < 2; ++n) _Pragma("unroll") for (int k = 0; k < 2; ++k) \
;         acc[ai][bj][m][n] = __builtin_amdgcn_mfma_f32_16x16x32_bf16(Bt[n][k], At[m][k], acc[ai][bj][m][n], 0, 0, 0); __builtin_amdgcn_s_setprio(0); } while (0)
; template <class Epi, class Sched, bool ALIGN_EPI = false, bool SP2 = false>
; __device__ __forceinline__ void gemm_phase(PG8_LAS unsigned char* lds, const Gemm g, const Sched& S, const Epi& E, const int wave0) {
;     ...
;         const char* nA = has_next ? (const char*)g.A + (size_t)nxt.z * g.zsA + (size_t)nxt.pm * tstepA + (size_t)nxt.k0 * 2 : cA; const char* nB = has_next ? (const char*)g.Bt + (size_t)nxt.z * g.zsB + (size_t)nxt.pn * tstepB + (size_t)nxt.k0 * 2 : cB;
;         for (int t = 0; t < nt; t += 2) {
;             const bool last = (t == nt - 2);
;             const char* a1 = cA + (size_t)(t + 1) * kstep;
;             const char* a2 = last ? nA : cA + (size_t)(t + 2) * kstep; const char* b2 = last ? nB : cB + (size_t)(t + 2) * kstep;
;     ...
;             PG8_LDB(B0, 0, 0); PG8_LDB(B1, 0, 1); PG8_SCHED; PG8_LDA(At, 0, 0); PG8_STAGE(PG8_SA(1, 1), a1 + hstepA, voffA);
;             PG8_WAIT_V(8); PG8_WAIT_L(0); PG8_BAR; PG8_MMA(0, 0, At, B0); PG8_MMA(0, 1, At, B1); PG8_BAR; PG8_SCHED;
;             PG8_LDA(At, 0, 1); PG8_STAGE(PG8_SB(0, 0), b2, voffB); PG8_STAGE(PG8_SB(0, 1), b2 + hstepB, voffB); PG8_STAGE(PG8_SA(0, 0), a2, voffA);
;             PG8_WAIT_V(8); PG8_WAIT_L(0); PG8_BAR; PG8_MMA(1, 0, At, B0); PG8_MMA(1, 1, At, B1); PG8_BAR; PG8_SCHED;
.LBB0_1702:
	s_add_u32 s18, s16, 0xffe00080
	s_addc_u32 s19, s17, -1
	s_add_i32 s44, 0, 0x10000
	s_cmp_eq_u32 s43, 12
	s_cselect_b32 s21, s9, s19
	s_cselect_b32 s20, s11, s18
	s_cselect_b32 s19, s13, s42
	s_cselect_b32 s18, s38, s39
	s_add_i32 s46, 0, 0x14000
	ds_read_b128 v[144:147], v252
	ds_read_b128 v[148:151], v252 offset:1024
	ds_read_b128 v[152:155], v252 offset:2048
	ds_read_b128 v[156:159], v252 offset:3072
	ds_read_b128 v[178:181], v253
	ds_read_b128 v[182:185], v253 offset:1024
	ds_read_b128 v[186:189], v253 offset:2048
	ds_read_b128 v[190:193], v253 offset:3072
	s_add_i32 m0, s28, 0xc000
	ds_read_b128 v[194:197], v143
	ds_read_b128 v[208:211], v143 offset:1024
	ds_read_b128 v[212:215], v143 offset:2048
	ds_read_b128 v[216:219], v143 offset:3072
	ds_read_b128 v[220:223], v143 offset:4096
	ds_read_b128 v[224:227], v143 offset:5120
	ds_read_b128 v[228:231], v143 offset:6144
	ds_read_b128 v[232:235], v143 offset:7168
	global_load_lds_dwordx4 v136, s[16:17]
	s_add_i32 m0, s28, 0xe000
	s_nop 0
	global_load_lds_dwordx4 v138, s[16:17]
	s_waitcnt vmcnt(8)
	s_waitcnt lgkmcnt(0)
	s_barrier
	s_setprio 1
	v_mfma_f32_16x16x32_bf16 v[126:129], v[144:147], v[194:197], v[126:129]
	v_mfma_f32_16x16x32_bf16 v[122:125], v[152:155], v[194:197], v[122:125]
	v_mfma_f32_16x16x32_bf16 v[118:121], v[144:147], v[212:215], v[118:121]
	v_mfma_f32_16x16x32_bf16 v[114:117], v[152:155], v[212:215], v[114:117]
	v_mfma_f32_16x16x32_bf16 v[102:105], v[144:147], v[220:223], v[102:105]
	v_mfma_f32_16x16x32_bf16 v[98:101], v[152:155], v[220:223], v[98:101]
	v_mfma_f32_16x16x32_bf16 v[86:89], v[144:147], v[228:231], v[86:89]
	v_mfma_f32_16x16x32_bf16 v[82:85], v[152:155], v[228:231], v[82:85]
	s_setprio 0
	s_setprio 1
	v_mfma_f32_16x16x32_bf16 v[126:129], v[148:151], v[208:211], v[126:129]
	v_mfma_f32_16x16x32_bf16 v[122:125], v[156:159], v[208:211], v[122:125]
	v_mfma_f32_16x16x32_bf16 v[118:121], v[148:151], v[216:219], v[118:121]
	v_mfma_f32_16x16x32_bf16 v[114:117], v[156:159], v[216:219], v[114:117]
	v_mfma_f32_16x16x32_bf16 v[102:105], v[148:151], v[224:227], v[102:105]
	v_mfma_f32_16x16x32_bf16 v[98:101], v[156:159], v[224:227], v[98:101]
	v_mfma_f32_16x16x32_bf16 v[86:89], v[148:151], v[232:235], v[86:89]
	v_mfma_f32_16x16x32_bf16 v[82:85], v[156:159], v[232:235], v[82:85]
	s_setprio 0
	s_setprio 1
	v_mfma_f32_16x16x32_bf16 v[110:113], v[178:181], v[194:197], v[110:113]
	v_mfma_f32_16x16x32_bf16 v[106:109], v[186:189], v[194:197], v[106:109]
	v_mfma_f32_16x16x32_bf16 v[94:97], v[178:181], v[212:215], v[94:97]
	v_mfma_f32_16x16x32_bf16 v[90:93], v[186:189], v[212:215], v[90:93]
	v_mfma_f32_16x16x32_bf16 v[78:81], v[178:181], v[220:223], v[78:81]
	v_mfma_f32_16x16x32_bf16 v[74:77], v[186:189], v[220:223], v[74:77]
	v_mfma_f32_16x16x32_bf16 v[70:73], v[178:181], v[228:231], v[70:73]
	v_mfma_f32_16x16x32_bf16 v[66:69], v[186:189], v[228:231], v[66:69]
	s_setprio 0
	s_setprio 1
	v_mfma_f32_16x16x32_bf16 v[110:113], v[182:185], v[208:211], v[110:113]
	v_mfma_f32_16x16x32_bf16 v[106:109], v[190:193], v[208:211], v[106:109]
	v_mfma_f32_16x16x32_bf16 v[94:97], v[182:185], v[216:219], v[94:97]
	v_mfma_f32_16x16x32_bf16 v[90:93], v[190:193], v[216:219], v[90:93]
	v_mfma_f32_16x16x32_bf16 v[78:81], v[182:185], v[224:227], v[78:81]
	v_mfma_f32_16x16x32_bf16 v[74:77], v[190:193], v[224:227], v[74:77]
	v_mfma_f32_16x16x32_bf16 v[70:73], v[182:185], v[232:235], v[70:73]
	v_mfma_f32_16x16x32_bf16 v[66:69], v[190:193], v[232:235], v[66:69]
	s_setprio 0
	s_barrier
	s_add_i32 s44, s44, s25
	s_mov_b32 m0, s44
	ds_read_b128 v[194:197], v143 offset:16384
	ds_read_b128 v[208:211], v143 offset:17408
	ds_read_b128 v[212:215], v143 offset:18432
	ds_read_b128 v[216:219], v143 offset:19456
	ds_read_b128 v[220:223], v143 offset:20480
	ds_read_b128 v[224:227], v143 offset:21504
	ds_read_b128 v[228:231], v143 offset:22528
	ds_read_b128 v[232:235], v143 offset:23552
	global_load_lds_dwordx4 v64, s[18:19]
	s_add_i32 m0, s44, 0x2000
	s_add_u32 s44, s18, 0x200000
	s_addc_u32 s45, s19, 0
	s_add_i32 s46, s46, s25
	global_load_lds_dwordx4 v130, s[18:19]
	s_mov_b32 m0, s46
	s_mov_b64 s[100:101], s[20:21]
	global_load_lds_dwordx4 v64, s[44:45]
	s_add_i32 m0, s46, 0x2000
	s_nop 0
	global_load_lds_dwordx4 v130, s[44:45]
	s_mov_b32 m0, s28
	s_nop 0
	global_load_lds_dwordx4 v134, s[20:21]
	s_mov_b32 m0, s29
	s_nop 0
	global_load_lds_dwordx4 v132, s[20:21]
	s_waitcnt vmcnt(8)
	s_waitcnt lgkmcnt(0)
	s_barrier
	s_setprio 1
	v_mfma_f32_16x16x32_bf16 v[60:63], v[144:147], v[194:197], v[60:63]
	v_mfma_f32_16x16x32_bf16 v[56:59], v[152:155], v[194:197], v[56:59]
	v_mfma_f32_16x16x32_bf16 v[52:55], v[144:147], v[212:215], v[52:55]
	v_mfma_f32_16x16x32_bf16 v[48:51], v[152:155], v[212:215], v[48:51]
	v_mfma_f32_16x16x32_bf16 v[36:39], v[144:147], v[220:223], v[36:39]
	v_mfma_f32_16x16x32_bf16 v[32:35], v[152:155], v[220:223], v[32:35]
	v_mfma_f32_16x16x32_bf16 v[20:23], v[144:147], v[228:231], v[20:23]
	v_mfma_f32_16x16x32_bf16 v[16:19], v[152:155], v[228:231], v[16:19]
	s_setprio 0
	s_setprio 1
	v_mfma_f32_16x16x32_bf16 v[60:63], v[148:151], v[208:211], v[60:63]
	v_mfma_f32_16x16x32_bf16 v[56:59], v[156:159], v[208:211], v[56:59]
	v_mfma_f32_16x16x32_bf16 v[52:55], v[148:151], v[216:219], v[52:55]
	v_mfma_f32_16x16x32_bf16 v[48:51], v[156:159], v[216:219], v[48:51]
	v_mfma_f32_16x16x32_bf16 v[36:39], v[148:151], v[224:227], v[36:39]
	v_mfma_f32_16x16x32_bf16 v[32:35], v[156:159], v[224:227], v[32:35]
	v_mfma_f32_16x16x32_bf16 v[20:23], v[148:151], v[232:235], v[20:23]
	v_mfma_f32_16x16x32_bf16 v[16:19], v[156:159], v[232:235], v[16:19]
	s_setprio 0
	s_setprio 1
	v_mfma_f32_16x16x32_bf16 v[44:47], v[178:181], v[194:197], v[44:47]
	v_mfma_f32_16x16x32_bf16 v[40:43], v[186:189], v[194:197], v[40:43]
	v_mfma_f32_16x16x32_bf16 v[28:31], v[178:181], v[212:215], v[28:31]
	v_mfma_f32_16x16x32_bf16 v[24:27], v[186:189], v[212:215], v[24:27]
	v_mfma_f32_16x16x32_bf16 v[12:15], v[178:181], v[220:223], v[12:15]
	v_mfma_f32_16x16x32_bf16 v[8:11], v[186:189], v[220:223], v[8:11]
	v_mfma_f32_16x16x32_bf16 v[4:7], v[178:181], v[228:231], v[4:7]
	v_mfma_f32_16x16x32_bf16 v[0:3], v[186:189], v[228:231], v[0:3]
	s_setprio 0
	s_setprio 1
	v_mfma_f32_16x16x32_bf16 v[44:47], v[182:185], v[208:211], v[44:47]
	v_mfma_f32_16x16x32_bf16 v[40:43], v[190:193], v[208:211], v[40:43]
	v_mfma_f32_16x16x32_bf16 v[28:31], v[182:185], v[216:219], v[28:31]
	v_mfma_f32_16x16x32_bf16 v[24:27], v[190:193], v[216:219], v[24:27]
	v_mfma_f32_16x16x32_bf16 v[12:15], v[182:185], v[224:227], v[12:15]
	v_mfma_f32_16x16x32_bf16 v[8:11], v[190:193], v[224:227], v[8:11]
	v_mfma_f32_16x16x32_bf16 v[4:7], v[182:185], v[232:235], v[4:7]
	v_mfma_f32_16x16x32_bf16 v[0:3], v[190:193], v[232:235], v[0:3]
	s_setprio 0
	s_barrier
; #define PG8_STAGE(bufoff, gbase, voff) do { _Pragma("unroll") for (int _i = 0; _i < 2; ++_i) \
;         __builtin_amdgcn_global_load_lds((const unsigned*)((const char*)(gbase) + (voff)[_i]), (PG8_LAS unsigned*)(lds + (bufoff) + ldsw + _i * 8192), 16, 0, 0); } while (0)
; #define PG8_LDA(dst, b, h) do { _Pragma("unroll") for (int m = 0; m < 4; ++m) _Pragma("unroll") for (int k = 0; k < 2; ++k) dst[m][k] = *(const PG8_LAS bf16x8*)(lds + PG8_SA(b, h) + aoff + m * 2048 + k * 1024); } while (0)
; #define PG8_LDB(dst, b, h) do { _Pragma("unroll") for (int n = 0; n < 2; ++n) _Pragma("unroll") for (int k = 0; k < 2; ++k) dst[n][k] = *(const PG8_LAS bf16x8*)(lds + PG8_SB(b, h) + boff + n * 2048 + k * 1024); } while (0)
; #define PG8_MMA(ai, bj, At, Bt) do { __builtin_amdgcn_s_setprio(1); _Pragma("unroll") for (int m = 0; m < 4; ++m) _Pragma("unroll") for (int n = 0; n < 2; ++n) _Pragma("unroll") for (int k = 0; k < 2; ++k) \
;         acc[ai][bj][m][n] = __builtin_amdgcn_mfma_f32_16x16x32_bf16(Bt[n][k], At[m][k], acc[ai][bj][m][n], 0, 0, 0); __builtin_amdgcn_s_setprio(0); } while (0)
; #define PG8_WAIT_V(n) asm volatile("s_waitcnt vmcnt(" #n ")" ::: "memory")
; #define PG8_WAIT_L(n) asm volatile("s_waitcnt lgkmcnt(" #n ")" ::: "memory")
; #define PG8_BAR __builtin_amdgcn_s_barrier()
; #define PG8_SCHED __builtin_amdgcn_sched_barrier(0)
; template <class Epi, class Sched, bool ALIGN_EPI = false, bool SP2 = false>
; __device__ __forceinline__ void gemm_phase(PG8_LAS unsigned char* lds, const Gemm g, const Sched& S, const Epi& E, const int wave0) {
;     ...
;         for (int t = 0; t < nt; t += 2) {
;             const bool last = (t == nt - 2);
;             const char* a1 = cA + (size_t)(t + 1) * kstep;
;             const char* a2 = last ? nA : cA + (size_t)(t + 2) * kstep; const char* b2 = last ? nB : cB + (size_t)(t + 2) * kstep;
;     ...
;             PG8_LDB(B0, 1, 0); PG8_LDB(B1, 1, 1); PG8_SCHED; PG8_LDA(At, 1, 0); PG8_STAGE(PG8_SA(0, 1), a2 + hstepA, voffA);
;             PG8_WAIT_V(8); PG8_WAIT_L(0); PG8_BAR; PG8_MMA(0, 0, At, B0); PG8_MMA(0, 1, At, B1); PG8_BAR; PG8_SCHED;
;             PG8_LDA(At, 1, 1); PG8_STAGE(PG8_SB(1, 0), b3, voffB); PG8_STAGE(PG8_SB(1, 1), b3 + hstepB, voffB); PG8_STAGE(PG8_SA(1, 0), a3, voffA);
;             PG8_WAIT_V(8); PG8_WAIT_L(0); PG8_BAR; PG8_MMA(1, 0, At, B0); PG8_MMA(1, 1, At, B1); PG8_BAR; PG8_SCHED;
	s_add_i32 s44, 0, 0x18000
	s_add_i32 s45, 0, 0x1c000
	ds_read_b128 v[144:147], v254
	ds_read_b128 v[148:151], v254 offset:1024
	ds_read_b128 v[152:155], v254 offset:2048
	ds_read_b128 v[156:159], v254 offset:3072
	ds_read_b128 v[178:181], v255
	ds_read_b128 v[182:185], v255 offset:1024
	ds_read_b128 v[186:189], v255 offset:2048
	ds_read_b128 v[190:193], v255 offset:3072
	s_add_u32 s20, s20, 0x200000
	s_addc_u32 s21, s21, 0
	s_mov_b32 m0, s30
	ds_read_b128 v[194:197], v143 offset:32768
	ds_read_b128 v[208:211], v143 offset:33792
	ds_read_b128 v[212:215], v143 offset:34816
	ds_read_b128 v[216:219], v143 offset:35840
	ds_read_b128 v[220:223], v143 offset:36864
	ds_read_b128 v[224:227], v143 offset:37888
	ds_read_b128 v[228:231], v143 offset:38912
	ds_read_b128 v[232:235], v143 offset:39936
	global_load_lds_dwordx4 v134, s[20:21]
	s_mov_b32 m0, s31
	s_nop 0
	global_load_lds_dwordx4 v132, s[20:21]
	s_waitcnt vmcnt(8)
	s_waitcnt lgkmcnt(0)
	s_barrier
	s_setprio 1
	v_mfma_f32_16x16x32_bf16 v[126:129], v[144:147], v[194:197], v[126:129]
	v_mfma_f32_16x16x32_bf16 v[122:125], v[152:155], v[194:197], v[122:125]
	v_mfma_f32_16x16x32_bf16 v[118:121], v[144:147], v[212:215], v[118:121]
	v_mfma_f32_16x16x32_bf16 v[114:117], v[152:155], v[212:215], v[114:117]
	v_mfma_f32_16x16x32_bf16 v[102:105], v[144:147], v[220:223], v[102:105]
	v_mfma_f32_16x16x32_bf16 v[98:101], v[152:155], v[220:223], v[98:101]
	v_mfma_f32_16x16x32_bf16 v[86:89], v[144:147], v[228:231], v[86:89]
	v_mfma_f32_16x16x32_bf16 v[82:85], v[152:155], v[228:231], v[82:85]
	s_setprio 0
	s_setprio 1
	v_mfma_f32_16x16x32_bf16 v[126:129], v[148:151], v[208:211], v[126:129]
	v_mfma_f32_16x16x32_bf16 v[122:125], v[156:159], v[208:211], v[122:125]
	v_mfma_f32_16x16x32_bf16 v[118:121], v[148:151], v[216:219], v[118:121]
	v_mfma_f32_16x16x32_bf16 v[114:117], v[156:159], v[216:219], v[114:117]
	v_mfma_f32_16x16x32_bf16 v[102:105], v[148:151], v[224:227], v[102:105]
	v_mfma_f32_16x16x32_bf16 v[98:101], v[156:159], v[224:227], v[98:101]
	v_mfma_f32_16x16x32_bf16 v[86:89], v[148:151], v[232:235], v[86:89]
	v_mfma_f32_16x16x32_bf16 v[82:85], v[156:159], v[232:235], v[82:85]
	s_setprio 0
	s_setprio 1
	v_mfma_f32_16x16x32_bf16 v[110:113], v[178:181], v[194:197], v[110:113]
	v_mfma_f32_16x16x32_bf16 v[106:109], v[186:189], v[194:197], v[106:109]
	v_mfma_f32_16x16x32_bf16 v[94:97], v[178:181], v[212:215], v[94:97]
	v_mfma_f32_16x16x32_bf16 v[90:93], v[186:189], v[212:215], v[90:93]
	v_mfma_f32_16x16x32_bf16 v[78:81], v[178:181], v[220:223], v[78:81]
	v_mfma_f32_16x16x32_bf16 v[74:77], v[186:189], v[220:223], v[74:77]
	v_mfma_f32_16x16x32_bf16 v[70:73], v[178:181], v[228:231], v[70:73]
	v_mfma_f32_16x16x32_bf16 v[66:69], v[186:189], v[228:231], v[66:69]
	s_setprio 0
	s_setprio 1
	v_mfma_f32_16x16x32_bf16 v[110:113], v[182:185], v[208:211], v[110:113]
	v_mfma_f32_16x16x32_bf16 v[106:109], v[190:193], v[208:211], v[106:109]
	v_mfma_f32_16x16x32_bf16 v[94:97], v[182:185], v[216:219], v[94:97]
	v_mfma_f32_16x16x32_bf16 v[90:93], v[190:193], v[216:219], v[90:93]
	v_mfma_f32_16x16x32_bf16 v[78:81], v[182:185], v[224:227], v[78:81]
	v_mfma_f32_16x16x32_bf16 v[74:77], v[190:193], v[224:227], v[74:77]
	v_mfma_f32_16x16x32_bf16 v[70:73], v[182:185], v[232:235], v[70:73]
	v_mfma_f32_16x16x32_bf16 v[66:69], v[190:193], v[232:235], v[66:69]
	s_setprio 0
	s_barrier
	s_add_i32 s20, s44, s25
	s_add_u32 s48, s18, 0x80
	s_addc_u32 s49, s19, 0
	s_mov_b32 m0, s20
	ds_read_b128 v[194:197], v143 offset:49152
	ds_read_b128 v[208:211], v143 offset:50176
	ds_read_b128 v[212:215], v143 offset:51200
	ds_read_b128 v[216:219], v143 offset:52224
	ds_read_b128 v[220:223], v143 offset:53248
	ds_read_b128 v[224:227], v143 offset:54272
	ds_read_b128 v[228:231], v143 offset:55296
	ds_read_b128 v[232:235], v143 offset:56320
	global_load_lds_dwordx4 v64, s[48:49]
	s_add_i32 m0, s20, 0x2000
	s_add_u32 s18, s18, 0x200080
	s_addc_u32 s19, s19, 0
	s_add_i32 s20, s45, s25
	global_load_lds_dwordx4 v130, s[48:49]
	s_mov_b32 m0, s20
	s_nop 0
	global_load_lds_dwordx4 v64, s[18:19]
	s_add_i32 m0, s20, 0x2000
	s_nop 0
	global_load_lds_dwordx4 v130, s[18:19]
	s_add_u32 s100, s100, 0x80
	s_addc_u32 s101, s101, 0
	s_mov_b32 m0, s33
	s_nop 0
	global_load_lds_dwordx4 v134, s[100:101]
	s_mov_b32 m0, s34
	s_nop 0
	global_load_lds_dwordx4 v132, s[100:101]
	s_waitcnt vmcnt(8)
	s_waitcnt lgkmcnt(0)
	s_barrier
	s_setprio 1
	v_mfma_f32_16x16x32_bf16 v[60:63], v[144:147], v[194:197], v[60:63]
	v_mfma_f32_16x16x32_bf16 v[56:59], v[152:155], v[194:197], v[56:59]
	v_mfma_f32_16x16x32_bf16 v[52:55], v[144:147], v[212:215], v[52:55]
	v_mfma_f32_16x16x32_bf16 v[48:51], v[152:155], v[212:215], v[48:51]
	v_mfma_f32_16x16x32_bf16 v[36:39], v[144:147], v[220:223], v[36:39]
	v_mfma_f32_16x16x32_bf16 v[32:35], v[152:155], v[220:223], v[32:35]
	v_mfma_f32_16x16x32_bf16 v[20:23], v[144:147], v[228:231], v[20:23]
	v_mfma_f32_16x16x32_bf16 v[16:19], v[152:155], v[228:231], v[16:19]
	s_setprio 0
	s_setprio 1
	v_mfma_f32_16x16x32_bf16 v[60:63], v[148:151], v[208:211], v[60:63]
	v_mfma_f32_16x16x32_bf16 v[56:59], v[156:159], v[208:211], v[56:59]
	v_mfma_f32_16x16x32_bf16 v[52:55], v[148:151], v[216:219], v[52:55]
	v_mfma_f32_16x16x32_bf16 v[48:51], v[156:159], v[216:219], v[48:51]
	v_mfma_f32_16x16x32_bf16 v[36:39], v[148:151], v[224:227], v[36:39]
	v_mfma_f32_16x16x32_bf16 v[32:35], v[156:159], v[224:227], v[32:35]
	v_mfma_f32_16x16x32_bf16 v[20:23], v[148:151], v[232:235], v[20:23]
	v_mfma_f32_16x16x32_bf16 v[16:19], v[156:159], v[232:235], v[16:19]
	s_setprio 0
	s_setprio 1
	v_mfma_f32_16x16x32_bf16 v[44:47], v[178:181], v[194:197], v[44:47]
	v_mfma_f32_16x16x32_bf16 v[40:43], v[186:189], v[194:197], v[40:43]
	v_mfma_f32_16x16x32_bf16 v[28:31], v[178:181], v[212:215], v[28:31]
	v_mfma_f32_16x16x32_bf16 v[24:27], v[186:189], v[212:215], v[24:27]
	v_mfma_f32_16x16x32_bf16 v[12:15], v[178:181], v[220:223], v[12:15]
	v_mfma_f32_16x16x32_bf16 v[8:11], v[186:189], v[220:223], v[8:11]
	v_mfma_f32_16x16x32_bf16 v[4:7], v[178:181], v[228:231], v[4:7]
	v_mfma_f32_16x16x32_bf16 v[0:3], v[186:189], v[228:231], v[0:3]
	s_setprio 0
	s_setprio 1
	v_mfma_f32_16x16x32_bf16 v[44:47], v[182:185], v[208:211], v[44:47]
	v_mfma_f32_16x16x32_bf16 v[40:43], v[190:193], v[208:211], v[40:43]
	v_mfma_f32_16x16x32_bf16 v[28:31], v[182:185], v[216:219], v[28:31]
	v_mfma_f32_16x16x32_bf16 v[24:27], v[190:193], v[216:219], v[24:27]
	v_mfma_f32_16x16x32_bf16 v[12:15], v[182:185], v[224:227], v[12:15]
	v_mfma_f32_16x16x32_bf16 v[8:11], v[190:193], v[224:227], v[8:11]
	v_mfma_f32_16x16x32_bf16 v[4:7], v[182:185], v[232:235], v[4:7]
	v_mfma_f32_16x16x32_bf16 v[0:3], v[190:193], v[232:235], v[0:3]
	s_setprio 0
	s_barrier
	s_add_i32 s43, s43, 2
	s_add_u32 s16, s16, 0x100
	s_addc_u32 s17, s17, 0
	s_add_u32 s39, s39, 0x100
	s_addc_u32 s42, s42, 0
	s_cmp_gt_u32 s43, 13
	s_cbranch_scc0 .LBB0_1702
	s_mov_b64 s[48:49], 0x80
	s_and_b64 vcc, exec, s[6:7]
	s_cbranch_vccz .LBB0_1705
	s_barrier
